# GEMM K-loops: dropped the redundant s_waitcnt lgkmcnt(0) that follows each segment-opening barrier (the same wait already precedes the barrier)
# baseline (speedup 1.0000x reference)
; #define PG8_STAGE(bufoff, gbase, voff) do { _Pragma("unroll") for (int _i = 0; _i < 2; ++_i) \
;         __builtin_amdgcn_global_load_lds((const unsigned*)((const char*)(gbase) + (voff)[_i]), (PG8_LAS unsigned*)(lds + (bufoff) + ldsw + _i * 8192), 16, 0, 0); } while (0)
; #define PG8_LDA(dst, b, h) do { _Pragma("unroll") for (int m = 0; m < 4; ++m) _Pragma("unroll") for (int k = 0; k < 2; ++k) dst[m][k] = *(const PG8_LAS bf16x8*)(lds + PG8_SA(b, h) + aoff + m * 2048 + k * 1024); } while (0)
; #define PG8_LDB(dst, b, h) do { _Pragma("unroll") for (int n = 0; n < 2; ++n) _Pragma("unroll") for (int k = 0; k < 2; ++k) dst[n][k] = *(const PG8_LAS bf16x8*)(lds + PG8_SB(b, h) + boff + n * 2048 + k * 1024); } while (0)
; #define PG8_MMA(ai, bj, At, Bt) do { __builtin_amdgcn_s_setprio(1); _Pragma("unroll") for (int m = 0; m < 4; ++m) _Pragma("unroll") for (int n = 0; n < 2; ++n) _Pragma("unroll") for (int k = 0; k < 2; ++k) \
;         acc[ai][bj][m][n] = __builtin_amdgcn_mfma_f32_16x16x32_bf16(Bt[n][k], At[m][k], acc[ai][bj][m][n], 0, 0, 0); __builtin_amdgcn_s_setprio(0); } while (0)
; #define PG8_WAIT_V(n) asm volatile("s_waitcnt vmcnt(" #n ")" ::: "memory")
; #define PG8_WAIT_L(n) asm volatile("s_waitcnt lgkmcnt(" #n ")" ::: "memory")
; template <class Epi, class Sched, bool ALIGN_EPI = false, bool SP2 = false>
; __device__ __forceinline__ void gemm_phase(PG8_LAS unsigned char* lds, const Gemm g, const Sched& S, const Epi& E) {
;     ...
;             const bool last = (t == nt - 2);
;             const char* a1 = cA + (size_t)(t + 1) * kstep;
;             const char* a2 = last ? nA : cA + (size_t)(t + 2) * kstep; const char* b2 = last ? nB : cB + (size_t)(t + 2) * kstep;
;             const char* a3 = a2 + kstep; const char* b3 = b2 + kstep;
;             if (last && has_next) S.a_ready(nxt);
;             if constexpr (SP2) {
;             PG8_LDB(B0, 0, 0); PG8_LDB(B1, 0, 1); PG8_SCHED; PG8_LDA(At, 0, 0); PG8_STAGE(PG8_SA(1, 1), a1 + hstepA, voffA);
;             PG8_WAIT_V(8); PG8_WAIT_L(0); PG8_BAR; PG8_MMA(0, 0, At, B0); PG8_MMA(0, 1, At, B1); PG8_BAR; PG8_SCHED;
;             PG8_LDA(At, 0, 1); PG8_STAGE(PG8_SB(0, 0), b2, voffB); PG8_STAGE(PG8_SB(0, 1), b2 + hstepB, voffB); PG8_STAGE(PG8_SA(0, 0), a2, voffA);
;             PG8_WAIT_V(8); PG8_WAIT_L(0); PG8_BAR; PG8_MMA(1, 0, At, B0); PG8_MMA(1, 1, At, B1); PG8_BAR; PG8_SCHED;
.LBB0_454:
	s_add_u32 s0, s40, 0xfffc0080
	s_addc_u32 s1, s41, -1
	s_add_i32 s16, 0, 0x10000
	s_cmp_eq_u32 s13, 12
	s_cselect_b32 s1, s2, s1
	s_cselect_b32 s0, s3, s0
	s_cselect_b32 s49, s8, s12
	s_cselect_b32 s48, s9, s10
	s_add_i32 s18, 0, 0x14000
	v_add_u32_e32 v152, s16, v158
	v_add_u32_e32 v156, s18, v158
	ds_read_b128 v[140:143], v152
	ds_read_b128 v[144:147], v152 offset:1024
	ds_read_b128 v[148:151], v152 offset:2048
	ds_read_b128 v[152:155], v152 offset:3072
	ds_read_b128 v[160:163], v156
	ds_read_b128 v[186:189], v156 offset:1024
	ds_read_b128 v[190:193], v156 offset:2048
	ds_read_b128 v[194:197], v156 offset:3072
	v_lshl_add_u64 v[156:157], s[40:41], 0, v[138:139]
	s_add_i32 m0, s59, 0xc000
	ds_read_b128 v[198:201], v159
	ds_read_b128 v[202:205], v159 offset:1024
	ds_read_b128 v[214:217], v159 offset:2048
	ds_read_b128 v[218:221], v159 offset:3072
	ds_read_b128 v[222:225], v159 offset:4096
	ds_read_b128 v[226:229], v159 offset:5120
	ds_read_b128 v[230:233], v159 offset:6144
	ds_read_b128 v[234:237], v159 offset:7168
	global_load_lds_dwordx4 v[156:157], off
	v_lshl_add_u64 v[156:157], s[40:41], 0, v[136:137]
	s_add_i32 m0, s59, 0xe000
	s_nop 0
	global_load_lds_dwordx4 v[156:157], off
	s_waitcnt vmcnt(8)
	s_waitcnt lgkmcnt(0)
	s_barrier
	s_setprio 1
	v_mfma_f32_16x16x32_bf16 v[116:119], v[140:143], v[198:201], v[116:119]
	v_mfma_f32_16x16x32_bf16 v[112:115], v[148:151], v[198:201], v[112:115]
	v_mfma_f32_16x16x32_bf16 v[100:103], v[140:143], v[214:217], v[100:103]
	v_mfma_f32_16x16x32_bf16 v[96:99], v[148:151], v[214:217], v[96:99]
	v_mfma_f32_16x16x32_bf16 v[84:87], v[140:143], v[222:225], v[84:87]
	v_mfma_f32_16x16x32_bf16 v[80:83], v[148:151], v[222:225], v[80:83]
	v_mfma_f32_16x16x32_bf16 v[68:71], v[140:143], v[230:233], v[68:71]
	v_mfma_f32_16x16x32_bf16 v[64:67], v[148:151], v[230:233], v[64:67]
	v_mfma_f32_16x16x32_bf16 v[116:119], v[144:147], v[202:205], v[116:119]
	v_mfma_f32_16x16x32_bf16 v[112:115], v[152:155], v[202:205], v[112:115]
	v_mfma_f32_16x16x32_bf16 v[100:103], v[144:147], v[218:221], v[100:103]
	v_mfma_f32_16x16x32_bf16 v[96:99], v[152:155], v[218:221], v[96:99]
	v_mfma_f32_16x16x32_bf16 v[84:87], v[144:147], v[226:229], v[84:87]
	v_mfma_f32_16x16x32_bf16 v[80:83], v[152:155], v[226:229], v[80:83]
	v_mfma_f32_16x16x32_bf16 v[68:71], v[144:147], v[234:237], v[68:71]
	v_mfma_f32_16x16x32_bf16 v[64:67], v[152:155], v[234:237], v[64:67]
	v_mfma_f32_16x16x32_bf16 v[124:127], v[160:163], v[198:201], v[124:127]
	v_mfma_f32_16x16x32_bf16 v[120:123], v[190:193], v[198:201], v[120:123]
	v_mfma_f32_16x16x32_bf16 v[108:111], v[160:163], v[214:217], v[108:111]
	v_mfma_f32_16x16x32_bf16 v[104:107], v[190:193], v[214:217], v[104:107]
	v_mfma_f32_16x16x32_bf16 v[92:95], v[160:163], v[222:225], v[92:95]
	v_mfma_f32_16x16x32_bf16 v[88:91], v[190:193], v[222:225], v[88:91]
	v_mfma_f32_16x16x32_bf16 v[76:79], v[160:163], v[230:233], v[76:79]
	v_mfma_f32_16x16x32_bf16 v[72:75], v[190:193], v[230:233], v[72:75]
	v_mfma_f32_16x16x32_bf16 v[124:127], v[186:189], v[202:205], v[124:127]
	v_mfma_f32_16x16x32_bf16 v[120:123], v[194:197], v[202:205], v[120:123]
	v_mfma_f32_16x16x32_bf16 v[108:111], v[186:189], v[218:221], v[108:111]
	v_mfma_f32_16x16x32_bf16 v[104:107], v[194:197], v[218:221], v[104:107]
	v_mfma_f32_16x16x32_bf16 v[92:95], v[186:189], v[226:229], v[92:95]
	v_mfma_f32_16x16x32_bf16 v[88:91], v[194:197], v[226:229], v[88:91]
	v_mfma_f32_16x16x32_bf16 v[76:79], v[186:189], v[234:237], v[76:79]
	v_mfma_f32_16x16x32_bf16 v[72:75], v[194:197], v[234:237], v[72:75]
	s_setprio 0
	s_barrier
	s_add_i32 s16, s16, s58
	v_lshl_add_u64 v[156:157], s[48:49], 0, v[130:131]
	s_mov_b32 m0, s16
	ds_read_b128 v[198:201], v159 offset:16384
	ds_read_b128 v[202:205], v159 offset:17408
	ds_read_b128 v[214:217], v159 offset:18432
	ds_read_b128 v[218:221], v159 offset:19456
	ds_read_b128 v[222:225], v159 offset:20480
	ds_read_b128 v[226:229], v159 offset:21504
	ds_read_b128 v[230:233], v159 offset:22528
	ds_read_b128 v[234:237], v159 offset:23552
	global_load_lds_dwordx4 v[156:157], off
	s_add_i32 m0, s16, 0x2000
	s_add_u32 s16, s48, 0x40000
	v_lshl_add_u64 v[166:167], s[48:49], 0, v[134:135]
	s_addc_u32 s17, s49, 0
	s_add_i32 s18, s18, s58
	global_load_lds_dwordx4 v[166:167], off
	v_lshl_add_u64 v[168:169], s[16:17], 0, v[130:131]
	s_mov_b32 m0, s18
	v_lshl_add_u64 v[238:239], s[0:1], 0, v[132:133]
	global_load_lds_dwordx4 v[168:169], off
	v_lshl_add_u64 v[168:169], s[16:17], 0, v[134:135]
	s_add_i32 m0, s18, 0x2000
	s_nop 0
	global_load_lds_dwordx4 v[168:169], off
	v_lshl_add_u64 v[168:169], s[0:1], 0, v[128:129]
	s_mov_b32 m0, s59
	s_nop 0
	global_load_lds_dwordx4 v[168:169], off
	s_mov_b32 m0, s60
	s_nop 0
	global_load_lds_dwordx4 v[238:239], off
	s_waitcnt vmcnt(8)
	s_waitcnt lgkmcnt(0)
	s_barrier
; #define PG8_STAGE(bufoff, gbase, voff) do { _Pragma("unroll") for (int _i = 0; _i < 2; ++_i) \
;         __builtin_amdgcn_global_load_lds((const unsigned*)((const char*)(gbase) + (voff)[_i]), (PG8_LAS unsigned*)(lds + (bufoff) + ldsw + _i * 8192), 16, 0, 0); } while (0)
; #define PG8_LDA(dst, b, h) do { _Pragma("unroll") for (int m = 0; m < 4; ++m) _Pragma("unroll") for (int k = 0; k < 2; ++k) dst[m][k] = *(const PG8_LAS bf16x8*)(lds + PG8_SA(b, h) + aoff + m * 2048 + k * 1024); } while (0)
; #define PG8_LDB(dst, b, h) do { _Pragma("unroll") for (int n = 0; n < 2; ++n) _Pragma("unroll") for (int k = 0; k < 2; ++k) dst[n][k] = *(const PG8_LAS bf16x8*)(lds + PG8_SB(b, h) + boff + n * 2048 + k * 1024); } while (0)
; #define PG8_MMA(ai, bj, At, Bt) do { __builtin_amdgcn_s_setprio(1); _Pragma("unroll") for (int m = 0; m < 4; ++m) _Pragma("unroll") for (int n = 0; n < 2; ++n) _Pragma("unroll") for (int k = 0; k < 2; ++k) \
;         acc[ai][bj][m][n] = __builtin_amdgcn_mfma_f32_16x16x32_bf16(Bt[n][k], At[m][k], acc[ai][bj][m][n], 0, 0, 0); __builtin_amdgcn_s_setprio(0); } while (0)
; #define PG8_WAIT_V(n) asm volatile("s_waitcnt vmcnt(" #n ")" ::: "memory")
; #define PG8_WAIT_L(n) asm volatile("s_waitcnt lgkmcnt(" #n ")" ::: "memory")
; #define PG8_BAR __builtin_amdgcn_s_barrier()
; #define PG8_SCHED __builtin_amdgcn_sched_barrier(0)
; template <class Epi, class Sched, bool ALIGN_EPI = false, bool SP2 = false>
; __device__ __forceinline__ void gemm_phase(PG8_LAS unsigned char* lds, const Gemm g, const Sched& S, const Epi& E) {
;     ...
;             PG8_WAIT_V(8); PG8_WAIT_L(0); PG8_BAR; PG8_MMA(1, 0, At, B0); PG8_MMA(1, 1, At, B1); PG8_BAR; PG8_SCHED;
;             PG8_LDB(B0, 1, 0); PG8_LDB(B1, 1, 1); PG8_SCHED; PG8_LDA(At, 1, 0); PG8_STAGE(PG8_SA(0, 1), a2 + hstepA, voffA);
;             PG8_WAIT_V(8); PG8_WAIT_L(0); PG8_BAR; PG8_MMA(0, 0, At, B0); PG8_MMA(0, 1, At, B1); PG8_BAR; PG8_SCHED;
	s_setprio 1
	v_mfma_f32_16x16x32_bf16 v[52:55], v[140:143], v[198:201], v[52:55]
	v_mfma_f32_16x16x32_bf16 v[48:51], v[148:151], v[198:201], v[48:51]
	v_mfma_f32_16x16x32_bf16 v[36:39], v[140:143], v[214:217], v[36:39]
	v_mfma_f32_16x16x32_bf16 v[32:35], v[148:151], v[214:217], v[32:35]
	v_mfma_f32_16x16x32_bf16 v[20:23], v[140:143], v[222:225], v[20:23]
	v_mfma_f32_16x16x32_bf16 v[16:19], v[148:151], v[222:225], v[16:19]
	v_mfma_f32_16x16x32_bf16 v[4:7], v[140:143], v[230:233], v[4:7]
	v_mfma_f32_16x16x32_bf16 v[0:3], v[148:151], v[230:233], v[0:3]
	v_mfma_f32_16x16x32_bf16 v[52:55], v[144:147], v[202:205], v[52:55]
	v_mfma_f32_16x16x32_bf16 v[48:51], v[152:155], v[202:205], v[48:51]
	v_mfma_f32_16x16x32_bf16 v[36:39], v[144:147], v[218:221], v[36:39]
	v_mfma_f32_16x16x32_bf16 v[32:35], v[152:155], v[218:221], v[32:35]
	v_mfma_f32_16x16x32_bf16 v[20:23], v[144:147], v[226:229], v[20:23]
	v_mfma_f32_16x16x32_bf16 v[16:19], v[152:155], v[226:229], v[16:19]
	v_mfma_f32_16x16x32_bf16 v[4:7], v[144:147], v[234:237], v[4:7]
	v_mfma_f32_16x16x32_bf16 v[0:3], v[152:155], v[234:237], v[0:3]
	v_mfma_f32_16x16x32_bf16 v[60:63], v[160:163], v[198:201], v[60:63]
	v_mfma_f32_16x16x32_bf16 v[56:59], v[190:193], v[198:201], v[56:59]
	v_mfma_f32_16x16x32_bf16 v[44:47], v[160:163], v[214:217], v[44:47]
	v_mfma_f32_16x16x32_bf16 v[40:43], v[190:193], v[214:217], v[40:43]
	v_mfma_f32_16x16x32_bf16 v[28:31], v[160:163], v[222:225], v[28:31]
	v_mfma_f32_16x16x32_bf16 v[24:27], v[190:193], v[222:225], v[24:27]
	v_mfma_f32_16x16x32_bf16 v[12:15], v[160:163], v[230:233], v[12:15]
	v_mfma_f32_16x16x32_bf16 v[8:11], v[190:193], v[230:233], v[8:11]
	v_mfma_f32_16x16x32_bf16 v[60:63], v[186:189], v[202:205], v[60:63]
	v_mfma_f32_16x16x32_bf16 v[56:59], v[194:197], v[202:205], v[56:59]
	v_mfma_f32_16x16x32_bf16 v[44:47], v[186:189], v[218:221], v[44:47]
	v_mfma_f32_16x16x32_bf16 v[40:43], v[194:197], v[218:221], v[40:43]
	v_mfma_f32_16x16x32_bf16 v[28:31], v[186:189], v[226:229], v[28:31]
	v_mfma_f32_16x16x32_bf16 v[24:27], v[194:197], v[226:229], v[24:27]
	v_mfma_f32_16x16x32_bf16 v[12:15], v[186:189], v[234:237], v[12:15]
	v_mfma_f32_16x16x32_bf16 v[8:11], v[194:197], v[234:237], v[8:11]
	s_setprio 0
	s_barrier
	s_add_i32 s16, 0, 0x18000
	s_add_i32 s17, 0, 0x1c000
	v_add_u32_e32 v152, s16, v158
	v_add_u32_e32 v164, s17, v158
	ds_read_b128 v[140:143], v152
	ds_read_b128 v[144:147], v152 offset:1024
	ds_read_b128 v[148:151], v152 offset:2048
	ds_read_b128 v[152:155], v152 offset:3072
	ds_read_b128 v[160:163], v164
	ds_read_b128 v[186:189], v164 offset:1024
	ds_read_b128 v[190:193], v164 offset:2048
	ds_read_b128 v[194:197], v164 offset:3072
	s_add_u32 s0, s0, 0x40000
	s_addc_u32 s1, s1, 0
	s_mov_b32 m0, s61
	v_lshl_add_u64 v[240:241], s[0:1], 0, v[128:129]
	ds_read_b128 v[198:201], v159 offset:32768
	ds_read_b128 v[202:205], v159 offset:33792
	ds_read_b128 v[214:217], v159 offset:34816
	ds_read_b128 v[218:221], v159 offset:35840
	ds_read_b128 v[222:225], v159 offset:36864
	ds_read_b128 v[226:229], v159 offset:37888
	ds_read_b128 v[230:233], v159 offset:38912
	ds_read_b128 v[234:237], v159 offset:39936
	global_load_lds_dwordx4 v[240:241], off
	v_lshl_add_u64 v[240:241], s[0:1], 0, v[132:133]
	s_mov_b32 m0, s62
	s_nop 0
	global_load_lds_dwordx4 v[240:241], off
	s_waitcnt vmcnt(8)
	s_waitcnt lgkmcnt(0)
	s_barrier
	s_setprio 1
	v_mfma_f32_16x16x32_bf16 v[116:119], v[140:143], v[198:201], v[116:119]
	v_mfma_f32_16x16x32_bf16 v[112:115], v[148:151], v[198:201], v[112:115]
	v_mfma_f32_16x16x32_bf16 v[100:103], v[140:143], v[214:217], v[100:103]
	v_mfma_f32_16x16x32_bf16 v[96:99], v[148:151], v[214:217], v[96:99]
	v_mfma_f32_16x16x32_bf16 v[84:87], v[140:143], v[222:225], v[84:87]
	v_mfma_f32_16x16x32_bf16 v[80:83], v[148:151], v[222:225], v[80:83]
	v_mfma_f32_16x16x32_bf16 v[68:71], v[140:143], v[230:233], v[68:71]
	v_mfma_f32_16x16x32_bf16 v[64:67], v[148:151], v[230:233], v[64:67]
	v_mfma_f32_16x16x32_bf16 v[116:119], v[144:147], v[202:205], v[116:119]
	v_mfma_f32_16x16x32_bf16 v[112:115], v[152:155], v[202:205], v[112:115]
	v_mfma_f32_16x16x32_bf16 v[100:103], v[144:147], v[218:221], v[100:103]
	v_mfma_f32_16x16x32_bf16 v[96:99], v[152:155], v[218:221], v[96:99]
	v_mfma_f32_16x16x32_bf16 v[84:87], v[144:147], v[226:229], v[84:87]
	v_mfma_f32_16x16x32_bf16 v[80:83], v[152:155], v[226:229], v[80:83]
	v_mfma_f32_16x16x32_bf16 v[68:71], v[144:147], v[234:237], v[68:71]
	v_mfma_f32_16x16x32_bf16 v[64:67], v[152:155], v[234:237], v[64:67]
	v_mfma_f32_16x16x32_bf16 v[124:127], v[160:163], v[198:201], v[124:127]
	v_mfma_f32_16x16x32_bf16 v[120:123], v[190:193], v[198:201], v[120:123]
	v_mfma_f32_16x16x32_bf16 v[108:111], v[160:163], v[214:217], v[108:111]
	v_mfma_f32_16x16x32_bf16 v[104:107], v[190:193], v[214:217], v[104:107]
	v_mfma_f32_16x16x32_bf16 v[92:95], v[160:163], v[222:225], v[92:95]
	v_mfma_f32_16x16x32_bf16 v[88:91], v[190:193], v[222:225], v[88:91]
	v_mfma_f32_16x16x32_bf16 v[76:79], v[160:163], v[230:233], v[76:79]
	v_mfma_f32_16x16x32_bf16 v[72:75], v[190:193], v[230:233], v[72:75]
	v_mfma_f32_16x16x32_bf16 v[124:127], v[186:189], v[202:205], v[124:127]
	v_mfma_f32_16x16x32_bf16 v[120:123], v[194:197], v[202:205], v[120:123]
	v_mfma_f32_16x16x32_bf16 v[108:111], v[186:189], v[218:221], v[108:111]
	v_mfma_f32_16x16x32_bf16 v[104:107], v[194:197], v[218:221], v[104:107]
	v_mfma_f32_16x16x32_bf16 v[92:95], v[186:189], v[226:229], v[92:95]
	v_mfma_f32_16x16x32_bf16 v[88:91], v[194:197], v[226:229], v[88:91]
	v_mfma_f32_16x16x32_bf16 v[76:79], v[186:189], v[234:237], v[76:79]
	v_mfma_f32_16x16x32_bf16 v[72:75], v[194:197], v[234:237], v[72:75]
	s_setprio 0
	s_barrier
; #define PG8_STAGE(bufoff, gbase, voff) do { _Pragma("unroll") for (int _i = 0; _i < 2; ++_i) \
;         __builtin_amdgcn_global_load_lds((const unsigned*)((const char*)(gbase) + (voff)[_i]), (PG8_LAS unsigned*)(lds + (bufoff) + ldsw + _i * 8192), 16, 0, 0); } while (0)
; #define PG8_LDA(dst, b, h) do { _Pragma("unroll") for (int m = 0; m < 4; ++m) _Pragma("unroll") for (int k = 0; k < 2; ++k) dst[m][k] = *(const PG8_LAS bf16x8*)(lds + PG8_SA(b, h) + aoff + m * 2048 + k * 1024); } while (0)
; #define PG8_WAIT_V(n) asm volatile("s_waitcnt vmcnt(" #n ")" ::: "memory")
; template <class Epi, class Sched, bool ALIGN_EPI = false, bool SP2 = false>
; __device__ __forceinline__ void gemm_phase(PG8_LAS unsigned char* lds, const Gemm g, const Sched& S, const Epi& E) {
;     ...
;             PG8_LDA(At, 1, 1); PG8_STAGE(PG8_SB(1, 0), b3, voffB); PG8_STAGE(PG8_SB(1, 1), b3 + hstepB, voffB); PG8_STAGE(PG8_SA(1, 0), a3, voffA);
;             PG8_WAIT_V(8); PG8_WAIT_L(0); PG8_BAR; PG8_MMA(1, 0, At, B0); PG8_MMA(1, 1, At, B1); PG8_BAR; PG8_SCHED;
;             } else {
;             PG8_LDB(B0, 0, 0); PG8_SCHED; PG8_LDA(At, 0, 0); PG8_STAGE(PG8_SA(1, 1), a1 + hstepA, voffA);
;             PG8_WAIT_L(8); PG8_BAR; PG8_WAIT_L(0); PG8_MMA(0, 0, At, B0); PG8_BAR; PG8_SCHED;
;             PG8_LDB(B1, 0, 1); PG8_STAGE(PG8_SB(0, 0), b2, voffB);
;             PG8_BAR; PG8_WAIT_L(0); PG8_MMA(0, 1, At, B1); PG8_BAR;
;             PG8_LDA(At, 0, 1); PG8_STAGE(PG8_SA(0, 0), a2, voffA);
;             PG8_BAR; PG8_WAIT_L(0); PG8_MMA(1, 0, At, B0); PG8_BAR; PG8_SCHED;
;             PG8_STAGE(PG8_SB(0, 1), b2 + hstepB, voffB);
;             PG8_WAIT_V(6); PG8_BAR; PG8_MMA(1, 1, At, B1); PG8_BAR;
;             PG8_LDB(B0, 1, 0); PG8_SCHED; PG8_LDA(At, 1, 0); PG8_STAGE(PG8_SA(0, 1), a2 + hstepA, voffA);
;             PG8_WAIT_L(8); PG8_BAR; PG8_WAIT_L(0); PG8_MMA(0, 0, At, B0); PG8_BAR; PG8_SCHED;
;             PG8_LDB(B1, 1, 1); PG8_STAGE(PG8_SB(1, 0), b3, voffB);
;             PG8_BAR; PG8_WAIT_L(0); PG8_MMA(0, 1, At, B1); PG8_BAR;
;             PG8_LDA(At, 1, 1); PG8_STAGE(PG8_SA(1, 0), a3, voffA);
;             PG8_BAR; PG8_WAIT_L(0); PG8_MMA(1, 0, At, B0); PG8_BAR; PG8_SCHED;
;             PG8_STAGE(PG8_SB(1, 1), b3 + hstepB, voffB);
;             PG8_WAIT_V(6); PG8_BAR; PG8_MMA(1, 1, At, B1); PG8_BAR;
;             }
;         }
;         if constexpr (ALIGN_EPI) { if (wr == 0) PG8_BAR; }
	s_add_i32 s0, s16, s58
	v_lshl_add_u64 v[156:157], v[156:157], 0, s[14:15]
	s_mov_b32 m0, s0
	ds_read_b128 v[198:201], v159 offset:49152
	ds_read_b128 v[202:205], v159 offset:50176
	ds_read_b128 v[214:217], v159 offset:51200
	ds_read_b128 v[218:221], v159 offset:52224
	ds_read_b128 v[222:225], v159 offset:53248
	ds_read_b128 v[226:229], v159 offset:54272
	ds_read_b128 v[230:233], v159 offset:55296
	ds_read_b128 v[234:237], v159 offset:56320
	global_load_lds_dwordx4 v[156:157], off
	s_add_i32 m0, s0, 0x2000
	s_add_u32 s0, s48, 0x40080
	v_lshl_add_u64 v[156:157], v[166:167], 0, s[14:15]
	s_addc_u32 s1, s49, 0
	s_add_i32 s16, s17, s58
	global_load_lds_dwordx4 v[156:157], off
	v_lshl_add_u64 v[156:157], s[0:1], 0, v[130:131]
	s_mov_b32 m0, s16
	s_nop 0
	global_load_lds_dwordx4 v[156:157], off
	v_lshl_add_u64 v[156:157], s[0:1], 0, v[134:135]
	s_add_i32 m0, s16, 0x2000
	s_nop 0
	global_load_lds_dwordx4 v[156:157], off
	v_lshl_add_u64 v[156:157], v[168:169], 0, s[14:15]
	s_mov_b32 m0, s79
	s_nop 0
	global_load_lds_dwordx4 v[156:157], off
	v_lshl_add_u64 v[156:157], v[238:239], 0, s[14:15]
	s_mov_b32 m0, s94
	s_nop 0
	global_load_lds_dwordx4 v[156:157], off
	s_waitcnt vmcnt(8)
	s_waitcnt lgkmcnt(0)
	s_barrier
	s_setprio 1
	v_mfma_f32_16x16x32_bf16 v[52:55], v[140:143], v[198:201], v[52:55]
	v_mfma_f32_16x16x32_bf16 v[48:51], v[148:151], v[198:201], v[48:51]
	v_mfma_f32_16x16x32_bf16 v[36:39], v[140:143], v[214:217], v[36:39]
	v_mfma_f32_16x16x32_bf16 v[32:35], v[148:151], v[214:217], v[32:35]
	v_mfma_f32_16x16x32_bf16 v[20:23], v[140:143], v[222:225], v[20:23]
	v_mfma_f32_16x16x32_bf16 v[16:19], v[148:151], v[222:225], v[16:19]
	v_mfma_f32_16x16x32_bf16 v[4:7], v[140:143], v[230:233], v[4:7]
	v_mfma_f32_16x16x32_bf16 v[0:3], v[148:151], v[230:233], v[0:3]
	v_mfma_f32_16x16x32_bf16 v[52:55], v[144:147], v[202:205], v[52:55]
	v_mfma_f32_16x16x32_bf16 v[48:51], v[152:155], v[202:205], v[48:51]
	v_mfma_f32_16x16x32_bf16 v[36:39], v[144:147], v[218:221], v[36:39]
	v_mfma_f32_16x16x32_bf16 v[32:35], v[152:155], v[218:221], v[32:35]
	v_mfma_f32_16x16x32_bf16 v[20:23], v[144:147], v[226:229], v[20:23]
	v_mfma_f32_16x16x32_bf16 v[16:19], v[152:155], v[226:229], v[16:19]
	v_mfma_f32_16x16x32_bf16 v[4:7], v[144:147], v[234:237], v[4:7]
	v_mfma_f32_16x16x32_bf16 v[0:3], v[152:155], v[234:237], v[0:3]
	v_mfma_f32_16x16x32_bf16 v[60:63], v[160:163], v[198:201], v[60:63]
	v_mfma_f32_16x16x32_bf16 v[56:59], v[190:193], v[198:201], v[56:59]
	v_mfma_f32_16x16x32_bf16 v[44:47], v[160:163], v[214:217], v[44:47]
	v_mfma_f32_16x16x32_bf16 v[40:43], v[190:193], v[214:217], v[40:43]
	v_mfma_f32_16x16x32_bf16 v[28:31], v[160:163], v[222:225], v[28:31]
	v_mfma_f32_16x16x32_bf16 v[24:27], v[190:193], v[222:225], v[24:27]
	v_mfma_f32_16x16x32_bf16 v[12:15], v[160:163], v[230:233], v[12:15]
	v_mfma_f32_16x16x32_bf16 v[8:11], v[190:193], v[230:233], v[8:11]
	v_mfma_f32_16x16x32_bf16 v[60:63], v[186:189], v[202:205], v[60:63]
	v_mfma_f32_16x16x32_bf16 v[56:59], v[194:197], v[202:205], v[56:59]
	v_mfma_f32_16x16x32_bf16 v[44:47], v[186:189], v[218:221], v[44:47]
	v_mfma_f32_16x16x32_bf16 v[40:43], v[194:197], v[218:221], v[40:43]
	v_mfma_f32_16x16x32_bf16 v[28:31], v[186:189], v[226:229], v[28:31]
	v_mfma_f32_16x16x32_bf16 v[24:27], v[194:197], v[226:229], v[24:27]
	v_mfma_f32_16x16x32_bf16 v[12:15], v[186:189], v[234:237], v[12:15]
	v_mfma_f32_16x16x32_bf16 v[8:11], v[194:197], v[234:237], v[8:11]
	s_setprio 0
	s_barrier
	s_add_i32 s13, s13, 2
	s_add_u32 s10, s10, 0x100
	s_addc_u32 s12, s12, 0
	s_add_u32 s40, s40, 0x100
	s_addc_u32 s41, s41, 0
	s_cmp_gt_u32 s13, 13
	s_cbranch_scc0 .LBB0_454
	s_and_b64 vcc, exec, s[66:67]
	s_cbranch_vccz .LBB0_457
	s_barrier

; #define PG8_STAGE(bufoff, gbase, voff) do { _Pragma("unroll") for (int _i = 0; _i < 2; ++_i) \
;         __builtin_amdgcn_global_load_lds((const unsigned*)((const char*)(gbase) + (voff)[_i]), (PG8_LAS unsigned*)(lds + (bufoff) + ldsw + _i * 8192), 16, 0, 0); } while (0)
; #define PG8_LDA(dst, b, h) do { _Pragma("unroll") for (int m = 0; m < 4; ++m) _Pragma("unroll") for (int k = 0; k < 2; ++k) dst[m][k] = *(const PG8_LAS bf16x8*)(lds + PG8_SA(b, h) + aoff + m * 2048 + k * 1024); } while (0)
; #define PG8_LDB(dst, b, h) do { _Pragma("unroll") for (int n = 0; n < 2; ++n) _Pragma("unroll") for (int k = 0; k < 2; ++k) dst[n][k] = *(const PG8_LAS bf16x8*)(lds + PG8_SB(b, h) + boff + n * 2048 + k * 1024); } while (0)
; #define PG8_MMA(ai, bj, At, Bt) do { __builtin_amdgcn_s_setprio(1); _Pragma("unroll") for (int m = 0; m < 4; ++m) _Pragma("unroll") for (int n = 0; n < 2; ++n) _Pragma("unroll") for (int k = 0; k < 2; ++k) \
;         acc[ai][bj][m][n] = __builtin_amdgcn_mfma_f32_16x16x32_bf16(Bt[n][k], At[m][k], acc[ai][bj][m][n], 0, 0, 0); __builtin_amdgcn_s_setprio(0); } while (0)
; #define PG8_WAIT_V(n) asm volatile("s_waitcnt vmcnt(" #n ")" ::: "memory")
; #define PG8_WAIT_L(n) asm volatile("s_waitcnt lgkmcnt(" #n ")" ::: "memory")
; template <class Epi, class Sched, bool ALIGN_EPI = false, bool SP2 = false>
; __device__ __forceinline__ void gemm_phase(PG8_LAS unsigned char* lds, const Gemm g, const Sched& S, const Epi& E) {
;     ...
;             const bool last = (t == nt - 2);
;             const char* a1 = cA + (size_t)(t + 1) * kstep;
;             const char* a2 = last ? nA : cA + (size_t)(t + 2) * kstep; const char* b2 = last ? nB : cB + (size_t)(t + 2) * kstep;
;             const char* a3 = a2 + kstep; const char* b3 = b2 + kstep;
;             if (last && has_next) S.a_ready(nxt);
;             if constexpr (SP2) {
;             PG8_LDB(B0, 0, 0); PG8_LDB(B1, 0, 1); PG8_SCHED; PG8_LDA(At, 0, 0); PG8_STAGE(PG8_SA(1, 1), a1 + hstepA, voffA);
;             PG8_WAIT_V(8); PG8_WAIT_L(0); PG8_BAR; PG8_MMA(0, 0, At, B0); PG8_MMA(0, 1, At, B1); PG8_BAR; PG8_SCHED;
;             PG8_LDA(At, 0, 1); PG8_STAGE(PG8_SB(0, 0), b2, voffB); PG8_STAGE(PG8_SB(0, 1), b2 + hstepB, voffB); PG8_STAGE(PG8_SA(0, 0), a2, voffA);
;             PG8_WAIT_V(8); PG8_WAIT_L(0); PG8_BAR; PG8_MMA(1, 0, At, B0); PG8_MMA(1, 1, At, B1); PG8_BAR; PG8_SCHED;
.LBB0_760:
	s_add_u32 s48, s22, 0x100
	s_addc_u32 s49, s23, 0
	s_add_i32 s13, 0, 0x10000
	s_cmp_eq_u32 s12, 2
	s_cselect_b32 s1, s41, s49
	s_cselect_b32 s0, s40, s48
	v_add_u32_e32 v148, s13, v150
	s_cselect_b32 s51, s69, s10
	s_cselect_b32 s50, s68, s9
	s_add_i32 s18, 0, 0x14000
	ds_read_b128 v[128:131], v148
	ds_read_b128 v[132:135], v148 offset:1024
	ds_read_b128 v[152:155], v148 offset:2048
	ds_read_b128 v[156:159], v148 offset:3072
	v_add_u32_e32 v148, s18, v150
	ds_read_b128 v[160:163], v148
	ds_read_b128 v[186:189], v148 offset:1024
	ds_read_b128 v[190:193], v148 offset:2048
	ds_read_b128 v[194:197], v148 offset:3072
	v_lshl_add_u64 v[148:149], s[22:23], 0, v[146:147]
	s_add_i32 m0, s59, 0xc000
	ds_read_b128 v[198:201], v151
	ds_read_b128 v[202:205], v151 offset:1024
	ds_read_b128 v[214:217], v151 offset:2048
	ds_read_b128 v[218:221], v151 offset:3072
	ds_read_b128 v[222:225], v151 offset:4096
	ds_read_b128 v[226:229], v151 offset:5120
	ds_read_b128 v[230:233], v151 offset:6144
	ds_read_b128 v[234:237], v151 offset:7168
	global_load_lds_dwordx4 v[148:149], off
	v_lshl_add_u64 v[148:149], s[22:23], 0, v[144:145]
	s_add_i32 m0, s59, 0xe000
	s_nop 0
	global_load_lds_dwordx4 v[148:149], off
	s_waitcnt vmcnt(8)
	s_waitcnt lgkmcnt(0)
	s_barrier
	s_setprio 1
	v_mfma_f32_16x16x32_bf16 v[124:127], v[128:131], v[198:201], v[124:127]
	v_mfma_f32_16x16x32_bf16 v[120:123], v[152:155], v[198:201], v[120:123]
	v_mfma_f32_16x16x32_bf16 v[116:119], v[128:131], v[214:217], v[116:119]
	v_mfma_f32_16x16x32_bf16 v[108:111], v[152:155], v[214:217], v[108:111]
	v_mfma_f32_16x16x32_bf16 v[100:103], v[128:131], v[222:225], v[100:103]
	v_mfma_f32_16x16x32_bf16 v[92:95], v[152:155], v[222:225], v[92:95]
	v_mfma_f32_16x16x32_bf16 v[84:87], v[128:131], v[230:233], v[84:87]
	v_mfma_f32_16x16x32_bf16 v[76:79], v[152:155], v[230:233], v[76:79]
	v_mfma_f32_16x16x32_bf16 v[124:127], v[132:135], v[202:205], v[124:127]
	v_mfma_f32_16x16x32_bf16 v[120:123], v[156:159], v[202:205], v[120:123]
	v_mfma_f32_16x16x32_bf16 v[116:119], v[132:135], v[218:221], v[116:119]
	v_mfma_f32_16x16x32_bf16 v[108:111], v[156:159], v[218:221], v[108:111]
	v_mfma_f32_16x16x32_bf16 v[100:103], v[132:135], v[226:229], v[100:103]
	v_mfma_f32_16x16x32_bf16 v[92:95], v[156:159], v[226:229], v[92:95]
	v_mfma_f32_16x16x32_bf16 v[84:87], v[132:135], v[234:237], v[84:87]
	v_mfma_f32_16x16x32_bf16 v[76:79], v[156:159], v[234:237], v[76:79]
	v_mfma_f32_16x16x32_bf16 v[112:115], v[160:163], v[198:201], v[112:115]
	v_mfma_f32_16x16x32_bf16 v[104:107], v[190:193], v[198:201], v[104:107]
	v_mfma_f32_16x16x32_bf16 v[96:99], v[160:163], v[214:217], v[96:99]
	v_mfma_f32_16x16x32_bf16 v[88:91], v[190:193], v[214:217], v[88:91]
	v_mfma_f32_16x16x32_bf16 v[80:83], v[160:163], v[222:225], v[80:83]
	v_mfma_f32_16x16x32_bf16 v[72:75], v[190:193], v[222:225], v[72:75]
	v_mfma_f32_16x16x32_bf16 v[68:71], v[160:163], v[230:233], v[68:71]
	v_mfma_f32_16x16x32_bf16 v[64:67], v[190:193], v[230:233], v[64:67]
	v_mfma_f32_16x16x32_bf16 v[112:115], v[186:189], v[202:205], v[112:115]
	v_mfma_f32_16x16x32_bf16 v[104:107], v[194:197], v[202:205], v[104:107]
	v_mfma_f32_16x16x32_bf16 v[96:99], v[186:189], v[218:221], v[96:99]
	v_mfma_f32_16x16x32_bf16 v[88:91], v[194:197], v[218:221], v[88:91]
	v_mfma_f32_16x16x32_bf16 v[80:83], v[186:189], v[226:229], v[80:83]
	v_mfma_f32_16x16x32_bf16 v[72:75], v[194:197], v[226:229], v[72:75]
	v_mfma_f32_16x16x32_bf16 v[68:71], v[186:189], v[234:237], v[68:71]
	v_mfma_f32_16x16x32_bf16 v[64:67], v[194:197], v[234:237], v[64:67]
	s_setprio 0
	s_barrier
	s_add_i32 s13, s13, s57
	v_lshl_add_u64 v[148:149], s[50:51], 0, v[140:141]
	s_mov_b32 m0, s13
	ds_read_b128 v[198:201], v151 offset:16384
	ds_read_b128 v[202:205], v151 offset:17408
	ds_read_b128 v[214:217], v151 offset:18432
	ds_read_b128 v[218:221], v151 offset:19456
	ds_read_b128 v[222:225], v151 offset:20480
	ds_read_b128 v[226:229], v151 offset:21504
	ds_read_b128 v[230:233], v151 offset:22528
	ds_read_b128 v[234:237], v151 offset:23552
	global_load_lds_dwordx4 v[148:149], off
	s_add_i32 m0, s13, 0x2000
	s_add_u32 s16, s50, 0x18000
	v_lshl_add_u64 v[166:167], s[50:51], 0, v[136:137]
	s_addc_u32 s17, s51, 0
	s_add_i32 s13, s18, s57
	global_load_lds_dwordx4 v[166:167], off
	v_lshl_add_u64 v[168:169], s[16:17], 0, v[140:141]
	s_mov_b32 m0, s13
	v_lshl_add_u64 v[238:239], s[0:1], 0, v[138:139]
	global_load_lds_dwordx4 v[168:169], off
	v_lshl_add_u64 v[168:169], s[16:17], 0, v[136:137]
	s_add_i32 m0, s13, 0x2000
	s_nop 0
	global_load_lds_dwordx4 v[168:169], off
	v_lshl_add_u64 v[168:169], s[0:1], 0, v[142:143]
	s_mov_b32 m0, s59
	s_nop 0
	global_load_lds_dwordx4 v[168:169], off
	s_mov_b32 m0, s60
	s_nop 0
	global_load_lds_dwordx4 v[238:239], off
	s_waitcnt vmcnt(8)
	s_waitcnt lgkmcnt(0)
	s_barrier
; #define PG8_STAGE(bufoff, gbase, voff) do { _Pragma("unroll") for (int _i = 0; _i < 2; ++_i) \
;         __builtin_amdgcn_global_load_lds((const unsigned*)((const char*)(gbase) + (voff)[_i]), (PG8_LAS unsigned*)(lds + (bufoff) + ldsw + _i * 8192), 16, 0, 0); } while (0)
; #define PG8_LDA(dst, b, h) do { _Pragma("unroll") for (int m = 0; m < 4; ++m) _Pragma("unroll") for (int k = 0; k < 2; ++k) dst[m][k] = *(const PG8_LAS bf16x8*)(lds + PG8_SA(b, h) + aoff + m * 2048 + k * 1024); } while (0)
; #define PG8_LDB(dst, b, h) do { _Pragma("unroll") for (int n = 0; n < 2; ++n) _Pragma("unroll") for (int k = 0; k < 2; ++k) dst[n][k] = *(const PG8_LAS bf16x8*)(lds + PG8_SB(b, h) + boff + n * 2048 + k * 1024); } while (0)
; #define PG8_MMA(ai, bj, At, Bt) do { __builtin_amdgcn_s_setprio(1); _Pragma("unroll") for (int m = 0; m < 4; ++m) _Pragma("unroll") for (int n = 0; n < 2; ++n) _Pragma("unroll") for (int k = 0; k < 2; ++k) \
;         acc[ai][bj][m][n] = __builtin_amdgcn_mfma_f32_16x16x32_bf16(Bt[n][k], At[m][k], acc[ai][bj][m][n], 0, 0, 0); __builtin_amdgcn_s_setprio(0); } while (0)
; #define PG8_WAIT_V(n) asm volatile("s_waitcnt vmcnt(" #n ")" ::: "memory")
; #define PG8_WAIT_L(n) asm volatile("s_waitcnt lgkmcnt(" #n ")" ::: "memory")
; #define PG8_BAR __builtin_amdgcn_s_barrier()
; #define PG8_SCHED __builtin_amdgcn_sched_barrier(0)
; template <class Epi, class Sched, bool ALIGN_EPI = false, bool SP2 = false>
; __device__ __forceinline__ void gemm_phase(PG8_LAS unsigned char* lds, const Gemm g, const Sched& S, const Epi& E) {
;     ...
;             PG8_WAIT_V(8); PG8_WAIT_L(0); PG8_BAR; PG8_MMA(1, 0, At, B0); PG8_MMA(1, 1, At, B1); PG8_BAR; PG8_SCHED;
;             PG8_LDB(B0, 1, 0); PG8_LDB(B1, 1, 1); PG8_SCHED; PG8_LDA(At, 1, 0); PG8_STAGE(PG8_SA(0, 1), a2 + hstepA, voffA);
;             PG8_WAIT_V(8); PG8_WAIT_L(0); PG8_BAR; PG8_MMA(0, 0, At, B0); PG8_MMA(0, 1, At, B1); PG8_BAR; PG8_SCHED;
	s_setprio 1
	v_mfma_f32_16x16x32_bf16 v[60:63], v[128:131], v[198:201], v[60:63]
	v_mfma_f32_16x16x32_bf16 v[56:59], v[152:155], v[198:201], v[56:59]
	v_mfma_f32_16x16x32_bf16 v[52:55], v[128:131], v[214:217], v[52:55]
	v_mfma_f32_16x16x32_bf16 v[44:47], v[152:155], v[214:217], v[44:47]
	v_mfma_f32_16x16x32_bf16 v[36:39], v[128:131], v[222:225], v[36:39]
	v_mfma_f32_16x16x32_bf16 v[28:31], v[152:155], v[222:225], v[28:31]
	v_mfma_f32_16x16x32_bf16 v[20:23], v[128:131], v[230:233], v[20:23]
	v_mfma_f32_16x16x32_bf16 v[12:15], v[152:155], v[230:233], v[12:15]
	v_mfma_f32_16x16x32_bf16 v[60:63], v[132:135], v[202:205], v[60:63]
	v_mfma_f32_16x16x32_bf16 v[56:59], v[156:159], v[202:205], v[56:59]
	v_mfma_f32_16x16x32_bf16 v[52:55], v[132:135], v[218:221], v[52:55]
	v_mfma_f32_16x16x32_bf16 v[44:47], v[156:159], v[218:221], v[44:47]
	v_mfma_f32_16x16x32_bf16 v[36:39], v[132:135], v[226:229], v[36:39]
	v_mfma_f32_16x16x32_bf16 v[28:31], v[156:159], v[226:229], v[28:31]
	v_mfma_f32_16x16x32_bf16 v[20:23], v[132:135], v[234:237], v[20:23]
	v_mfma_f32_16x16x32_bf16 v[12:15], v[156:159], v[234:237], v[12:15]
	v_mfma_f32_16x16x32_bf16 v[48:51], v[160:163], v[198:201], v[48:51]
	v_mfma_f32_16x16x32_bf16 v[40:43], v[190:193], v[198:201], v[40:43]
	v_mfma_f32_16x16x32_bf16 v[32:35], v[160:163], v[214:217], v[32:35]
	v_mfma_f32_16x16x32_bf16 v[24:27], v[190:193], v[214:217], v[24:27]
	v_mfma_f32_16x16x32_bf16 v[16:19], v[160:163], v[222:225], v[16:19]
	v_mfma_f32_16x16x32_bf16 v[8:11], v[190:193], v[222:225], v[8:11]
	v_mfma_f32_16x16x32_bf16 v[4:7], v[160:163], v[230:233], v[4:7]
	v_mfma_f32_16x16x32_bf16 v[0:3], v[190:193], v[230:233], v[0:3]
	v_mfma_f32_16x16x32_bf16 v[48:51], v[186:189], v[202:205], v[48:51]
	v_mfma_f32_16x16x32_bf16 v[40:43], v[194:197], v[202:205], v[40:43]
	v_mfma_f32_16x16x32_bf16 v[32:35], v[186:189], v[218:221], v[32:35]
	v_mfma_f32_16x16x32_bf16 v[24:27], v[194:197], v[218:221], v[24:27]
	v_mfma_f32_16x16x32_bf16 v[16:19], v[186:189], v[226:229], v[16:19]
	v_mfma_f32_16x16x32_bf16 v[8:11], v[194:197], v[226:229], v[8:11]
	v_mfma_f32_16x16x32_bf16 v[4:7], v[186:189], v[234:237], v[4:7]
	v_mfma_f32_16x16x32_bf16 v[0:3], v[194:197], v[234:237], v[0:3]
	s_setprio 0
	s_barrier
	s_add_i32 s13, 0, 0x18000
	s_add_i32 s16, 0, 0x1c000
	v_add_u32_e32 v156, s13, v150
	v_add_u32_e32 v164, s16, v150
	ds_read_b128 v[128:131], v156
	ds_read_b128 v[132:135], v156 offset:1024
	ds_read_b128 v[152:155], v156 offset:2048
	ds_read_b128 v[156:159], v156 offset:3072
	ds_read_b128 v[160:163], v164
	ds_read_b128 v[186:189], v164 offset:1024
	ds_read_b128 v[190:193], v164 offset:2048
	ds_read_b128 v[194:197], v164 offset:3072
	s_add_u32 s0, s0, 0x18000
	s_addc_u32 s1, s1, 0
	s_mov_b32 m0, s61
	v_lshl_add_u64 v[240:241], s[0:1], 0, v[142:143]
	ds_read_b128 v[198:201], v151 offset:32768
	ds_read_b128 v[202:205], v151 offset:33792
	ds_read_b128 v[214:217], v151 offset:34816
	ds_read_b128 v[218:221], v151 offset:35840
	ds_read_b128 v[222:225], v151 offset:36864
	ds_read_b128 v[226:229], v151 offset:37888
	ds_read_b128 v[230:233], v151 offset:38912
	ds_read_b128 v[234:237], v151 offset:39936
	global_load_lds_dwordx4 v[240:241], off
	v_lshl_add_u64 v[240:241], s[0:1], 0, v[138:139]
	s_mov_b32 m0, s62
	s_nop 0
	global_load_lds_dwordx4 v[240:241], off
	s_waitcnt vmcnt(8)
	s_waitcnt lgkmcnt(0)
	s_barrier
	s_setprio 1
	v_mfma_f32_16x16x32_bf16 v[124:127], v[128:131], v[198:201], v[124:127]
	v_mfma_f32_16x16x32_bf16 v[120:123], v[152:155], v[198:201], v[120:123]
	v_mfma_f32_16x16x32_bf16 v[116:119], v[128:131], v[214:217], v[116:119]
	v_mfma_f32_16x16x32_bf16 v[108:111], v[152:155], v[214:217], v[108:111]
	v_mfma_f32_16x16x32_bf16 v[100:103], v[128:131], v[222:225], v[100:103]
	v_mfma_f32_16x16x32_bf16 v[92:95], v[152:155], v[222:225], v[92:95]
	v_mfma_f32_16x16x32_bf16 v[84:87], v[128:131], v[230:233], v[84:87]
	v_mfma_f32_16x16x32_bf16 v[76:79], v[152:155], v[230:233], v[76:79]
	v_mfma_f32_16x16x32_bf16 v[124:127], v[132:135], v[202:205], v[124:127]
	v_mfma_f32_16x16x32_bf16 v[120:123], v[156:159], v[202:205], v[120:123]
	v_mfma_f32_16x16x32_bf16 v[116:119], v[132:135], v[218:221], v[116:119]
	v_mfma_f32_16x16x32_bf16 v[108:111], v[156:159], v[218:221], v[108:111]
	v_mfma_f32_16x16x32_bf16 v[100:103], v[132:135], v[226:229], v[100:103]
	v_mfma_f32_16x16x32_bf16 v[92:95], v[156:159], v[226:229], v[92:95]
	v_mfma_f32_16x16x32_bf16 v[84:87], v[132:135], v[234:237], v[84:87]
	v_mfma_f32_16x16x32_bf16 v[76:79], v[156:159], v[234:237], v[76:79]
	v_mfma_f32_16x16x32_bf16 v[112:115], v[160:163], v[198:201], v[112:115]
	v_mfma_f32_16x16x32_bf16 v[104:107], v[190:193], v[198:201], v[104:107]
	v_mfma_f32_16x16x32_bf16 v[96:99], v[160:163], v[214:217], v[96:99]
	v_mfma_f32_16x16x32_bf16 v[88:91], v[190:193], v[214:217], v[88:91]
	v_mfma_f32_16x16x32_bf16 v[80:83], v[160:163], v[222:225], v[80:83]
	v_mfma_f32_16x16x32_bf16 v[72:75], v[190:193], v[222:225], v[72:75]
	v_mfma_f32_16x16x32_bf16 v[68:71], v[160:163], v[230:233], v[68:71]
	v_mfma_f32_16x16x32_bf16 v[64:67], v[190:193], v[230:233], v[64:67]
	v_mfma_f32_16x16x32_bf16 v[112:115], v[186:189], v[202:205], v[112:115]
	v_mfma_f32_16x16x32_bf16 v[104:107], v[194:197], v[202:205], v[104:107]
	v_mfma_f32_16x16x32_bf16 v[96:99], v[186:189], v[218:221], v[96:99]
	v_mfma_f32_16x16x32_bf16 v[88:91], v[194:197], v[218:221], v[88:91]
	v_mfma_f32_16x16x32_bf16 v[80:83], v[186:189], v[226:229], v[80:83]
	v_mfma_f32_16x16x32_bf16 v[72:75], v[194:197], v[226:229], v[72:75]
	v_mfma_f32_16x16x32_bf16 v[68:71], v[186:189], v[234:237], v[68:71]
	v_mfma_f32_16x16x32_bf16 v[64:67], v[194:197], v[234:237], v[64:67]
	s_setprio 0
	s_barrier
; #define PG8_STAGE(bufoff, gbase, voff) do { _Pragma("unroll") for (int _i = 0; _i < 2; ++_i) \
;         __builtin_amdgcn_global_load_lds((const unsigned*)((const char*)(gbase) + (voff)[_i]), (PG8_LAS unsigned*)(lds + (bufoff) + ldsw + _i * 8192), 16, 0, 0); } while (0)
; #define PG8_LDA(dst, b, h) do { _Pragma("unroll") for (int m = 0; m < 4; ++m) _Pragma("unroll") for (int k = 0; k < 2; ++k) dst[m][k] = *(const PG8_LAS bf16x8*)(lds + PG8_SA(b, h) + aoff + m * 2048 + k * 1024); } while (0)
; #define PG8_WAIT_V(n) asm volatile("s_waitcnt vmcnt(" #n ")" ::: "memory")
; template <class Epi, class Sched, bool ALIGN_EPI = false, bool SP2 = false>
; __device__ __forceinline__ void gemm_phase(PG8_LAS unsigned char* lds, const Gemm g, const Sched& S, const Epi& E) {
;     ...
;             PG8_LDA(At, 1, 1); PG8_STAGE(PG8_SB(1, 0), b3, voffB); PG8_STAGE(PG8_SB(1, 1), b3 + hstepB, voffB); PG8_STAGE(PG8_SA(1, 0), a3, voffA);
;             PG8_WAIT_V(8); PG8_WAIT_L(0); PG8_BAR; PG8_MMA(1, 0, At, B0); PG8_MMA(1, 1, At, B1); PG8_BAR; PG8_SCHED;
;             } else {
;             PG8_LDB(B0, 0, 0); PG8_SCHED; PG8_LDA(At, 0, 0); PG8_STAGE(PG8_SA(1, 1), a1 + hstepA, voffA);
;             PG8_WAIT_L(8); PG8_BAR; PG8_WAIT_L(0); PG8_MMA(0, 0, At, B0); PG8_BAR; PG8_SCHED;
;             PG8_LDB(B1, 0, 1); PG8_STAGE(PG8_SB(0, 0), b2, voffB);
;             PG8_BAR; PG8_WAIT_L(0); PG8_MMA(0, 1, At, B1); PG8_BAR;
;             PG8_LDA(At, 0, 1); PG8_STAGE(PG8_SA(0, 0), a2, voffA);
;             PG8_BAR; PG8_WAIT_L(0); PG8_MMA(1, 0, At, B0); PG8_BAR; PG8_SCHED;
;             PG8_STAGE(PG8_SB(0, 1), b2 + hstepB, voffB);
;             PG8_WAIT_V(6); PG8_BAR; PG8_MMA(1, 1, At, B1); PG8_BAR;
;             PG8_LDB(B0, 1, 0); PG8_SCHED; PG8_LDA(At, 1, 0); PG8_STAGE(PG8_SA(0, 1), a2 + hstepA, voffA);
;             PG8_WAIT_L(8); PG8_BAR; PG8_WAIT_L(0); PG8_MMA(0, 0, At, B0); PG8_BAR; PG8_SCHED;
;             PG8_LDB(B1, 1, 1); PG8_STAGE(PG8_SB(1, 0), b3, voffB);
;             PG8_BAR; PG8_WAIT_L(0); PG8_MMA(0, 1, At, B1); PG8_BAR;
;             PG8_LDA(At, 1, 1); PG8_STAGE(PG8_SA(1, 0), a3, voffA);
;             PG8_BAR; PG8_WAIT_L(0); PG8_MMA(1, 0, At, B0); PG8_BAR; PG8_SCHED;
;             PG8_STAGE(PG8_SB(1, 1), b3 + hstepB, voffB);
;             PG8_WAIT_V(6); PG8_BAR; PG8_MMA(1, 1, At, B1); PG8_BAR;
;             }
;         }
;         if constexpr (ALIGN_EPI) { if (wr == 0) PG8_BAR; }
	s_add_i32 s0, s13, s57
	v_lshl_add_u64 v[148:149], v[148:149], 0, s[14:15]
	s_mov_b32 m0, s0
	ds_read_b128 v[198:201], v151 offset:49152
	ds_read_b128 v[202:205], v151 offset:50176
	ds_read_b128 v[214:217], v151 offset:51200
	ds_read_b128 v[218:221], v151 offset:52224
	ds_read_b128 v[222:225], v151 offset:53248
	ds_read_b128 v[226:229], v151 offset:54272
	ds_read_b128 v[230:233], v151 offset:55296
	ds_read_b128 v[234:237], v151 offset:56320
	global_load_lds_dwordx4 v[148:149], off
	s_add_i32 m0, s0, 0x2000
	s_add_u32 s0, s50, 0x18080
	v_lshl_add_u64 v[148:149], v[166:167], 0, s[14:15]
	s_addc_u32 s1, s51, 0
	s_add_i32 s13, s16, s57
	global_load_lds_dwordx4 v[148:149], off
	v_lshl_add_u64 v[148:149], s[0:1], 0, v[140:141]
	s_mov_b32 m0, s13
	s_nop 0
	global_load_lds_dwordx4 v[148:149], off
	v_lshl_add_u64 v[148:149], s[0:1], 0, v[136:137]
	s_add_i32 m0, s13, 0x2000
	s_nop 0
	global_load_lds_dwordx4 v[148:149], off
	v_lshl_add_u64 v[148:149], v[168:169], 0, s[14:15]
	s_mov_b32 m0, s70
	s_nop 0
	global_load_lds_dwordx4 v[148:149], off
	v_lshl_add_u64 v[148:149], v[238:239], 0, s[14:15]
	s_mov_b32 m0, s71
	s_nop 0
	global_load_lds_dwordx4 v[148:149], off
	s_waitcnt vmcnt(8)
	s_waitcnt lgkmcnt(0)
	s_barrier
	s_setprio 1
	v_mfma_f32_16x16x32_bf16 v[60:63], v[128:131], v[198:201], v[60:63]
	v_mfma_f32_16x16x32_bf16 v[56:59], v[152:155], v[198:201], v[56:59]
	v_mfma_f32_16x16x32_bf16 v[52:55], v[128:131], v[214:217], v[52:55]
	v_mfma_f32_16x16x32_bf16 v[44:47], v[152:155], v[214:217], v[44:47]
	v_mfma_f32_16x16x32_bf16 v[36:39], v[128:131], v[222:225], v[36:39]
	v_mfma_f32_16x16x32_bf16 v[28:31], v[152:155], v[222:225], v[28:31]
	v_mfma_f32_16x16x32_bf16 v[20:23], v[128:131], v[230:233], v[20:23]
	v_mfma_f32_16x16x32_bf16 v[12:15], v[152:155], v[230:233], v[12:15]
	v_mfma_f32_16x16x32_bf16 v[60:63], v[132:135], v[202:205], v[60:63]
	v_mfma_f32_16x16x32_bf16 v[56:59], v[156:159], v[202:205], v[56:59]
	v_mfma_f32_16x16x32_bf16 v[52:55], v[132:135], v[218:221], v[52:55]
	v_mfma_f32_16x16x32_bf16 v[44:47], v[156:159], v[218:221], v[44:47]
	v_mfma_f32_16x16x32_bf16 v[36:39], v[132:135], v[226:229], v[36:39]
	v_mfma_f32_16x16x32_bf16 v[28:31], v[156:159], v[226:229], v[28:31]
	v_mfma_f32_16x16x32_bf16 v[20:23], v[132:135], v[234:237], v[20:23]
	v_mfma_f32_16x16x32_bf16 v[12:15], v[156:159], v[234:237], v[12:15]
	v_mfma_f32_16x16x32_bf16 v[48:51], v[160:163], v[198:201], v[48:51]
	v_mfma_f32_16x16x32_bf16 v[40:43], v[190:193], v[198:201], v[40:43]
	v_mfma_f32_16x16x32_bf16 v[32:35], v[160:163], v[214:217], v[32:35]
	v_mfma_f32_16x16x32_bf16 v[24:27], v[190:193], v[214:217], v[24:27]
	v_mfma_f32_16x16x32_bf16 v[16:19], v[160:163], v[222:225], v[16:19]
	v_mfma_f32_16x16x32_bf16 v[8:11], v[190:193], v[222:225], v[8:11]
	v_mfma_f32_16x16x32_bf16 v[4:7], v[160:163], v[230:233], v[4:7]
	v_mfma_f32_16x16x32_bf16 v[0:3], v[190:193], v[230:233], v[0:3]
	v_mfma_f32_16x16x32_bf16 v[48:51], v[186:189], v[202:205], v[48:51]
	v_mfma_f32_16x16x32_bf16 v[40:43], v[194:197], v[202:205], v[40:43]
	v_mfma_f32_16x16x32_bf16 v[32:35], v[186:189], v[218:221], v[32:35]
	v_mfma_f32_16x16x32_bf16 v[24:27], v[194:197], v[218:221], v[24:27]
	v_mfma_f32_16x16x32_bf16 v[16:19], v[186:189], v[226:229], v[16:19]
	v_mfma_f32_16x16x32_bf16 v[8:11], v[194:197], v[226:229], v[8:11]
	v_mfma_f32_16x16x32_bf16 v[4:7], v[186:189], v[234:237], v[4:7]
	v_mfma_f32_16x16x32_bf16 v[0:3], v[194:197], v[234:237], v[0:3]
	s_setprio 0
	s_barrier
	s_add_i32 s12, s12, 2
	s_add_u32 s9, s9, 0x100
	s_addc_u32 s10, s10, 0
	s_cmp_gt_u32 s12, 3
	s_mov_b64 s[22:23], s[48:49]
	s_cbranch_scc0 .LBB0_760
	s_and_b64 vcc, exec, s[66:67]
	s_cbranch_vccz .LBB0_763
	s_barrier

; #define PG8_STAGE(bufoff, gbase, voff) do { _Pragma("unroll") for (int _i = 0; _i < 2; ++_i) \
;         __builtin_amdgcn_global_load_lds((const unsigned*)((const char*)(gbase) + (voff)[_i]), (PG8_LAS unsigned*)(lds + (bufoff) + ldsw + _i * 8192), 16, 0, 0); } while (0)
; #define PG8_LDA(dst, b, h) do { _Pragma("unroll") for (int m = 0; m < 4; ++m) _Pragma("unroll") for (int k = 0; k < 2; ++k) dst[m][k] = *(const PG8_LAS bf16x8*)(lds + PG8_SA(b, h) + aoff + m * 2048 + k * 1024); } while (0)
; #define PG8_LDB(dst, b, h) do { _Pragma("unroll") for (int n = 0; n < 2; ++n) _Pragma("unroll") for (int k = 0; k < 2; ++k) dst[n][k] = *(const PG8_LAS bf16x8*)(lds + PG8_SB(b, h) + boff + n * 2048 + k * 1024); } while (0)
; #define PG8_WAIT_V(n) asm volatile("s_waitcnt vmcnt(" #n ")" ::: "memory")
; #define PG8_WAIT_L(n) asm volatile("s_waitcnt lgkmcnt(" #n ")" ::: "memory")
; #define PG8_BAR __builtin_amdgcn_s_barrier()
; #define PG8_SCHED __builtin_amdgcn_sched_barrier(0)
; template <class Epi, class Sched, bool ALIGN_EPI = false, bool SP2 = false>
; __device__ __forceinline__ void gemm_phase(PG8_LAS unsigned char* lds, const Gemm g, const Sched& S, const Epi& E) {
;     ...
;         const char* nA = has_next ? (const char*)g.A + (size_t)nxt.pm * tstepA + (size_t)nxt.ks * ksl : cA; const char* nB = has_next ? (const char*)g.Bt + (size_t)nxt.pn * tstepB + (size_t)nxt.ks * ksl : cB;
;         for (int t = 0; t < nt; t += 2) {
;             const bool last = (t == nt - 2);
;             const char* a1 = cA + (size_t)(t + 1) * kstep;
;             const char* a2 = last ? nA : cA + (size_t)(t + 2) * kstep; const char* b2 = last ? nB : cB + (size_t)(t + 2) * kstep;
;             const char* a3 = a2 + kstep; const char* b3 = b2 + kstep;
;             if (last && has_next) S.a_ready(nxt);
;             if constexpr (SP2) {
;             PG8_LDB(B0, 0, 0); PG8_LDB(B1, 0, 1); PG8_SCHED; PG8_LDA(At, 0, 0); PG8_STAGE(PG8_SA(1, 1), a1 + hstepA, voffA);
;             PG8_WAIT_V(8); PG8_WAIT_L(0); PG8_BAR; PG8_MMA(0, 0, At, B0); PG8_MMA(0, 1, At, B1); PG8_BAR; PG8_SCHED;
;             PG8_LDA(At, 0, 1); PG8_STAGE(PG8_SB(0, 0), b2, voffB); PG8_STAGE(PG8_SB(0, 1), b2 + hstepB, voffB); PG8_STAGE(PG8_SA(0, 0), a2, voffA);
;             PG8_WAIT_V(8); PG8_WAIT_L(0); PG8_BAR; PG8_MMA(1, 0, At, B0); PG8_MMA(1, 1, At, B1); PG8_BAR; PG8_SCHED;
.LBB0_783:
	s_add_u32 s31, s60, s0
	s_addc_u32 s33, s61, 0
	s_add_u32 s1, s31, 0x100
	s_addc_u32 s44, s33, 0
	s_and_b64 s[36:37], s[64:65], exec
	s_cselect_b32 s69, s17, s44
	s_cselect_b32 s68, s51, s1
	s_add_u32 s0, s54, s0
	s_addc_u32 s1, s55, 0
	s_add_u32 s36, s0, 0x100
	s_addc_u32 s37, s1, 0
	s_add_i32 s44, 0, 0x10000
	s_and_b64 s[0:1], s[64:65], exec
	s_cselect_b32 s71, s49, s37
	s_cselect_b32 s70, s30, s36
	s_add_i32 s45, 0, 0x14000
	s_add_u32 s0, s31, 0x10080
	s_addc_u32 s1, s33, 0
	s_add_i32 s97, s44, s80
	s_add_i32 m0, s4, 0xc000
	s_add_i32 s53, s4, 0xe000
	s_add_i32 s36, s97, 0x2000
	s_add_u32 s72, s70, 0x10000
	v_add_u32_e32 v148, s44, v134
	v_add_u32_e32 v166, s45, v134
	s_addc_u32 s73, s71, 0
	s_add_i32 s37, s45, s80
	ds_read_b128 v[136:139], v148
	ds_read_b128 v[140:143], v148 offset:1024
	ds_read_b128 v[144:147], v148 offset:2048
	ds_read_b128 v[148:151], v148 offset:3072
	ds_read_b128 v[152:155], v166
	ds_read_b128 v[156:159], v166 offset:1024
	ds_read_b128 v[160:163], v166 offset:2048
	ds_read_b128 v[186:189], v166 offset:3072
	s_add_i32 s96, s37, 0x2000
	s_add_i32 vcc_lo, 0, 0x18000
	s_add_i32 vcc_hi, 0, 0x1c000
	s_add_u32 s66, s68, 0x10000
	s_addc_u32 s67, s69, 0
	s_add_i32 s31, vcc_lo, s80
	s_add_i32 s33, s31, 0x2000
	s_add_u32 s64, s70, 0x10080
	s_addc_u32 s65, s71, 0
	s_add_i32 s45, vcc_hi, s80
	s_add_i32 s44, s45, 0x2000
	v_lshl_add_u64 v[166:167], s[0:1], 0, v[132:133]
	ds_read_b128 v[190:193], v135
	ds_read_b128 v[194:197], v135 offset:1024
	ds_read_b128 v[198:201], v135 offset:2048
	ds_read_b128 v[202:205], v135 offset:3072
	ds_read_b128 v[214:217], v135 offset:4096
	ds_read_b128 v[218:221], v135 offset:5120
	ds_read_b128 v[222:225], v135 offset:6144
	ds_read_b128 v[226:229], v135 offset:7168
	global_load_lds_dwordx4 v[166:167], off
	v_lshl_add_u64 v[166:167], s[0:1], 0, v[130:131]
	s_mov_b32 m0, s53
	s_nop 0
	global_load_lds_dwordx4 v[166:167], off
	s_waitcnt vmcnt(8)
	s_waitcnt lgkmcnt(0)
	s_barrier
	s_setprio 1
	v_mfma_f32_16x16x32_bf16 v[124:127], v[136:139], v[190:193], v[124:127]
	v_mfma_f32_16x16x32_bf16 v[120:123], v[144:147], v[190:193], v[120:123]
	v_mfma_f32_16x16x32_bf16 v[116:119], v[136:139], v[198:201], v[116:119]
	v_mfma_f32_16x16x32_bf16 v[112:115], v[144:147], v[198:201], v[112:115]
	v_mfma_f32_16x16x32_bf16 v[100:103], v[136:139], v[214:217], v[100:103]
	v_mfma_f32_16x16x32_bf16 v[96:99], v[144:147], v[214:217], v[96:99]
	v_mfma_f32_16x16x32_bf16 v[84:87], v[136:139], v[222:225], v[84:87]
	v_mfma_f32_16x16x32_bf16 v[80:83], v[144:147], v[222:225], v[80:83]
	v_mfma_f32_16x16x32_bf16 v[124:127], v[140:143], v[194:197], v[124:127]
	v_mfma_f32_16x16x32_bf16 v[120:123], v[148:151], v[194:197], v[120:123]
	v_mfma_f32_16x16x32_bf16 v[116:119], v[140:143], v[202:205], v[116:119]
	v_mfma_f32_16x16x32_bf16 v[112:115], v[148:151], v[202:205], v[112:115]
	v_mfma_f32_16x16x32_bf16 v[100:103], v[140:143], v[218:221], v[100:103]
	v_mfma_f32_16x16x32_bf16 v[96:99], v[148:151], v[218:221], v[96:99]
	v_mfma_f32_16x16x32_bf16 v[84:87], v[140:143], v[226:229], v[84:87]
	v_mfma_f32_16x16x32_bf16 v[80:83], v[148:151], v[226:229], v[80:83]
	v_mfma_f32_16x16x32_bf16 v[108:111], v[152:155], v[190:193], v[108:111]
	v_mfma_f32_16x16x32_bf16 v[104:107], v[160:163], v[190:193], v[104:107]
	v_mfma_f32_16x16x32_bf16 v[92:95], v[152:155], v[198:201], v[92:95]
	v_mfma_f32_16x16x32_bf16 v[88:91], v[160:163], v[198:201], v[88:91]
	v_mfma_f32_16x16x32_bf16 v[76:79], v[152:155], v[214:217], v[76:79]
	v_mfma_f32_16x16x32_bf16 v[72:75], v[160:163], v[214:217], v[72:75]
	v_mfma_f32_16x16x32_bf16 v[68:71], v[152:155], v[222:225], v[68:71]
	v_mfma_f32_16x16x32_bf16 v[64:67], v[160:163], v[222:225], v[64:67]
	v_mfma_f32_16x16x32_bf16 v[108:111], v[156:159], v[194:197], v[108:111]
	v_mfma_f32_16x16x32_bf16 v[104:107], v[186:189], v[194:197], v[104:107]
	v_mfma_f32_16x16x32_bf16 v[92:95], v[156:159], v[202:205], v[92:95]
	v_mfma_f32_16x16x32_bf16 v[88:91], v[186:189], v[202:205], v[88:91]
	v_mfma_f32_16x16x32_bf16 v[76:79], v[156:159], v[218:221], v[76:79]
	v_mfma_f32_16x16x32_bf16 v[72:75], v[186:189], v[218:221], v[72:75]
	v_mfma_f32_16x16x32_bf16 v[68:71], v[156:159], v[226:229], v[68:71]
	v_mfma_f32_16x16x32_bf16 v[64:67], v[186:189], v[226:229], v[64:67]
	s_setprio 0
	s_barrier
	s_mov_b32 m0, s97
	v_lshl_add_u64 v[166:167], s[70:71], 0, v[164:165]
	ds_read_b128 v[190:193], v135 offset:16384
	ds_read_b128 v[194:197], v135 offset:17408
	ds_read_b128 v[198:201], v135 offset:18432
	ds_read_b128 v[202:205], v135 offset:19456
	ds_read_b128 v[214:217], v135 offset:20480
	ds_read_b128 v[218:221], v135 offset:21504
	ds_read_b128 v[222:225], v135 offset:22528
	ds_read_b128 v[226:229], v135 offset:23552
	global_load_lds_dwordx4 v[166:167], off
	v_lshl_add_u64 v[168:169], s[70:71], 0, v[128:129]
	s_mov_b32 m0, s36
	v_lshl_add_u64 v[230:231], s[72:73], 0, v[164:165]
	global_load_lds_dwordx4 v[168:169], off
	s_mov_b32 m0, s37
	v_lshl_add_u64 v[232:233], s[68:69], 0, v[130:131]
	global_load_lds_dwordx4 v[230:231], off
	v_lshl_add_u64 v[230:231], s[72:73], 0, v[128:129]
	s_mov_b32 m0, s96
	s_nop 0
	global_load_lds_dwordx4 v[230:231], off
	v_lshl_add_u64 v[230:231], s[68:69], 0, v[132:133]
	s_mov_b32 m0, s4
	s_nop 0
	global_load_lds_dwordx4 v[230:231], off
	s_mov_b32 m0, s10
	s_nop 0
	global_load_lds_dwordx4 v[232:233], off
	s_waitcnt vmcnt(8)
	s_waitcnt lgkmcnt(0)
	s_barrier
; #define PG8_STAGE(bufoff, gbase, voff) do { _Pragma("unroll") for (int _i = 0; _i < 2; ++_i) \
;         __builtin_amdgcn_global_load_lds((const unsigned*)((const char*)(gbase) + (voff)[_i]), (PG8_LAS unsigned*)(lds + (bufoff) + ldsw + _i * 8192), 16, 0, 0); } while (0)
; #define PG8_LDA(dst, b, h) do { _Pragma("unroll") for (int m = 0; m < 4; ++m) _Pragma("unroll") for (int k = 0; k < 2; ++k) dst[m][k] = *(const PG8_LAS bf16x8*)(lds + PG8_SA(b, h) + aoff + m * 2048 + k * 1024); } while (0)
; #define PG8_LDB(dst, b, h) do { _Pragma("unroll") for (int n = 0; n < 2; ++n) _Pragma("unroll") for (int k = 0; k < 2; ++k) dst[n][k] = *(const PG8_LAS bf16x8*)(lds + PG8_SB(b, h) + boff + n * 2048 + k * 1024); } while (0)
; #define PG8_MMA(ai, bj, At, Bt) do { __builtin_amdgcn_s_setprio(1); _Pragma("unroll") for (int m = 0; m < 4; ++m) _Pragma("unroll") for (int n = 0; n < 2; ++n) _Pragma("unroll") for (int k = 0; k < 2; ++k) \
;         acc[ai][bj][m][n] = __builtin_amdgcn_mfma_f32_16x16x32_bf16(Bt[n][k], At[m][k], acc[ai][bj][m][n], 0, 0, 0); __builtin_amdgcn_s_setprio(0); } while (0)
; #define PG8_WAIT_V(n) asm volatile("s_waitcnt vmcnt(" #n ")" ::: "memory")
; #define PG8_WAIT_L(n) asm volatile("s_waitcnt lgkmcnt(" #n ")" ::: "memory")
; #define PG8_BAR __builtin_amdgcn_s_barrier()
; #define PG8_SCHED __builtin_amdgcn_sched_barrier(0)
; template <class Epi, class Sched, bool ALIGN_EPI = false, bool SP2 = false>
; __device__ __forceinline__ void gemm_phase(PG8_LAS unsigned char* lds, const Gemm g, const Sched& S, const Epi& E) {
;     ...
;             PG8_WAIT_V(8); PG8_WAIT_L(0); PG8_BAR; PG8_MMA(1, 0, At, B0); PG8_MMA(1, 1, At, B1); PG8_BAR; PG8_SCHED;
;             PG8_LDB(B0, 1, 0); PG8_LDB(B1, 1, 1); PG8_SCHED; PG8_LDA(At, 1, 0); PG8_STAGE(PG8_SA(0, 1), a2 + hstepA, voffA);
;             PG8_WAIT_V(8); PG8_WAIT_L(0); PG8_BAR; PG8_MMA(0, 0, At, B0); PG8_MMA(0, 1, At, B1); PG8_BAR; PG8_SCHED;
	s_setprio 1
	v_mfma_f32_16x16x32_bf16 v[60:63], v[136:139], v[190:193], v[60:63]
	v_mfma_f32_16x16x32_bf16 v[56:59], v[144:147], v[190:193], v[56:59]
	v_mfma_f32_16x16x32_bf16 v[52:55], v[136:139], v[198:201], v[52:55]
	v_mfma_f32_16x16x32_bf16 v[48:51], v[144:147], v[198:201], v[48:51]
	v_mfma_f32_16x16x32_bf16 v[36:39], v[136:139], v[214:217], v[36:39]
	v_mfma_f32_16x16x32_bf16 v[32:35], v[144:147], v[214:217], v[32:35]
	v_mfma_f32_16x16x32_bf16 v[20:23], v[136:139], v[222:225], v[20:23]
	v_mfma_f32_16x16x32_bf16 v[16:19], v[144:147], v[222:225], v[16:19]
	v_mfma_f32_16x16x32_bf16 v[60:63], v[140:143], v[194:197], v[60:63]
	v_mfma_f32_16x16x32_bf16 v[56:59], v[148:151], v[194:197], v[56:59]
	v_mfma_f32_16x16x32_bf16 v[52:55], v[140:143], v[202:205], v[52:55]
	v_mfma_f32_16x16x32_bf16 v[48:51], v[148:151], v[202:205], v[48:51]
	v_mfma_f32_16x16x32_bf16 v[36:39], v[140:143], v[218:221], v[36:39]
	v_mfma_f32_16x16x32_bf16 v[32:35], v[148:151], v[218:221], v[32:35]
	v_mfma_f32_16x16x32_bf16 v[20:23], v[140:143], v[226:229], v[20:23]
	v_mfma_f32_16x16x32_bf16 v[16:19], v[148:151], v[226:229], v[16:19]
	v_mfma_f32_16x16x32_bf16 v[44:47], v[152:155], v[190:193], v[44:47]
	v_mfma_f32_16x16x32_bf16 v[40:43], v[160:163], v[190:193], v[40:43]
	v_mfma_f32_16x16x32_bf16 v[28:31], v[152:155], v[198:201], v[28:31]
	v_mfma_f32_16x16x32_bf16 v[24:27], v[160:163], v[198:201], v[24:27]
	v_mfma_f32_16x16x32_bf16 v[12:15], v[152:155], v[214:217], v[12:15]
	v_mfma_f32_16x16x32_bf16 v[8:11], v[160:163], v[214:217], v[8:11]
	v_mfma_f32_16x16x32_bf16 v[4:7], v[152:155], v[222:225], v[4:7]
	v_mfma_f32_16x16x32_bf16 v[0:3], v[160:163], v[222:225], v[0:3]
	v_mfma_f32_16x16x32_bf16 v[44:47], v[156:159], v[194:197], v[44:47]
	v_mfma_f32_16x16x32_bf16 v[40:43], v[186:189], v[194:197], v[40:43]
	v_mfma_f32_16x16x32_bf16 v[28:31], v[156:159], v[202:205], v[28:31]
	v_mfma_f32_16x16x32_bf16 v[24:27], v[186:189], v[202:205], v[24:27]
	v_mfma_f32_16x16x32_bf16 v[12:15], v[156:159], v[218:221], v[12:15]
	v_mfma_f32_16x16x32_bf16 v[8:11], v[186:189], v[218:221], v[8:11]
	v_mfma_f32_16x16x32_bf16 v[4:7], v[156:159], v[226:229], v[4:7]
	v_mfma_f32_16x16x32_bf16 v[0:3], v[186:189], v[226:229], v[0:3]
	s_setprio 0
	s_barrier
	v_add_u32_e32 v148, vcc_lo, v134
	v_add_u32_e32 v186, vcc_hi, v134
	ds_read_b128 v[136:139], v148
	ds_read_b128 v[140:143], v148 offset:1024
	ds_read_b128 v[144:147], v148 offset:2048
	ds_read_b128 v[148:151], v148 offset:3072
	ds_read_b128 v[152:155], v186
	ds_read_b128 v[156:159], v186 offset:1024
	ds_read_b128 v[160:163], v186 offset:2048
	ds_read_b128 v[186:189], v186 offset:3072
	s_mov_b32 m0, s8
	v_lshl_add_u64 v[234:235], s[66:67], 0, v[132:133]
	ds_read_b128 v[190:193], v135 offset:32768
	ds_read_b128 v[194:197], v135 offset:33792
	ds_read_b128 v[198:201], v135 offset:34816
	ds_read_b128 v[202:205], v135 offset:35840
	ds_read_b128 v[214:217], v135 offset:36864
	ds_read_b128 v[218:221], v135 offset:37888
	ds_read_b128 v[222:225], v135 offset:38912
	ds_read_b128 v[226:229], v135 offset:39936
	global_load_lds_dwordx4 v[234:235], off
	v_lshl_add_u64 v[234:235], s[66:67], 0, v[130:131]
	s_mov_b32 m0, s9
	s_nop 0
	global_load_lds_dwordx4 v[234:235], off
	s_waitcnt vmcnt(8)
	s_waitcnt lgkmcnt(0)
	s_barrier
	s_setprio 1
	v_mfma_f32_16x16x32_bf16 v[124:127], v[136:139], v[190:193], v[124:127]
	v_mfma_f32_16x16x32_bf16 v[120:123], v[144:147], v[190:193], v[120:123]
	v_mfma_f32_16x16x32_bf16 v[116:119], v[136:139], v[198:201], v[116:119]
	v_mfma_f32_16x16x32_bf16 v[112:115], v[144:147], v[198:201], v[112:115]
	v_mfma_f32_16x16x32_bf16 v[100:103], v[136:139], v[214:217], v[100:103]
	v_mfma_f32_16x16x32_bf16 v[96:99], v[144:147], v[214:217], v[96:99]
	v_mfma_f32_16x16x32_bf16 v[84:87], v[136:139], v[222:225], v[84:87]
	v_mfma_f32_16x16x32_bf16 v[80:83], v[144:147], v[222:225], v[80:83]
	v_mfma_f32_16x16x32_bf16 v[124:127], v[140:143], v[194:197], v[124:127]
	v_mfma_f32_16x16x32_bf16 v[120:123], v[148:151], v[194:197], v[120:123]
	v_mfma_f32_16x16x32_bf16 v[116:119], v[140:143], v[202:205], v[116:119]
	v_mfma_f32_16x16x32_bf16 v[112:115], v[148:151], v[202:205], v[112:115]
	v_mfma_f32_16x16x32_bf16 v[100:103], v[140:143], v[218:221], v[100:103]
	v_mfma_f32_16x16x32_bf16 v[96:99], v[148:151], v[218:221], v[96:99]
	v_mfma_f32_16x16x32_bf16 v[84:87], v[140:143], v[226:229], v[84:87]
	v_mfma_f32_16x16x32_bf16 v[80:83], v[148:151], v[226:229], v[80:83]
	v_mfma_f32_16x16x32_bf16 v[108:111], v[152:155], v[190:193], v[108:111]
	v_mfma_f32_16x16x32_bf16 v[104:107], v[160:163], v[190:193], v[104:107]
	v_mfma_f32_16x16x32_bf16 v[92:95], v[152:155], v[198:201], v[92:95]
	v_mfma_f32_16x16x32_bf16 v[88:91], v[160:163], v[198:201], v[88:91]
	v_mfma_f32_16x16x32_bf16 v[76:79], v[152:155], v[214:217], v[76:79]
	v_mfma_f32_16x16x32_bf16 v[72:75], v[160:163], v[214:217], v[72:75]
	v_mfma_f32_16x16x32_bf16 v[68:71], v[152:155], v[222:225], v[68:71]
	v_mfma_f32_16x16x32_bf16 v[64:67], v[160:163], v[222:225], v[64:67]
	v_mfma_f32_16x16x32_bf16 v[108:111], v[156:159], v[194:197], v[108:111]
	v_mfma_f32_16x16x32_bf16 v[104:107], v[186:189], v[194:197], v[104:107]
	v_mfma_f32_16x16x32_bf16 v[92:95], v[156:159], v[202:205], v[92:95]
	v_mfma_f32_16x16x32_bf16 v[88:91], v[186:189], v[202:205], v[88:91]
	v_mfma_f32_16x16x32_bf16 v[76:79], v[156:159], v[218:221], v[76:79]
	v_mfma_f32_16x16x32_bf16 v[72:75], v[186:189], v[218:221], v[72:75]
	v_mfma_f32_16x16x32_bf16 v[68:71], v[156:159], v[226:229], v[68:71]
	v_mfma_f32_16x16x32_bf16 v[64:67], v[186:189], v[226:229], v[64:67]
	s_setprio 0
	s_barrier
; #define PG8_STAGE(bufoff, gbase, voff) do { _Pragma("unroll") for (int _i = 0; _i < 2; ++_i) \
;         __builtin_amdgcn_global_load_lds((const unsigned*)((const char*)(gbase) + (voff)[_i]), (PG8_LAS unsigned*)(lds + (bufoff) + ldsw + _i * 8192), 16, 0, 0); } while (0)
; #define PG8_LDA(dst, b, h) do { _Pragma("unroll") for (int m = 0; m < 4; ++m) _Pragma("unroll") for (int k = 0; k < 2; ++k) dst[m][k] = *(const PG8_LAS bf16x8*)(lds + PG8_SA(b, h) + aoff + m * 2048 + k * 1024); } while (0)
; #define PG8_WAIT_V(n) asm volatile("s_waitcnt vmcnt(" #n ")" ::: "memory")
; template <class Epi, class Sched, bool ALIGN_EPI = false, bool SP2 = false>
; __device__ __forceinline__ void gemm_phase(PG8_LAS unsigned char* lds, const Gemm g, const Sched& S, const Epi& E) {
;     ...
;             PG8_LDA(At, 1, 1); PG8_STAGE(PG8_SB(1, 0), b3, voffB); PG8_STAGE(PG8_SB(1, 1), b3 + hstepB, voffB); PG8_STAGE(PG8_SA(1, 0), a3, voffA);
;             PG8_WAIT_V(8); PG8_WAIT_L(0); PG8_BAR; PG8_MMA(1, 0, At, B0); PG8_MMA(1, 1, At, B1); PG8_BAR; PG8_SCHED;
;             } else {
;             PG8_LDB(B0, 0, 0); PG8_SCHED; PG8_LDA(At, 0, 0); PG8_STAGE(PG8_SA(1, 1), a1 + hstepA, voffA);
;             PG8_WAIT_L(8); PG8_BAR; PG8_WAIT_L(0); PG8_MMA(0, 0, At, B0); PG8_BAR; PG8_SCHED;
;             PG8_LDB(B1, 0, 1); PG8_STAGE(PG8_SB(0, 0), b2, voffB);
;             PG8_BAR; PG8_WAIT_L(0); PG8_MMA(0, 1, At, B1); PG8_BAR;
;             PG8_LDA(At, 0, 1); PG8_STAGE(PG8_SA(0, 0), a2, voffA);
;             PG8_BAR; PG8_WAIT_L(0); PG8_MMA(1, 0, At, B0); PG8_BAR; PG8_SCHED;
;             PG8_STAGE(PG8_SB(0, 1), b2 + hstepB, voffB);
;             PG8_WAIT_V(6); PG8_BAR; PG8_MMA(1, 1, At, B1); PG8_BAR;
;             PG8_LDB(B0, 1, 0); PG8_SCHED; PG8_LDA(At, 1, 0); PG8_STAGE(PG8_SA(0, 1), a2 + hstepA, voffA);
;             PG8_WAIT_L(8); PG8_BAR; PG8_WAIT_L(0); PG8_MMA(0, 0, At, B0); PG8_BAR; PG8_SCHED;
;             PG8_LDB(B1, 1, 1); PG8_STAGE(PG8_SB(1, 0), b3, voffB);
;             PG8_BAR; PG8_WAIT_L(0); PG8_MMA(0, 1, At, B1); PG8_BAR;
;             PG8_LDA(At, 1, 1); PG8_STAGE(PG8_SA(1, 0), a3, voffA);
;             PG8_BAR; PG8_WAIT_L(0); PG8_MMA(1, 0, At, B0); PG8_BAR; PG8_SCHED;
;             PG8_STAGE(PG8_SB(1, 1), b3 + hstepB, voffB);
;             PG8_WAIT_V(6); PG8_BAR; PG8_MMA(1, 1, At, B1); PG8_BAR;
;             }
;         }
;         if constexpr (ALIGN_EPI) { if (wr == 0) PG8_BAR; }
	s_mov_b32 m0, s31
	v_lshl_add_u64 v[166:167], v[166:167], 0, s[14:15]
	ds_read_b128 v[190:193], v135 offset:49152
	ds_read_b128 v[194:197], v135 offset:50176
	ds_read_b128 v[198:201], v135 offset:51200
	ds_read_b128 v[202:205], v135 offset:52224
	ds_read_b128 v[214:217], v135 offset:53248
	ds_read_b128 v[218:221], v135 offset:54272
	ds_read_b128 v[222:225], v135 offset:55296
	ds_read_b128 v[226:229], v135 offset:56320
	global_load_lds_dwordx4 v[166:167], off
	v_lshl_add_u64 v[166:167], v[168:169], 0, s[14:15]
	s_mov_b32 m0, s33
	s_nop 0
	global_load_lds_dwordx4 v[166:167], off
	v_lshl_add_u64 v[166:167], s[64:65], 0, v[164:165]
	s_mov_b32 m0, s45
	s_nop 0
	global_load_lds_dwordx4 v[166:167], off
	v_lshl_add_u64 v[166:167], s[64:65], 0, v[128:129]
	s_mov_b32 m0, s44
	s_nop 0
	global_load_lds_dwordx4 v[166:167], off
	v_lshl_add_u64 v[166:167], v[230:231], 0, s[14:15]
	s_mov_b32 m0, s19
	s_nop 0
	global_load_lds_dwordx4 v[166:167], off
	v_lshl_add_u64 v[166:167], v[232:233], 0, s[14:15]
	s_mov_b32 m0, s92
	s_nop 0
	global_load_lds_dwordx4 v[166:167], off
	s_waitcnt vmcnt(8)
	s_waitcnt lgkmcnt(0)
	s_barrier
	s_setprio 1
	v_mfma_f32_16x16x32_bf16 v[60:63], v[136:139], v[190:193], v[60:63]
	v_mfma_f32_16x16x32_bf16 v[56:59], v[144:147], v[190:193], v[56:59]
	v_mfma_f32_16x16x32_bf16 v[52:55], v[136:139], v[198:201], v[52:55]
	v_mfma_f32_16x16x32_bf16 v[48:51], v[144:147], v[198:201], v[48:51]
	v_mfma_f32_16x16x32_bf16 v[36:39], v[136:139], v[214:217], v[36:39]
	v_mfma_f32_16x16x32_bf16 v[32:35], v[144:147], v[214:217], v[32:35]
	v_mfma_f32_16x16x32_bf16 v[20:23], v[136:139], v[222:225], v[20:23]
	v_mfma_f32_16x16x32_bf16 v[16:19], v[144:147], v[222:225], v[16:19]
	v_mfma_f32_16x16x32_bf16 v[60:63], v[140:143], v[194:197], v[60:63]
	v_mfma_f32_16x16x32_bf16 v[56:59], v[148:151], v[194:197], v[56:59]
	v_mfma_f32_16x16x32_bf16 v[52:55], v[140:143], v[202:205], v[52:55]
	v_mfma_f32_16x16x32_bf16 v[48:51], v[148:151], v[202:205], v[48:51]
	v_mfma_f32_16x16x32_bf16 v[36:39], v[140:143], v[218:221], v[36:39]
	v_mfma_f32_16x16x32_bf16 v[32:35], v[148:151], v[218:221], v[32:35]
	v_mfma_f32_16x16x32_bf16 v[20:23], v[140:143], v[226:229], v[20:23]
	v_mfma_f32_16x16x32_bf16 v[16:19], v[148:151], v[226:229], v[16:19]
	v_mfma_f32_16x16x32_bf16 v[44:47], v[152:155], v[190:193], v[44:47]
	v_mfma_f32_16x16x32_bf16 v[40:43], v[160:163], v[190:193], v[40:43]
	v_mfma_f32_16x16x32_bf16 v[28:31], v[152:155], v[198:201], v[28:31]
	v_mfma_f32_16x16x32_bf16 v[24:27], v[160:163], v[198:201], v[24:27]
	v_mfma_f32_16x16x32_bf16 v[12:15], v[152:155], v[214:217], v[12:15]
	v_mfma_f32_16x16x32_bf16 v[8:11], v[160:163], v[214:217], v[8:11]
	v_mfma_f32_16x16x32_bf16 v[4:7], v[152:155], v[222:225], v[4:7]
	v_mfma_f32_16x16x32_bf16 v[0:3], v[160:163], v[222:225], v[0:3]
	v_mfma_f32_16x16x32_bf16 v[44:47], v[156:159], v[194:197], v[44:47]
	v_mfma_f32_16x16x32_bf16 v[40:43], v[186:189], v[194:197], v[40:43]
	v_mfma_f32_16x16x32_bf16 v[28:31], v[156:159], v[202:205], v[28:31]
	v_mfma_f32_16x16x32_bf16 v[24:27], v[186:189], v[202:205], v[24:27]
	v_mfma_f32_16x16x32_bf16 v[12:15], v[156:159], v[218:221], v[12:15]
	v_mfma_f32_16x16x32_bf16 v[8:11], v[186:189], v[218:221], v[8:11]
	v_mfma_f32_16x16x32_bf16 v[4:7], v[156:159], v[226:229], v[4:7]
	v_mfma_f32_16x16x32_bf16 v[0:3], v[186:189], v[226:229], v[0:3]
	s_setprio 0
	s_barrier
	s_movk_i32 s0, 0x100
	s_andn2_b64 vcc, exec, s[62:63]
	s_mov_b64 s[64:65], -1
	s_mov_b64 s[62:63], 0
	s_cbranch_vccz .LBB0_783
	s_and_b64 vcc, exec, s[40:41]
	s_cbranch_vccz .LBB0_786
	s_barrier

; #define PG8_STAGE(bufoff, gbase, voff) do { _Pragma("unroll") for (int _i = 0; _i < 2; ++_i) \
;         __builtin_amdgcn_global_load_lds((const unsigned*)((const char*)(gbase) + (voff)[_i]), (PG8_LAS unsigned*)(lds + (bufoff) + ldsw + _i * 8192), 16, 0, 0); } while (0)
; #define PG8_LDA(dst, b, h) do { _Pragma("unroll") for (int m = 0; m < 4; ++m) _Pragma("unroll") for (int k = 0; k < 2; ++k) dst[m][k] = *(const PG8_LAS bf16x8*)(lds + PG8_SA(b, h) + aoff + m * 2048 + k * 1024); } while (0)
; #define PG8_LDB(dst, b, h) do { _Pragma("unroll") for (int n = 0; n < 2; ++n) _Pragma("unroll") for (int k = 0; k < 2; ++k) dst[n][k] = *(const PG8_LAS bf16x8*)(lds + PG8_SB(b, h) + boff + n * 2048 + k * 1024); } while (0)
; #define PG8_MMA(ai, bj, At, Bt) do { __builtin_amdgcn_s_setprio(1); _Pragma("unroll") for (int m = 0; m < 4; ++m) _Pragma("unroll") for (int n = 0; n < 2; ++n) _Pragma("unroll") for (int k = 0; k < 2; ++k) \
;         acc[ai][bj][m][n] = __builtin_amdgcn_mfma_f32_16x16x32_bf16(Bt[n][k], At[m][k], acc[ai][bj][m][n], 0, 0, 0); __builtin_amdgcn_s_setprio(0); } while (0)
; #define PG8_WAIT_V(n) asm volatile("s_waitcnt vmcnt(" #n ")" ::: "memory")
; #define PG8_WAIT_L(n) asm volatile("s_waitcnt lgkmcnt(" #n ")" ::: "memory")
; template <class Epi, class Sched, bool ALIGN_EPI = false, bool SP2 = false>
; __device__ __forceinline__ void gemm_phase(PG8_LAS unsigned char* lds, const Gemm g, const Sched& S, const Epi& E) {
;     ...
;             const bool last = (t == nt - 2);
;             const char* a1 = cA + (size_t)(t + 1) * kstep;
;             const char* a2 = last ? nA : cA + (size_t)(t + 2) * kstep; const char* b2 = last ? nB : cB + (size_t)(t + 2) * kstep;
;             const char* a3 = a2 + kstep; const char* b3 = b2 + kstep;
;             if (last && has_next) S.a_ready(nxt);
;             if constexpr (SP2) {
;             PG8_LDB(B0, 0, 0); PG8_LDB(B1, 0, 1); PG8_SCHED; PG8_LDA(At, 0, 0); PG8_STAGE(PG8_SA(1, 1), a1 + hstepA, voffA);
;             PG8_WAIT_V(8); PG8_WAIT_L(0); PG8_BAR; PG8_MMA(0, 0, At, B0); PG8_MMA(0, 1, At, B1); PG8_BAR; PG8_SCHED;
;             PG8_LDA(At, 0, 1); PG8_STAGE(PG8_SB(0, 0), b2, voffB); PG8_STAGE(PG8_SB(0, 1), b2 + hstepB, voffB); PG8_STAGE(PG8_SA(0, 0), a2, voffA);
;             PG8_WAIT_V(8); PG8_WAIT_L(0); PG8_BAR; PG8_MMA(1, 0, At, B0); PG8_MMA(1, 1, At, B1); PG8_BAR; PG8_SCHED;
.LBB0_1027:
	s_add_u32 s0, s56, 0xfffc0080
	s_addc_u32 s1, s57, -1
	s_add_i32 s4, 0, 0x10000
	s_cmp_eq_u32 s63, 12
	s_cselect_b32 s1, s16, s1
	s_cselect_b32 s0, s17, s0
	s_cselect_b32 s59, s49, s62
	s_cselect_b32 s58, s51, s61
	s_add_i32 s5, 0, 0x14000
	v_add_u32_e32 v152, s4, v138
	v_add_u32_e32 v186, s5, v138
	ds_read_b128 v[140:143], v152
	ds_read_b128 v[144:147], v152 offset:1024
	ds_read_b128 v[148:151], v152 offset:2048
	ds_read_b128 v[152:155], v152 offset:3072
	ds_read_b128 v[156:159], v186
	ds_read_b128 v[160:163], v186 offset:1024
	ds_read_b128 v[166:169], v186 offset:2048
	ds_read_b128 v[186:189], v186 offset:3072
	v_lshl_add_u64 v[230:231], s[56:57], 0, v[136:137]
	s_add_i32 m0, s43, 0xc000
	ds_read_b128 v[190:193], v139
	ds_read_b128 v[194:197], v139 offset:1024
	ds_read_b128 v[198:201], v139 offset:2048
	ds_read_b128 v[202:205], v139 offset:3072
	ds_read_b128 v[214:217], v139 offset:4096
	ds_read_b128 v[218:221], v139 offset:5120
	ds_read_b128 v[222:225], v139 offset:6144
	ds_read_b128 v[226:229], v139 offset:7168
	global_load_lds_dwordx4 v[230:231], off
	v_lshl_add_u64 v[230:231], s[56:57], 0, v[134:135]
	s_add_i32 m0, s43, 0xe000
	s_nop 0
	global_load_lds_dwordx4 v[230:231], off
	s_waitcnt vmcnt(8)
	s_waitcnt lgkmcnt(0)
	s_barrier
	s_setprio 1
	v_mfma_f32_16x16x32_bf16 v[124:127], v[140:143], v[190:193], v[124:127]
	v_mfma_f32_16x16x32_bf16 v[120:123], v[148:151], v[190:193], v[120:123]
	v_mfma_f32_16x16x32_bf16 v[116:119], v[140:143], v[198:201], v[116:119]
	v_mfma_f32_16x16x32_bf16 v[112:115], v[148:151], v[198:201], v[112:115]
	v_mfma_f32_16x16x32_bf16 v[100:103], v[140:143], v[214:217], v[100:103]
	v_mfma_f32_16x16x32_bf16 v[96:99], v[148:151], v[214:217], v[96:99]
	v_mfma_f32_16x16x32_bf16 v[84:87], v[140:143], v[222:225], v[84:87]
	v_mfma_f32_16x16x32_bf16 v[80:83], v[148:151], v[222:225], v[80:83]
	v_mfma_f32_16x16x32_bf16 v[124:127], v[144:147], v[194:197], v[124:127]
	v_mfma_f32_16x16x32_bf16 v[120:123], v[152:155], v[194:197], v[120:123]
	v_mfma_f32_16x16x32_bf16 v[116:119], v[144:147], v[202:205], v[116:119]
	v_mfma_f32_16x16x32_bf16 v[112:115], v[152:155], v[202:205], v[112:115]
	v_mfma_f32_16x16x32_bf16 v[100:103], v[144:147], v[218:221], v[100:103]
	v_mfma_f32_16x16x32_bf16 v[96:99], v[152:155], v[218:221], v[96:99]
	v_mfma_f32_16x16x32_bf16 v[84:87], v[144:147], v[226:229], v[84:87]
	v_mfma_f32_16x16x32_bf16 v[80:83], v[152:155], v[226:229], v[80:83]
	v_mfma_f32_16x16x32_bf16 v[108:111], v[156:159], v[190:193], v[108:111]
	v_mfma_f32_16x16x32_bf16 v[104:107], v[166:169], v[190:193], v[104:107]
	v_mfma_f32_16x16x32_bf16 v[92:95], v[156:159], v[198:201], v[92:95]
	v_mfma_f32_16x16x32_bf16 v[88:91], v[166:169], v[198:201], v[88:91]
	v_mfma_f32_16x16x32_bf16 v[76:79], v[156:159], v[214:217], v[76:79]
	v_mfma_f32_16x16x32_bf16 v[72:75], v[166:169], v[214:217], v[72:75]
	v_mfma_f32_16x16x32_bf16 v[68:71], v[156:159], v[222:225], v[68:71]
	v_mfma_f32_16x16x32_bf16 v[64:67], v[166:169], v[222:225], v[64:67]
	v_mfma_f32_16x16x32_bf16 v[108:111], v[160:163], v[194:197], v[108:111]
	v_mfma_f32_16x16x32_bf16 v[104:107], v[186:189], v[194:197], v[104:107]
	v_mfma_f32_16x16x32_bf16 v[92:95], v[160:163], v[202:205], v[92:95]
	v_mfma_f32_16x16x32_bf16 v[88:91], v[186:189], v[202:205], v[88:91]
	v_mfma_f32_16x16x32_bf16 v[76:79], v[160:163], v[218:221], v[76:79]
	v_mfma_f32_16x16x32_bf16 v[72:75], v[186:189], v[218:221], v[72:75]
	v_mfma_f32_16x16x32_bf16 v[68:71], v[160:163], v[226:229], v[68:71]
	v_mfma_f32_16x16x32_bf16 v[64:67], v[186:189], v[226:229], v[64:67]
	s_setprio 0
	s_barrier
	s_add_i32 s4, s4, s13
	v_lshl_add_u64 v[230:231], s[58:59], 0, v[164:165]
	s_mov_b32 m0, s4
	ds_read_b128 v[190:193], v139 offset:16384
	ds_read_b128 v[194:197], v139 offset:17408
	ds_read_b128 v[198:201], v139 offset:18432
	ds_read_b128 v[202:205], v139 offset:19456
	ds_read_b128 v[214:217], v139 offset:20480
	ds_read_b128 v[218:221], v139 offset:21504
	ds_read_b128 v[222:225], v139 offset:22528
	ds_read_b128 v[226:229], v139 offset:23552
	global_load_lds_dwordx4 v[230:231], off
	s_add_i32 m0, s4, 0x2000
	s_add_u32 s36, s58, 0x40000
	v_lshl_add_u64 v[232:233], s[58:59], 0, v[132:133]
	s_addc_u32 s37, s59, 0
	s_add_i32 s4, s5, s13
	global_load_lds_dwordx4 v[232:233], off
	v_lshl_add_u64 v[234:235], s[36:37], 0, v[164:165]
	s_mov_b32 m0, s4
	v_lshl_add_u64 v[236:237], s[0:1], 0, v[130:131]
	global_load_lds_dwordx4 v[234:235], off
	v_lshl_add_u64 v[234:235], s[36:37], 0, v[132:133]
	s_add_i32 m0, s4, 0x2000
	s_nop 0
	global_load_lds_dwordx4 v[234:235], off
	v_lshl_add_u64 v[234:235], s[0:1], 0, v[128:129]
	s_mov_b32 m0, s43
	s_nop 0
	global_load_lds_dwordx4 v[234:235], off
	s_mov_b32 m0, s46
	s_nop 0
	global_load_lds_dwordx4 v[236:237], off
	s_waitcnt vmcnt(8)
	s_waitcnt lgkmcnt(0)
	s_barrier
; #define PG8_STAGE(bufoff, gbase, voff) do { _Pragma("unroll") for (int _i = 0; _i < 2; ++_i) \
;         __builtin_amdgcn_global_load_lds((const unsigned*)((const char*)(gbase) + (voff)[_i]), (PG8_LAS unsigned*)(lds + (bufoff) + ldsw + _i * 8192), 16, 0, 0); } while (0)
; #define PG8_LDA(dst, b, h) do { _Pragma("unroll") for (int m = 0; m < 4; ++m) _Pragma("unroll") for (int k = 0; k < 2; ++k) dst[m][k] = *(const PG8_LAS bf16x8*)(lds + PG8_SA(b, h) + aoff + m * 2048 + k * 1024); } while (0)
; #define PG8_LDB(dst, b, h) do { _Pragma("unroll") for (int n = 0; n < 2; ++n) _Pragma("unroll") for (int k = 0; k < 2; ++k) dst[n][k] = *(const PG8_LAS bf16x8*)(lds + PG8_SB(b, h) + boff + n * 2048 + k * 1024); } while (0)
; #define PG8_MMA(ai, bj, At, Bt) do { __builtin_amdgcn_s_setprio(1); _Pragma("unroll") for (int m = 0; m < 4; ++m) _Pragma("unroll") for (int n = 0; n < 2; ++n) _Pragma("unroll") for (int k = 0; k < 2; ++k) \
;         acc[ai][bj][m][n] = __builtin_amdgcn_mfma_f32_16x16x32_bf16(Bt[n][k], At[m][k], acc[ai][bj][m][n], 0, 0, 0); __builtin_amdgcn_s_setprio(0); } while (0)
; #define PG8_WAIT_V(n) asm volatile("s_waitcnt vmcnt(" #n ")" ::: "memory")
; #define PG8_WAIT_L(n) asm volatile("s_waitcnt lgkmcnt(" #n ")" ::: "memory")
; #define PG8_BAR __builtin_amdgcn_s_barrier()
; #define PG8_SCHED __builtin_amdgcn_sched_barrier(0)
; template <class Epi, class Sched, bool ALIGN_EPI = false, bool SP2 = false>
; __device__ __forceinline__ void gemm_phase(PG8_LAS unsigned char* lds, const Gemm g, const Sched& S, const Epi& E) {
;     ...
;             PG8_WAIT_V(8); PG8_WAIT_L(0); PG8_BAR; PG8_MMA(1, 0, At, B0); PG8_MMA(1, 1, At, B1); PG8_BAR; PG8_SCHED;
;             PG8_LDB(B0, 1, 0); PG8_LDB(B1, 1, 1); PG8_SCHED; PG8_LDA(At, 1, 0); PG8_STAGE(PG8_SA(0, 1), a2 + hstepA, voffA);
;             PG8_WAIT_V(8); PG8_WAIT_L(0); PG8_BAR; PG8_MMA(0, 0, At, B0); PG8_MMA(0, 1, At, B1); PG8_BAR; PG8_SCHED;
	s_setprio 1
	v_mfma_f32_16x16x32_bf16 v[60:63], v[140:143], v[190:193], v[60:63]
	v_mfma_f32_16x16x32_bf16 v[56:59], v[148:151], v[190:193], v[56:59]
	v_mfma_f32_16x16x32_bf16 v[52:55], v[140:143], v[198:201], v[52:55]
	v_mfma_f32_16x16x32_bf16 v[48:51], v[148:151], v[198:201], v[48:51]
	v_mfma_f32_16x16x32_bf16 v[36:39], v[140:143], v[214:217], v[36:39]
	v_mfma_f32_16x16x32_bf16 v[32:35], v[148:151], v[214:217], v[32:35]
	v_mfma_f32_16x16x32_bf16 v[20:23], v[140:143], v[222:225], v[20:23]
	v_mfma_f32_16x16x32_bf16 v[16:19], v[148:151], v[222:225], v[16:19]
	v_mfma_f32_16x16x32_bf16 v[60:63], v[144:147], v[194:197], v[60:63]
	v_mfma_f32_16x16x32_bf16 v[56:59], v[152:155], v[194:197], v[56:59]
	v_mfma_f32_16x16x32_bf16 v[52:55], v[144:147], v[202:205], v[52:55]
	v_mfma_f32_16x16x32_bf16 v[48:51], v[152:155], v[202:205], v[48:51]
	v_mfma_f32_16x16x32_bf16 v[36:39], v[144:147], v[218:221], v[36:39]
	v_mfma_f32_16x16x32_bf16 v[32:35], v[152:155], v[218:221], v[32:35]
	v_mfma_f32_16x16x32_bf16 v[20:23], v[144:147], v[226:229], v[20:23]
	v_mfma_f32_16x16x32_bf16 v[16:19], v[152:155], v[226:229], v[16:19]
	v_mfma_f32_16x16x32_bf16 v[44:47], v[156:159], v[190:193], v[44:47]
	v_mfma_f32_16x16x32_bf16 v[40:43], v[166:169], v[190:193], v[40:43]
	v_mfma_f32_16x16x32_bf16 v[28:31], v[156:159], v[198:201], v[28:31]
	v_mfma_f32_16x16x32_bf16 v[24:27], v[166:169], v[198:201], v[24:27]
	v_mfma_f32_16x16x32_bf16 v[12:15], v[156:159], v[214:217], v[12:15]
	v_mfma_f32_16x16x32_bf16 v[8:11], v[166:169], v[214:217], v[8:11]
	v_mfma_f32_16x16x32_bf16 v[4:7], v[156:159], v[222:225], v[4:7]
	v_mfma_f32_16x16x32_bf16 v[0:3], v[166:169], v[222:225], v[0:3]
	v_mfma_f32_16x16x32_bf16 v[44:47], v[160:163], v[194:197], v[44:47]
	v_mfma_f32_16x16x32_bf16 v[40:43], v[186:189], v[194:197], v[40:43]
	v_mfma_f32_16x16x32_bf16 v[28:31], v[160:163], v[202:205], v[28:31]
	v_mfma_f32_16x16x32_bf16 v[24:27], v[186:189], v[202:205], v[24:27]
	v_mfma_f32_16x16x32_bf16 v[12:15], v[160:163], v[218:221], v[12:15]
	v_mfma_f32_16x16x32_bf16 v[8:11], v[186:189], v[218:221], v[8:11]
	v_mfma_f32_16x16x32_bf16 v[4:7], v[160:163], v[226:229], v[4:7]
	v_mfma_f32_16x16x32_bf16 v[0:3], v[186:189], v[226:229], v[0:3]
	s_setprio 0
	s_barrier
	s_add_i32 s4, 0, 0x18000
	s_add_i32 s5, 0, 0x1c000
	v_add_u32_e32 v152, s4, v138
	v_add_u32_e32 v186, s5, v138
	ds_read_b128 v[140:143], v152
	ds_read_b128 v[144:147], v152 offset:1024
	ds_read_b128 v[148:151], v152 offset:2048
	ds_read_b128 v[152:155], v152 offset:3072
	ds_read_b128 v[156:159], v186
	ds_read_b128 v[160:163], v186 offset:1024
	ds_read_b128 v[166:169], v186 offset:2048
	ds_read_b128 v[186:189], v186 offset:3072
	s_add_u32 s0, s0, 0x40000
	s_addc_u32 s1, s1, 0
	s_mov_b32 m0, s47
	v_lshl_add_u64 v[238:239], s[0:1], 0, v[128:129]
	ds_read_b128 v[190:193], v139 offset:32768
	ds_read_b128 v[194:197], v139 offset:33792
	ds_read_b128 v[198:201], v139 offset:34816
	ds_read_b128 v[202:205], v139 offset:35840
	ds_read_b128 v[214:217], v139 offset:36864
	ds_read_b128 v[218:221], v139 offset:37888
	ds_read_b128 v[222:225], v139 offset:38912
	ds_read_b128 v[226:229], v139 offset:39936
	global_load_lds_dwordx4 v[238:239], off
	v_lshl_add_u64 v[238:239], s[0:1], 0, v[130:131]
	s_mov_b32 m0, s60
	s_nop 0
	global_load_lds_dwordx4 v[238:239], off
	s_waitcnt vmcnt(8)
	s_waitcnt lgkmcnt(0)
	s_barrier
	s_setprio 1
	v_mfma_f32_16x16x32_bf16 v[124:127], v[140:143], v[190:193], v[124:127]
	v_mfma_f32_16x16x32_bf16 v[120:123], v[148:151], v[190:193], v[120:123]
	v_mfma_f32_16x16x32_bf16 v[116:119], v[140:143], v[198:201], v[116:119]
	v_mfma_f32_16x16x32_bf16 v[112:115], v[148:151], v[198:201], v[112:115]
	v_mfma_f32_16x16x32_bf16 v[100:103], v[140:143], v[214:217], v[100:103]
	v_mfma_f32_16x16x32_bf16 v[96:99], v[148:151], v[214:217], v[96:99]
	v_mfma_f32_16x16x32_bf16 v[84:87], v[140:143], v[222:225], v[84:87]
	v_mfma_f32_16x16x32_bf16 v[80:83], v[148:151], v[222:225], v[80:83]
	v_mfma_f32_16x16x32_bf16 v[124:127], v[144:147], v[194:197], v[124:127]
	v_mfma_f32_16x16x32_bf16 v[120:123], v[152:155], v[194:197], v[120:123]
	v_mfma_f32_16x16x32_bf16 v[116:119], v[144:147], v[202:205], v[116:119]
	v_mfma_f32_16x16x32_bf16 v[112:115], v[152:155], v[202:205], v[112:115]
	v_mfma_f32_16x16x32_bf16 v[100:103], v[144:147], v[218:221], v[100:103]
	v_mfma_f32_16x16x32_bf16 v[96:99], v[152:155], v[218:221], v[96:99]
	v_mfma_f32_16x16x32_bf16 v[84:87], v[144:147], v[226:229], v[84:87]
	v_mfma_f32_16x16x32_bf16 v[80:83], v[152:155], v[226:229], v[80:83]
	v_mfma_f32_16x16x32_bf16 v[108:111], v[156:159], v[190:193], v[108:111]
	v_mfma_f32_16x16x32_bf16 v[104:107], v[166:169], v[190:193], v[104:107]
	v_mfma_f32_16x16x32_bf16 v[92:95], v[156:159], v[198:201], v[92:95]
	v_mfma_f32_16x16x32_bf16 v[88:91], v[166:169], v[198:201], v[88:91]
	v_mfma_f32_16x16x32_bf16 v[76:79], v[156:159], v[214:217], v[76:79]
	v_mfma_f32_16x16x32_bf16 v[72:75], v[166:169], v[214:217], v[72:75]
	v_mfma_f32_16x16x32_bf16 v[68:71], v[156:159], v[222:225], v[68:71]
	v_mfma_f32_16x16x32_bf16 v[64:67], v[166:169], v[222:225], v[64:67]
	v_mfma_f32_16x16x32_bf16 v[108:111], v[160:163], v[194:197], v[108:111]
	v_mfma_f32_16x16x32_bf16 v[104:107], v[186:189], v[194:197], v[104:107]
	v_mfma_f32_16x16x32_bf16 v[92:95], v[160:163], v[202:205], v[92:95]
	v_mfma_f32_16x16x32_bf16 v[88:91], v[186:189], v[202:205], v[88:91]
	v_mfma_f32_16x16x32_bf16 v[76:79], v[160:163], v[218:221], v[76:79]
	v_mfma_f32_16x16x32_bf16 v[72:75], v[186:189], v[218:221], v[72:75]
	v_mfma_f32_16x16x32_bf16 v[68:71], v[160:163], v[226:229], v[68:71]
	v_mfma_f32_16x16x32_bf16 v[64:67], v[186:189], v[226:229], v[64:67]
	s_setprio 0
	s_barrier
; #define PG8_STAGE(bufoff, gbase, voff) do { _Pragma("unroll") for (int _i = 0; _i < 2; ++_i) \
;         __builtin_amdgcn_global_load_lds((const unsigned*)((const char*)(gbase) + (voff)[_i]), (PG8_LAS unsigned*)(lds + (bufoff) + ldsw + _i * 8192), 16, 0, 0); } while (0)
; #define PG8_LDA(dst, b, h) do { _Pragma("unroll") for (int m = 0; m < 4; ++m) _Pragma("unroll") for (int k = 0; k < 2; ++k) dst[m][k] = *(const PG8_LAS bf16x8*)(lds + PG8_SA(b, h) + aoff + m * 2048 + k * 1024); } while (0)
; #define PG8_WAIT_V(n) asm volatile("s_waitcnt vmcnt(" #n ")" ::: "memory")
; template <class Epi, class Sched, bool ALIGN_EPI = false, bool SP2 = false>
; __device__ __forceinline__ void gemm_phase(PG8_LAS unsigned char* lds, const Gemm g, const Sched& S, const Epi& E) {
;     ...
;             PG8_LDA(At, 1, 1); PG8_STAGE(PG8_SB(1, 0), b3, voffB); PG8_STAGE(PG8_SB(1, 1), b3 + hstepB, voffB); PG8_STAGE(PG8_SA(1, 0), a3, voffA);
;             PG8_WAIT_V(8); PG8_WAIT_L(0); PG8_BAR; PG8_MMA(1, 0, At, B0); PG8_MMA(1, 1, At, B1); PG8_BAR; PG8_SCHED;
;             } else {
;             PG8_LDB(B0, 0, 0); PG8_SCHED; PG8_LDA(At, 0, 0); PG8_STAGE(PG8_SA(1, 1), a1 + hstepA, voffA);
;             PG8_WAIT_L(8); PG8_BAR; PG8_WAIT_L(0); PG8_MMA(0, 0, At, B0); PG8_BAR; PG8_SCHED;
;             PG8_LDB(B1, 0, 1); PG8_STAGE(PG8_SB(0, 0), b2, voffB);
;             PG8_BAR; PG8_WAIT_L(0); PG8_MMA(0, 1, At, B1); PG8_BAR;
;             PG8_LDA(At, 0, 1); PG8_STAGE(PG8_SA(0, 0), a2, voffA);
;             PG8_BAR; PG8_WAIT_L(0); PG8_MMA(1, 0, At, B0); PG8_BAR; PG8_SCHED;
;             PG8_STAGE(PG8_SB(0, 1), b2 + hstepB, voffB);
;             PG8_WAIT_V(6); PG8_BAR; PG8_MMA(1, 1, At, B1); PG8_BAR;
;             PG8_LDB(B0, 1, 0); PG8_SCHED; PG8_LDA(At, 1, 0); PG8_STAGE(PG8_SA(0, 1), a2 + hstepA, voffA);
;             PG8_WAIT_L(8); PG8_BAR; PG8_WAIT_L(0); PG8_MMA(0, 0, At, B0); PG8_BAR; PG8_SCHED;
;             PG8_LDB(B1, 1, 1); PG8_STAGE(PG8_SB(1, 0), b3, voffB);
;             PG8_BAR; PG8_WAIT_L(0); PG8_MMA(0, 1, At, B1); PG8_BAR;
;             PG8_LDA(At, 1, 1); PG8_STAGE(PG8_SA(1, 0), a3, voffA);
;             PG8_BAR; PG8_WAIT_L(0); PG8_MMA(1, 0, At, B0); PG8_BAR; PG8_SCHED;
;             PG8_STAGE(PG8_SB(1, 1), b3 + hstepB, voffB);
;             PG8_WAIT_V(6); PG8_BAR; PG8_MMA(1, 1, At, B1); PG8_BAR;
;             }
;         }
;         if constexpr (ALIGN_EPI) { if (wr == 0) PG8_BAR; }
	s_add_i32 s0, s4, s13
	v_lshl_add_u64 v[230:231], v[230:231], 0, s[14:15]
	s_mov_b32 m0, s0
	ds_read_b128 v[190:193], v139 offset:49152
	ds_read_b128 v[194:197], v139 offset:50176
	ds_read_b128 v[198:201], v139 offset:51200
	ds_read_b128 v[202:205], v139 offset:52224
	ds_read_b128 v[214:217], v139 offset:53248
	ds_read_b128 v[218:221], v139 offset:54272
	ds_read_b128 v[222:225], v139 offset:55296
	ds_read_b128 v[226:229], v139 offset:56320
	global_load_lds_dwordx4 v[230:231], off
	s_add_i32 m0, s0, 0x2000
	s_add_u32 s0, s58, 0x40080
	v_lshl_add_u64 v[230:231], v[232:233], 0, s[14:15]
	s_addc_u32 s1, s59, 0
	s_add_i32 s4, s5, s13
	global_load_lds_dwordx4 v[230:231], off
	v_lshl_add_u64 v[230:231], s[0:1], 0, v[164:165]
	s_mov_b32 m0, s4
	s_nop 0
	global_load_lds_dwordx4 v[230:231], off
	v_lshl_add_u64 v[230:231], s[0:1], 0, v[132:133]
	s_add_i32 m0, s4, 0x2000
	s_nop 0
	global_load_lds_dwordx4 v[230:231], off
	v_lshl_add_u64 v[230:231], v[234:235], 0, s[14:15]
	s_mov_b32 m0, s9
	s_nop 0
	global_load_lds_dwordx4 v[230:231], off
	v_lshl_add_u64 v[230:231], v[236:237], 0, s[14:15]
	s_mov_b32 m0, s25
	s_nop 0
	global_load_lds_dwordx4 v[230:231], off
	s_waitcnt vmcnt(8)
	s_waitcnt lgkmcnt(0)
	s_barrier
	s_setprio 1
	v_mfma_f32_16x16x32_bf16 v[60:63], v[140:143], v[190:193], v[60:63]
	v_mfma_f32_16x16x32_bf16 v[56:59], v[148:151], v[190:193], v[56:59]
	v_mfma_f32_16x16x32_bf16 v[52:55], v[140:143], v[198:201], v[52:55]
	v_mfma_f32_16x16x32_bf16 v[48:51], v[148:151], v[198:201], v[48:51]
	v_mfma_f32_16x16x32_bf16 v[36:39], v[140:143], v[214:217], v[36:39]
	v_mfma_f32_16x16x32_bf16 v[32:35], v[148:151], v[214:217], v[32:35]
	v_mfma_f32_16x16x32_bf16 v[20:23], v[140:143], v[222:225], v[20:23]
	v_mfma_f32_16x16x32_bf16 v[16:19], v[148:151], v[222:225], v[16:19]
	v_mfma_f32_16x16x32_bf16 v[60:63], v[144:147], v[194:197], v[60:63]
	v_mfma_f32_16x16x32_bf16 v[56:59], v[152:155], v[194:197], v[56:59]
	v_mfma_f32_16x16x32_bf16 v[52:55], v[144:147], v[202:205], v[52:55]
	v_mfma_f32_16x16x32_bf16 v[48:51], v[152:155], v[202:205], v[48:51]
	v_mfma_f32_16x16x32_bf16 v[36:39], v[144:147], v[218:221], v[36:39]
	v_mfma_f32_16x16x32_bf16 v[32:35], v[152:155], v[218:221], v[32:35]
	v_mfma_f32_16x16x32_bf16 v[20:23], v[144:147], v[226:229], v[20:23]
	v_mfma_f32_16x16x32_bf16 v[16:19], v[152:155], v[226:229], v[16:19]
	v_mfma_f32_16x16x32_bf16 v[44:47], v[156:159], v[190:193], v[44:47]
	v_mfma_f32_16x16x32_bf16 v[40:43], v[166:169], v[190:193], v[40:43]
	v_mfma_f32_16x16x32_bf16 v[28:31], v[156:159], v[198:201], v[28:31]
	v_mfma_f32_16x16x32_bf16 v[24:27], v[166:169], v[198:201], v[24:27]
	v_mfma_f32_16x16x32_bf16 v[12:15], v[156:159], v[214:217], v[12:15]
	v_mfma_f32_16x16x32_bf16 v[8:11], v[166:169], v[214:217], v[8:11]
	v_mfma_f32_16x16x32_bf16 v[4:7], v[156:159], v[222:225], v[4:7]
	v_mfma_f32_16x16x32_bf16 v[0:3], v[166:169], v[222:225], v[0:3]
	v_mfma_f32_16x16x32_bf16 v[44:47], v[160:163], v[194:197], v[44:47]
	v_mfma_f32_16x16x32_bf16 v[40:43], v[186:189], v[194:197], v[40:43]
	v_mfma_f32_16x16x32_bf16 v[28:31], v[160:163], v[202:205], v[28:31]
	v_mfma_f32_16x16x32_bf16 v[24:27], v[186:189], v[202:205], v[24:27]
	v_mfma_f32_16x16x32_bf16 v[12:15], v[160:163], v[218:221], v[12:15]
	v_mfma_f32_16x16x32_bf16 v[8:11], v[186:189], v[218:221], v[8:11]
	v_mfma_f32_16x16x32_bf16 v[4:7], v[160:163], v[226:229], v[4:7]
	v_mfma_f32_16x16x32_bf16 v[0:3], v[186:189], v[226:229], v[0:3]
	s_setprio 0
	s_barrier
	s_add_i32 s63, s63, 2
	s_add_u32 s61, s61, 0x100
	s_addc_u32 s62, s62, 0
	s_add_u32 s56, s56, 0x100
	s_addc_u32 s57, s57, 0
	s_cmp_gt_u32 s63, 13
	s_cbranch_scc0 .LBB0_1027
	s_and_b64 vcc, exec, s[40:41]
	s_cbranch_vccz .LBB0_1030
	s_barrier

; #define PG8_STAGE(bufoff, gbase, voff) do { _Pragma("unroll") for (int _i = 0; _i < 2; ++_i) \
;         __builtin_amdgcn_global_load_lds((const unsigned*)((const char*)(gbase) + (voff)[_i]), (PG8_LAS unsigned*)(lds + (bufoff) + ldsw + _i * 8192), 16, 0, 0); } while (0)
; #define PG8_LDA(dst, b, h) do { _Pragma("unroll") for (int m = 0; m < 4; ++m) _Pragma("unroll") for (int k = 0; k < 2; ++k) dst[m][k] = *(const PG8_LAS bf16x8*)(lds + PG8_SA(b, h) + aoff + m * 2048 + k * 1024); } while (0)
; #define PG8_LDB(dst, b, h) do { _Pragma("unroll") for (int n = 0; n < 2; ++n) _Pragma("unroll") for (int k = 0; k < 2; ++k) dst[n][k] = *(const PG8_LAS bf16x8*)(lds + PG8_SB(b, h) + boff + n * 2048 + k * 1024); } while (0)
; #define PG8_WAIT_V(n) asm volatile("s_waitcnt vmcnt(" #n ")" ::: "memory")
; #define PG8_WAIT_L(n) asm volatile("s_waitcnt lgkmcnt(" #n ")" ::: "memory")
; #define PG8_BAR __builtin_amdgcn_s_barrier()
; #define PG8_SCHED __builtin_amdgcn_sched_barrier(0)
; template <class Epi, class Sched, bool ALIGN_EPI = false, bool SP2 = false>
; __device__ __forceinline__ void gemm_phase(PG8_LAS unsigned char* lds, const Gemm g, const Sched& S, const Epi& E) {
;     ...
;         const char* nA = has_next ? (const char*)g.A + (size_t)nxt.pm * tstepA + (size_t)nxt.ks * ksl : cA; const char* nB = has_next ? (const char*)g.Bt + (size_t)nxt.pn * tstepB + (size_t)nxt.ks * ksl : cB;
;         for (int t = 0; t < nt; t += 2) {
;             const bool last = (t == nt - 2);
;             const char* a1 = cA + (size_t)(t + 1) * kstep;
;             const char* a2 = last ? nA : cA + (size_t)(t + 2) * kstep; const char* b2 = last ? nB : cB + (size_t)(t + 2) * kstep;
;             const char* a3 = a2 + kstep; const char* b3 = b2 + kstep;
;             if (last && has_next) S.a_ready(nxt);
;             if constexpr (SP2) {
;             PG8_LDB(B0, 0, 0); PG8_LDB(B1, 0, 1); PG8_SCHED; PG8_LDA(At, 0, 0); PG8_STAGE(PG8_SA(1, 1), a1 + hstepA, voffA);
;             PG8_WAIT_V(8); PG8_WAIT_L(0); PG8_BAR; PG8_MMA(0, 0, At, B0); PG8_MMA(0, 1, At, B1); PG8_BAR; PG8_SCHED;
;             PG8_LDA(At, 0, 1); PG8_STAGE(PG8_SB(0, 0), b2, voffB); PG8_STAGE(PG8_SB(0, 1), b2 + hstepB, voffB); PG8_STAGE(PG8_SA(0, 0), a2, voffA);
;             PG8_WAIT_V(8); PG8_WAIT_L(0); PG8_BAR; PG8_MMA(1, 0, At, B0); PG8_MMA(1, 1, At, B1); PG8_BAR; PG8_SCHED;
.LBB0_1047:
	s_add_u32 s4, s56, s0
	s_addc_u32 s5, s57, 0
	s_add_u32 s1, s4, 0x100
	s_addc_u32 s16, s5, 0
	s_and_b64 s[2:3], s[64:65], exec
	s_cselect_b32 s69, s59, s16
	s_cselect_b32 s68, s58, s1
	s_add_u32 s0, s48, s0
	s_addc_u32 s1, s49, 0
	s_add_u32 s2, s0, 0x100
	s_addc_u32 s3, s1, 0
	s_add_i32 s44, 0, 0x10000
	s_and_b64 s[0:1], s[64:65], exec
	s_cselect_b32 s71, s61, s3
	s_cselect_b32 s70, s60, s2
	s_add_i32 s45, 0, 0x14000
	s_add_u32 s0, s4, 0x40080
	s_addc_u32 s1, s5, 0
	s_add_i32 s41, s44, s10
	s_add_i32 m0, s13, 0xc000
	s_add_i32 s4, s13, 0xe000
	s_add_i32 s33, s41, 0x2000
	s_add_u32 s72, s70, 0x40000
	v_add_u32_e32 v146, s44, v132
	v_add_u32_e32 v162, s45, v132
	s_addc_u32 s73, s71, 0
	s_add_i32 s37, s45, s10
	ds_read_b128 v[134:137], v146
	ds_read_b128 v[138:141], v146 offset:1024
	ds_read_b128 v[142:145], v146 offset:2048
	ds_read_b128 v[146:149], v146 offset:3072
	ds_read_b128 v[150:153], v162
	ds_read_b128 v[154:157], v162 offset:1024
	ds_read_b128 v[158:161], v162 offset:2048
	ds_read_b128 v[166:169], v162 offset:3072
	s_add_i32 s36, s37, 0x2000
	s_add_i32 s17, 0, 0x18000
	s_add_i32 s16, 0, 0x1c000
	s_add_u32 s66, s68, 0x40000
	s_addc_u32 s67, s69, 0
	s_add_i32 s3, s17, s10
	s_add_i32 s2, s3, 0x2000
	s_add_u32 s64, s70, 0x40080
	s_addc_u32 s65, s71, 0
	s_add_i32 s45, s16, s10
	s_add_i32 s44, s45, 0x2000
	v_lshl_add_u64 v[162:163], s[0:1], 0, v[130:131]
	ds_read_b128 v[186:189], v133
	ds_read_b128 v[190:193], v133 offset:1024
	ds_read_b128 v[194:197], v133 offset:2048
	ds_read_b128 v[198:201], v133 offset:3072
	ds_read_b128 v[202:205], v133 offset:4096
	ds_read_b128 v[214:217], v133 offset:5120
	ds_read_b128 v[218:221], v133 offset:6144
	ds_read_b128 v[222:225], v133 offset:7168
	global_load_lds_dwordx4 v[162:163], off
	v_lshl_add_u64 v[162:163], s[0:1], 0, v[128:129]
	s_mov_b32 m0, s4
	s_nop 0
	global_load_lds_dwordx4 v[162:163], off
	s_waitcnt vmcnt(8)
	s_waitcnt lgkmcnt(0)
	s_barrier
	s_setprio 1
	v_mfma_f32_16x16x32_bf16 v[124:127], v[134:137], v[186:189], v[124:127]
	v_mfma_f32_16x16x32_bf16 v[120:123], v[142:145], v[186:189], v[120:123]
	v_mfma_f32_16x16x32_bf16 v[116:119], v[134:137], v[194:197], v[116:119]
	v_mfma_f32_16x16x32_bf16 v[112:115], v[142:145], v[194:197], v[112:115]
	v_mfma_f32_16x16x32_bf16 v[108:111], v[134:137], v[202:205], v[108:111]
	v_mfma_f32_16x16x32_bf16 v[100:103], v[142:145], v[202:205], v[100:103]
	v_mfma_f32_16x16x32_bf16 v[92:95], v[134:137], v[218:221], v[92:95]
	v_mfma_f32_16x16x32_bf16 v[84:87], v[142:145], v[218:221], v[84:87]
	v_mfma_f32_16x16x32_bf16 v[124:127], v[138:141], v[190:193], v[124:127]
	v_mfma_f32_16x16x32_bf16 v[120:123], v[146:149], v[190:193], v[120:123]
	v_mfma_f32_16x16x32_bf16 v[116:119], v[138:141], v[198:201], v[116:119]
	v_mfma_f32_16x16x32_bf16 v[112:115], v[146:149], v[198:201], v[112:115]
	v_mfma_f32_16x16x32_bf16 v[108:111], v[138:141], v[214:217], v[108:111]
	v_mfma_f32_16x16x32_bf16 v[100:103], v[146:149], v[214:217], v[100:103]
	v_mfma_f32_16x16x32_bf16 v[92:95], v[138:141], v[222:225], v[92:95]
	v_mfma_f32_16x16x32_bf16 v[84:87], v[146:149], v[222:225], v[84:87]
	v_mfma_f32_16x16x32_bf16 v[104:107], v[150:153], v[186:189], v[104:107]
	v_mfma_f32_16x16x32_bf16 v[96:99], v[158:161], v[186:189], v[96:99]
	v_mfma_f32_16x16x32_bf16 v[88:91], v[150:153], v[194:197], v[88:91]
	v_mfma_f32_16x16x32_bf16 v[80:83], v[158:161], v[194:197], v[80:83]
	v_mfma_f32_16x16x32_bf16 v[76:79], v[150:153], v[202:205], v[76:79]
	v_mfma_f32_16x16x32_bf16 v[72:75], v[158:161], v[202:205], v[72:75]
	v_mfma_f32_16x16x32_bf16 v[68:71], v[150:153], v[218:221], v[68:71]
	v_mfma_f32_16x16x32_bf16 v[64:67], v[158:161], v[218:221], v[64:67]
	v_mfma_f32_16x16x32_bf16 v[104:107], v[154:157], v[190:193], v[104:107]
	v_mfma_f32_16x16x32_bf16 v[96:99], v[166:169], v[190:193], v[96:99]
	v_mfma_f32_16x16x32_bf16 v[88:91], v[154:157], v[198:201], v[88:91]
	v_mfma_f32_16x16x32_bf16 v[80:83], v[166:169], v[198:201], v[80:83]
	v_mfma_f32_16x16x32_bf16 v[76:79], v[154:157], v[214:217], v[76:79]
	v_mfma_f32_16x16x32_bf16 v[72:75], v[166:169], v[214:217], v[72:75]
	v_mfma_f32_16x16x32_bf16 v[68:71], v[154:157], v[222:225], v[68:71]
	v_mfma_f32_16x16x32_bf16 v[64:67], v[166:169], v[222:225], v[64:67]
	s_setprio 0
	s_barrier
	s_mov_b32 m0, s41
	v_lshl_add_u64 v[162:163], s[70:71], 0, v[130:131]
	ds_read_b128 v[186:189], v133 offset:16384
	ds_read_b128 v[190:193], v133 offset:17408
	ds_read_b128 v[194:197], v133 offset:18432
	ds_read_b128 v[198:201], v133 offset:19456
	ds_read_b128 v[202:205], v133 offset:20480
	ds_read_b128 v[214:217], v133 offset:21504
	ds_read_b128 v[218:221], v133 offset:22528
	ds_read_b128 v[222:225], v133 offset:23552
	global_load_lds_dwordx4 v[162:163], off
	v_lshl_add_u64 v[226:227], s[70:71], 0, v[128:129]
	s_mov_b32 m0, s33
	v_lshl_add_u64 v[228:229], s[72:73], 0, v[130:131]
	global_load_lds_dwordx4 v[226:227], off
	s_mov_b32 m0, s37
	v_lshl_add_u64 v[230:231], s[68:69], 0, v[128:129]
	global_load_lds_dwordx4 v[228:229], off
	v_lshl_add_u64 v[228:229], s[72:73], 0, v[128:129]
	s_mov_b32 m0, s36
	s_nop 0
	global_load_lds_dwordx4 v[228:229], off
	v_lshl_add_u64 v[228:229], s[68:69], 0, v[130:131]
	s_mov_b32 m0, s13
	s_nop 0
	global_load_lds_dwordx4 v[228:229], off
	s_mov_b32 m0, s18
	s_nop 0
	global_load_lds_dwordx4 v[230:231], off
	s_waitcnt vmcnt(8)
	s_waitcnt lgkmcnt(0)
	s_barrier
; #define PG8_STAGE(bufoff, gbase, voff) do { _Pragma("unroll") for (int _i = 0; _i < 2; ++_i) \
;         __builtin_amdgcn_global_load_lds((const unsigned*)((const char*)(gbase) + (voff)[_i]), (PG8_LAS unsigned*)(lds + (bufoff) + ldsw + _i * 8192), 16, 0, 0); } while (0)
; #define PG8_LDA(dst, b, h) do { _Pragma("unroll") for (int m = 0; m < 4; ++m) _Pragma("unroll") for (int k = 0; k < 2; ++k) dst[m][k] = *(const PG8_LAS bf16x8*)(lds + PG8_SA(b, h) + aoff + m * 2048 + k * 1024); } while (0)
; #define PG8_LDB(dst, b, h) do { _Pragma("unroll") for (int n = 0; n < 2; ++n) _Pragma("unroll") for (int k = 0; k < 2; ++k) dst[n][k] = *(const PG8_LAS bf16x8*)(lds + PG8_SB(b, h) + boff + n * 2048 + k * 1024); } while (0)
; #define PG8_MMA(ai, bj, At, Bt) do { __builtin_amdgcn_s_setprio(1); _Pragma("unroll") for (int m = 0; m < 4; ++m) _Pragma("unroll") for (int n = 0; n < 2; ++n) _Pragma("unroll") for (int k = 0; k < 2; ++k) \
;         acc[ai][bj][m][n] = __builtin_amdgcn_mfma_f32_16x16x32_bf16(Bt[n][k], At[m][k], acc[ai][bj][m][n], 0, 0, 0); __builtin_amdgcn_s_setprio(0); } while (0)
; #define PG8_WAIT_V(n) asm volatile("s_waitcnt vmcnt(" #n ")" ::: "memory")
; #define PG8_WAIT_L(n) asm volatile("s_waitcnt lgkmcnt(" #n ")" ::: "memory")
; #define PG8_BAR __builtin_amdgcn_s_barrier()
; #define PG8_SCHED __builtin_amdgcn_sched_barrier(0)
; template <class Epi, class Sched, bool ALIGN_EPI = false, bool SP2 = false>
; __device__ __forceinline__ void gemm_phase(PG8_LAS unsigned char* lds, const Gemm g, const Sched& S, const Epi& E) {
;     ...
;             PG8_WAIT_V(8); PG8_WAIT_L(0); PG8_BAR; PG8_MMA(1, 0, At, B0); PG8_MMA(1, 1, At, B1); PG8_BAR; PG8_SCHED;
;             PG8_LDB(B0, 1, 0); PG8_LDB(B1, 1, 1); PG8_SCHED; PG8_LDA(At, 1, 0); PG8_STAGE(PG8_SA(0, 1), a2 + hstepA, voffA);
;             PG8_WAIT_V(8); PG8_WAIT_L(0); PG8_BAR; PG8_MMA(0, 0, At, B0); PG8_MMA(0, 1, At, B1); PG8_BAR; PG8_SCHED;
	s_setprio 1
	v_mfma_f32_16x16x32_bf16 v[60:63], v[134:137], v[186:189], v[60:63]
	v_mfma_f32_16x16x32_bf16 v[56:59], v[142:145], v[186:189], v[56:59]
	v_mfma_f32_16x16x32_bf16 v[52:55], v[134:137], v[194:197], v[52:55]
	v_mfma_f32_16x16x32_bf16 v[48:51], v[142:145], v[194:197], v[48:51]
	v_mfma_f32_16x16x32_bf16 v[40:43], v[134:137], v[202:205], v[40:43]
	v_mfma_f32_16x16x32_bf16 v[32:35], v[142:145], v[202:205], v[32:35]
	v_mfma_f32_16x16x32_bf16 v[24:27], v[134:137], v[218:221], v[24:27]
	v_mfma_f32_16x16x32_bf16 v[16:19], v[142:145], v[218:221], v[16:19]
	v_mfma_f32_16x16x32_bf16 v[60:63], v[138:141], v[190:193], v[60:63]
	v_mfma_f32_16x16x32_bf16 v[56:59], v[146:149], v[190:193], v[56:59]
	v_mfma_f32_16x16x32_bf16 v[52:55], v[138:141], v[198:201], v[52:55]
	v_mfma_f32_16x16x32_bf16 v[48:51], v[146:149], v[198:201], v[48:51]
	v_mfma_f32_16x16x32_bf16 v[40:43], v[138:141], v[214:217], v[40:43]
	v_mfma_f32_16x16x32_bf16 v[32:35], v[146:149], v[214:217], v[32:35]
	v_mfma_f32_16x16x32_bf16 v[24:27], v[138:141], v[222:225], v[24:27]
	v_mfma_f32_16x16x32_bf16 v[16:19], v[146:149], v[222:225], v[16:19]
	v_mfma_f32_16x16x32_bf16 v[44:47], v[150:153], v[186:189], v[44:47]
	v_mfma_f32_16x16x32_bf16 v[36:39], v[158:161], v[186:189], v[36:39]
	v_mfma_f32_16x16x32_bf16 v[28:31], v[150:153], v[194:197], v[28:31]
	v_mfma_f32_16x16x32_bf16 v[20:23], v[158:161], v[194:197], v[20:23]
	v_mfma_f32_16x16x32_bf16 v[12:15], v[150:153], v[202:205], v[12:15]
	v_mfma_f32_16x16x32_bf16 v[8:11], v[158:161], v[202:205], v[8:11]
	v_mfma_f32_16x16x32_bf16 v[4:7], v[150:153], v[218:221], v[4:7]
	v_mfma_f32_16x16x32_bf16 v[0:3], v[158:161], v[218:221], v[0:3]
	v_mfma_f32_16x16x32_bf16 v[44:47], v[154:157], v[190:193], v[44:47]
	v_mfma_f32_16x16x32_bf16 v[36:39], v[166:169], v[190:193], v[36:39]
	v_mfma_f32_16x16x32_bf16 v[28:31], v[154:157], v[198:201], v[28:31]
	v_mfma_f32_16x16x32_bf16 v[20:23], v[166:169], v[198:201], v[20:23]
	v_mfma_f32_16x16x32_bf16 v[12:15], v[154:157], v[214:217], v[12:15]
	v_mfma_f32_16x16x32_bf16 v[8:11], v[166:169], v[214:217], v[8:11]
	v_mfma_f32_16x16x32_bf16 v[4:7], v[154:157], v[222:225], v[4:7]
	v_mfma_f32_16x16x32_bf16 v[0:3], v[166:169], v[222:225], v[0:3]
	s_setprio 0
	s_barrier
	v_add_u32_e32 v146, s17, v132
	v_add_u32_e32 v164, s16, v132
	ds_read_b128 v[134:137], v146
	ds_read_b128 v[138:141], v146 offset:1024
	ds_read_b128 v[142:145], v146 offset:2048
	ds_read_b128 v[146:149], v146 offset:3072
	ds_read_b128 v[150:153], v164
	ds_read_b128 v[154:157], v164 offset:1024
	ds_read_b128 v[158:161], v164 offset:2048
	ds_read_b128 v[166:169], v164 offset:3072
	s_mov_b32 m0, s19
	v_lshl_add_u64 v[232:233], s[66:67], 0, v[130:131]
	ds_read_b128 v[186:189], v133 offset:32768
	ds_read_b128 v[190:193], v133 offset:33792
	ds_read_b128 v[194:197], v133 offset:34816
	ds_read_b128 v[198:201], v133 offset:35840
	ds_read_b128 v[202:205], v133 offset:36864
	ds_read_b128 v[214:217], v133 offset:37888
	ds_read_b128 v[218:221], v133 offset:38912
	ds_read_b128 v[222:225], v133 offset:39936
	global_load_lds_dwordx4 v[232:233], off
	v_lshl_add_u64 v[232:233], s[66:67], 0, v[128:129]
	s_mov_b32 m0, s24
	s_nop 0
	global_load_lds_dwordx4 v[232:233], off
	s_waitcnt vmcnt(8)
	s_waitcnt lgkmcnt(0)
	s_barrier
	s_setprio 1
	v_mfma_f32_16x16x32_bf16 v[124:127], v[134:137], v[186:189], v[124:127]
	v_mfma_f32_16x16x32_bf16 v[120:123], v[142:145], v[186:189], v[120:123]
	v_mfma_f32_16x16x32_bf16 v[116:119], v[134:137], v[194:197], v[116:119]
	v_mfma_f32_16x16x32_bf16 v[112:115], v[142:145], v[194:197], v[112:115]
	v_mfma_f32_16x16x32_bf16 v[108:111], v[134:137], v[202:205], v[108:111]
	v_mfma_f32_16x16x32_bf16 v[100:103], v[142:145], v[202:205], v[100:103]
	v_mfma_f32_16x16x32_bf16 v[92:95], v[134:137], v[218:221], v[92:95]
	v_mfma_f32_16x16x32_bf16 v[84:87], v[142:145], v[218:221], v[84:87]
	v_mfma_f32_16x16x32_bf16 v[124:127], v[138:141], v[190:193], v[124:127]
	v_mfma_f32_16x16x32_bf16 v[120:123], v[146:149], v[190:193], v[120:123]
	v_mfma_f32_16x16x32_bf16 v[116:119], v[138:141], v[198:201], v[116:119]
	v_mfma_f32_16x16x32_bf16 v[112:115], v[146:149], v[198:201], v[112:115]
	v_mfma_f32_16x16x32_bf16 v[108:111], v[138:141], v[214:217], v[108:111]
	v_mfma_f32_16x16x32_bf16 v[100:103], v[146:149], v[214:217], v[100:103]
	v_mfma_f32_16x16x32_bf16 v[92:95], v[138:141], v[222:225], v[92:95]
	v_mfma_f32_16x16x32_bf16 v[84:87], v[146:149], v[222:225], v[84:87]
	v_mfma_f32_16x16x32_bf16 v[104:107], v[150:153], v[186:189], v[104:107]
	v_mfma_f32_16x16x32_bf16 v[96:99], v[158:161], v[186:189], v[96:99]
	v_mfma_f32_16x16x32_bf16 v[88:91], v[150:153], v[194:197], v[88:91]
	v_mfma_f32_16x16x32_bf16 v[80:83], v[158:161], v[194:197], v[80:83]
	v_mfma_f32_16x16x32_bf16 v[76:79], v[150:153], v[202:205], v[76:79]
	v_mfma_f32_16x16x32_bf16 v[72:75], v[158:161], v[202:205], v[72:75]
	v_mfma_f32_16x16x32_bf16 v[68:71], v[150:153], v[218:221], v[68:71]
	v_mfma_f32_16x16x32_bf16 v[64:67], v[158:161], v[218:221], v[64:67]
	v_mfma_f32_16x16x32_bf16 v[104:107], v[154:157], v[190:193], v[104:107]
	v_mfma_f32_16x16x32_bf16 v[96:99], v[166:169], v[190:193], v[96:99]
	v_mfma_f32_16x16x32_bf16 v[88:91], v[154:157], v[198:201], v[88:91]
	v_mfma_f32_16x16x32_bf16 v[80:83], v[166:169], v[198:201], v[80:83]
	v_mfma_f32_16x16x32_bf16 v[76:79], v[154:157], v[214:217], v[76:79]
	v_mfma_f32_16x16x32_bf16 v[72:75], v[166:169], v[214:217], v[72:75]
	v_mfma_f32_16x16x32_bf16 v[68:71], v[154:157], v[222:225], v[68:71]
	v_mfma_f32_16x16x32_bf16 v[64:67], v[166:169], v[222:225], v[64:67]
	s_setprio 0
	s_barrier
; #define PG8_STAGE(bufoff, gbase, voff) do { _Pragma("unroll") for (int _i = 0; _i < 2; ++_i) \
;         __builtin_amdgcn_global_load_lds((const unsigned*)((const char*)(gbase) + (voff)[_i]), (PG8_LAS unsigned*)(lds + (bufoff) + ldsw + _i * 8192), 16, 0, 0); } while (0)
; #define PG8_LDA(dst, b, h) do { _Pragma("unroll") for (int m = 0; m < 4; ++m) _Pragma("unroll") for (int k = 0; k < 2; ++k) dst[m][k] = *(const PG8_LAS bf16x8*)(lds + PG8_SA(b, h) + aoff + m * 2048 + k * 1024); } while (0)
; #define PG8_WAIT_V(n) asm volatile("s_waitcnt vmcnt(" #n ")" ::: "memory")
; template <class Epi, class Sched, bool ALIGN_EPI = false, bool SP2 = false>
; __device__ __forceinline__ void gemm_phase(PG8_LAS unsigned char* lds, const Gemm g, const Sched& S, const Epi& E) {
;     ...
;             PG8_LDA(At, 1, 1); PG8_STAGE(PG8_SB(1, 0), b3, voffB); PG8_STAGE(PG8_SB(1, 1), b3 + hstepB, voffB); PG8_STAGE(PG8_SA(1, 0), a3, voffA);
;             PG8_WAIT_V(8); PG8_WAIT_L(0); PG8_BAR; PG8_MMA(1, 0, At, B0); PG8_MMA(1, 1, At, B1); PG8_BAR; PG8_SCHED;
;             } else {
;             PG8_LDB(B0, 0, 0); PG8_SCHED; PG8_LDA(At, 0, 0); PG8_STAGE(PG8_SA(1, 1), a1 + hstepA, voffA);
;             PG8_WAIT_L(8); PG8_BAR; PG8_WAIT_L(0); PG8_MMA(0, 0, At, B0); PG8_BAR; PG8_SCHED;
;             PG8_LDB(B1, 0, 1); PG8_STAGE(PG8_SB(0, 0), b2, voffB);
;             PG8_BAR; PG8_WAIT_L(0); PG8_MMA(0, 1, At, B1); PG8_BAR;
;             PG8_LDA(At, 0, 1); PG8_STAGE(PG8_SA(0, 0), a2, voffA);
;             PG8_BAR; PG8_WAIT_L(0); PG8_MMA(1, 0, At, B0); PG8_BAR; PG8_SCHED;
;             PG8_STAGE(PG8_SB(0, 1), b2 + hstepB, voffB);
;             PG8_WAIT_V(6); PG8_BAR; PG8_MMA(1, 1, At, B1); PG8_BAR;
;             PG8_LDB(B0, 1, 0); PG8_SCHED; PG8_LDA(At, 1, 0); PG8_STAGE(PG8_SA(0, 1), a2 + hstepA, voffA);
;             PG8_WAIT_L(8); PG8_BAR; PG8_WAIT_L(0); PG8_MMA(0, 0, At, B0); PG8_BAR; PG8_SCHED;
;             PG8_LDB(B1, 1, 1); PG8_STAGE(PG8_SB(1, 0), b3, voffB);
;             PG8_BAR; PG8_WAIT_L(0); PG8_MMA(0, 1, At, B1); PG8_BAR;
;             PG8_LDA(At, 1, 1); PG8_STAGE(PG8_SA(1, 0), a3, voffA);
;             PG8_BAR; PG8_WAIT_L(0); PG8_MMA(1, 0, At, B0); PG8_BAR; PG8_SCHED;
;             PG8_STAGE(PG8_SB(1, 1), b3 + hstepB, voffB);
;             PG8_WAIT_V(6); PG8_BAR; PG8_MMA(1, 1, At, B1); PG8_BAR;
;             }
;         }
;         if constexpr (ALIGN_EPI) { if (wr == 0) PG8_BAR; }
	s_mov_b32 m0, s3
	v_lshl_add_u64 v[162:163], v[162:163], 0, s[14:15]
	ds_read_b128 v[186:189], v133 offset:49152
	ds_read_b128 v[190:193], v133 offset:50176
	ds_read_b128 v[194:197], v133 offset:51200
	ds_read_b128 v[198:201], v133 offset:52224
	ds_read_b128 v[202:205], v133 offset:53248
	ds_read_b128 v[214:217], v133 offset:54272
	ds_read_b128 v[218:221], v133 offset:55296
	ds_read_b128 v[222:225], v133 offset:56320
	global_load_lds_dwordx4 v[162:163], off
	v_lshl_add_u64 v[162:163], v[226:227], 0, s[14:15]
	s_mov_b32 m0, s2
	s_nop 0
	global_load_lds_dwordx4 v[162:163], off
	v_lshl_add_u64 v[162:163], s[64:65], 0, v[130:131]
	s_mov_b32 m0, s45
	s_nop 0
	global_load_lds_dwordx4 v[162:163], off
	v_lshl_add_u64 v[162:163], s[64:65], 0, v[128:129]
	s_mov_b32 m0, s44
	s_nop 0
	global_load_lds_dwordx4 v[162:163], off
	v_lshl_add_u64 v[162:163], v[228:229], 0, s[14:15]
	s_mov_b32 m0, s46
	s_nop 0
	global_load_lds_dwordx4 v[162:163], off
	v_lshl_add_u64 v[162:163], v[230:231], 0, s[14:15]
	s_mov_b32 m0, s47
	s_nop 0
	global_load_lds_dwordx4 v[162:163], off
	s_waitcnt vmcnt(8)
	s_waitcnt lgkmcnt(0)
	s_barrier
	s_setprio 1
	v_mfma_f32_16x16x32_bf16 v[60:63], v[134:137], v[186:189], v[60:63]
	v_mfma_f32_16x16x32_bf16 v[56:59], v[142:145], v[186:189], v[56:59]
	v_mfma_f32_16x16x32_bf16 v[52:55], v[134:137], v[194:197], v[52:55]
	v_mfma_f32_16x16x32_bf16 v[48:51], v[142:145], v[194:197], v[48:51]
	v_mfma_f32_16x16x32_bf16 v[40:43], v[134:137], v[202:205], v[40:43]
	v_mfma_f32_16x16x32_bf16 v[32:35], v[142:145], v[202:205], v[32:35]
	v_mfma_f32_16x16x32_bf16 v[24:27], v[134:137], v[218:221], v[24:27]
	v_mfma_f32_16x16x32_bf16 v[16:19], v[142:145], v[218:221], v[16:19]
	v_mfma_f32_16x16x32_bf16 v[60:63], v[138:141], v[190:193], v[60:63]
	v_mfma_f32_16x16x32_bf16 v[56:59], v[146:149], v[190:193], v[56:59]
	v_mfma_f32_16x16x32_bf16 v[52:55], v[138:141], v[198:201], v[52:55]
	v_mfma_f32_16x16x32_bf16 v[48:51], v[146:149], v[198:201], v[48:51]
	v_mfma_f32_16x16x32_bf16 v[40:43], v[138:141], v[214:217], v[40:43]
	v_mfma_f32_16x16x32_bf16 v[32:35], v[146:149], v[214:217], v[32:35]
	v_mfma_f32_16x16x32_bf16 v[24:27], v[138:141], v[222:225], v[24:27]
	v_mfma_f32_16x16x32_bf16 v[16:19], v[146:149], v[222:225], v[16:19]
	v_mfma_f32_16x16x32_bf16 v[44:47], v[150:153], v[186:189], v[44:47]
	v_mfma_f32_16x16x32_bf16 v[36:39], v[158:161], v[186:189], v[36:39]
	v_mfma_f32_16x16x32_bf16 v[28:31], v[150:153], v[194:197], v[28:31]
	v_mfma_f32_16x16x32_bf16 v[20:23], v[158:161], v[194:197], v[20:23]
	v_mfma_f32_16x16x32_bf16 v[12:15], v[150:153], v[202:205], v[12:15]
	v_mfma_f32_16x16x32_bf16 v[8:11], v[158:161], v[202:205], v[8:11]
	v_mfma_f32_16x16x32_bf16 v[4:7], v[150:153], v[218:221], v[4:7]
	v_mfma_f32_16x16x32_bf16 v[0:3], v[158:161], v[218:221], v[0:3]
	v_mfma_f32_16x16x32_bf16 v[44:47], v[154:157], v[190:193], v[44:47]
	v_mfma_f32_16x16x32_bf16 v[36:39], v[166:169], v[190:193], v[36:39]
	v_mfma_f32_16x16x32_bf16 v[28:31], v[154:157], v[198:201], v[28:31]
	v_mfma_f32_16x16x32_bf16 v[20:23], v[166:169], v[198:201], v[20:23]
	v_mfma_f32_16x16x32_bf16 v[12:15], v[154:157], v[214:217], v[12:15]
	v_mfma_f32_16x16x32_bf16 v[8:11], v[166:169], v[214:217], v[8:11]
	v_mfma_f32_16x16x32_bf16 v[4:7], v[154:157], v[222:225], v[4:7]
	v_mfma_f32_16x16x32_bf16 v[0:3], v[166:169], v[222:225], v[0:3]
	s_setprio 0
	s_barrier
	s_movk_i32 s0, 0x100
	s_andn2_b64 vcc, exec, s[62:63]
	s_mov_b64 s[64:65], -1
	s_mov_b64 s[62:63], 0
	s_cbranch_vccz .LBB0_1047
	s_and_b64 vcc, exec, s[30:31]
	s_cbranch_vccz .LBB0_1050
	s_barrier

; #define PG8_STAGE(bufoff, gbase, voff) do { _Pragma("unroll") for (int _i = 0; _i < 2; ++_i) \
;         __builtin_amdgcn_global_load_lds((const unsigned*)((const char*)(gbase) + (voff)[_i]), (PG8_LAS unsigned*)(lds + (bufoff) + ldsw + _i * 8192), 16, 0, 0); } while (0)
; #define PG8_LDA(dst, b, h) do { _Pragma("unroll") for (int m = 0; m < 4; ++m) _Pragma("unroll") for (int k = 0; k < 2; ++k) dst[m][k] = *(const PG8_LAS bf16x8*)(lds + PG8_SA(b, h) + aoff + m * 2048 + k * 1024); } while (0)
; #define PG8_LDB(dst, b, h) do { _Pragma("unroll") for (int n = 0; n < 2; ++n) _Pragma("unroll") for (int k = 0; k < 2; ++k) dst[n][k] = *(const PG8_LAS bf16x8*)(lds + PG8_SB(b, h) + boff + n * 2048 + k * 1024); } while (0)
; #define PG8_MMA(ai, bj, At, Bt) do { __builtin_amdgcn_s_setprio(1); _Pragma("unroll") for (int m = 0; m < 4; ++m) _Pragma("unroll") for (int n = 0; n < 2; ++n) _Pragma("unroll") for (int k = 0; k < 2; ++k) \
;         acc[ai][bj][m][n] = __builtin_amdgcn_mfma_f32_16x16x32_bf16(Bt[n][k], At[m][k], acc[ai][bj][m][n], 0, 0, 0); __builtin_amdgcn_s_setprio(0); } while (0)
; #define PG8_WAIT_V(n) asm volatile("s_waitcnt vmcnt(" #n ")" ::: "memory")
; #define PG8_WAIT_L(n) asm volatile("s_waitcnt lgkmcnt(" #n ")" ::: "memory")
; template <class Epi, class Sched, bool ALIGN_EPI = false, bool SP2 = false>
; __device__ __forceinline__ void gemm_phase(PG8_LAS unsigned char* lds, const Gemm g, const Sched& S, const Epi& E) {
;     ...
;             const bool last = (t == nt - 2);
;             const char* a1 = cA + (size_t)(t + 1) * kstep;
;             const char* a2 = last ? nA : cA + (size_t)(t + 2) * kstep; const char* b2 = last ? nB : cB + (size_t)(t + 2) * kstep;
;             const char* a3 = a2 + kstep; const char* b3 = b2 + kstep;
;             if (last && has_next) S.a_ready(nxt);
;             if constexpr (SP2) {
;             PG8_LDB(B0, 0, 0); PG8_LDB(B1, 0, 1); PG8_SCHED; PG8_LDA(At, 0, 0); PG8_STAGE(PG8_SA(1, 1), a1 + hstepA, voffA);
;             PG8_WAIT_V(8); PG8_WAIT_L(0); PG8_BAR; PG8_MMA(0, 0, At, B0); PG8_MMA(0, 1, At, B1); PG8_BAR; PG8_SCHED;
;             PG8_LDA(At, 0, 1); PG8_STAGE(PG8_SB(0, 0), b2, voffB); PG8_STAGE(PG8_SB(0, 1), b2 + hstepB, voffB); PG8_STAGE(PG8_SA(0, 0), a2, voffA);
;             PG8_WAIT_V(8); PG8_WAIT_L(0); PG8_BAR; PG8_MMA(1, 0, At, B0); PG8_MMA(1, 1, At, B1); PG8_BAR; PG8_SCHED;
.LBB0_1218:
	s_add_u32 s0, s48, 0xfffc0080
	s_addc_u32 s1, s49, -1
	s_add_i32 s4, 0, 0x10000
	s_cmp_eq_u32 s18, 12
	s_cselect_b32 s1, s9, s1
	s_cselect_b32 s0, s10, s0
	s_cselect_b32 s51, s12, s17
	s_cselect_b32 s50, s13, s16
	s_add_i32 s5, 0, 0x14000
	v_add_u32_e32 v152, s4, v146
	v_add_u32_e32 v186, s5, v146
	ds_read_b128 v[138:141], v152
	ds_read_b128 v[142:145], v152 offset:1024
	ds_read_b128 v[148:151], v152 offset:2048
	ds_read_b128 v[152:155], v152 offset:3072
	ds_read_b128 v[156:159], v186
	ds_read_b128 v[160:163], v186 offset:1024
	ds_read_b128 v[166:169], v186 offset:2048
	ds_read_b128 v[186:189], v186 offset:3072
	v_lshl_add_u64 v[230:231], s[48:49], 0, v[136:137]
	s_add_i32 m0, s56, 0xc000
	ds_read_b128 v[190:193], v147
	ds_read_b128 v[194:197], v147 offset:1024
	ds_read_b128 v[198:201], v147 offset:2048
	ds_read_b128 v[202:205], v147 offset:3072
	ds_read_b128 v[214:217], v147 offset:4096
	ds_read_b128 v[218:221], v147 offset:5120
	ds_read_b128 v[222:225], v147 offset:6144
	ds_read_b128 v[226:229], v147 offset:7168
	global_load_lds_dwordx4 v[230:231], off
	v_lshl_add_u64 v[230:231], s[48:49], 0, v[134:135]
	s_add_i32 m0, s56, 0xe000
	s_nop 0
	global_load_lds_dwordx4 v[230:231], off
	s_waitcnt vmcnt(8)
	s_waitcnt lgkmcnt(0)
	s_barrier
	s_setprio 1
	v_mfma_f32_16x16x32_bf16 v[124:127], v[138:141], v[190:193], v[124:127]
	v_mfma_f32_16x16x32_bf16 v[120:123], v[148:151], v[190:193], v[120:123]
	v_mfma_f32_16x16x32_bf16 v[108:111], v[138:141], v[198:201], v[108:111]
	v_mfma_f32_16x16x32_bf16 v[104:107], v[148:151], v[198:201], v[104:107]
	v_mfma_f32_16x16x32_bf16 v[92:95], v[138:141], v[214:217], v[92:95]
	v_mfma_f32_16x16x32_bf16 v[88:91], v[148:151], v[214:217], v[88:91]
	v_mfma_f32_16x16x32_bf16 v[76:79], v[138:141], v[222:225], v[76:79]
	v_mfma_f32_16x16x32_bf16 v[72:75], v[148:151], v[222:225], v[72:75]
	v_mfma_f32_16x16x32_bf16 v[124:127], v[142:145], v[194:197], v[124:127]
	v_mfma_f32_16x16x32_bf16 v[120:123], v[152:155], v[194:197], v[120:123]
	v_mfma_f32_16x16x32_bf16 v[108:111], v[142:145], v[202:205], v[108:111]
	v_mfma_f32_16x16x32_bf16 v[104:107], v[152:155], v[202:205], v[104:107]
	v_mfma_f32_16x16x32_bf16 v[92:95], v[142:145], v[218:221], v[92:95]
	v_mfma_f32_16x16x32_bf16 v[88:91], v[152:155], v[218:221], v[88:91]
	v_mfma_f32_16x16x32_bf16 v[76:79], v[142:145], v[226:229], v[76:79]
	v_mfma_f32_16x16x32_bf16 v[72:75], v[152:155], v[226:229], v[72:75]
	v_mfma_f32_16x16x32_bf16 v[116:119], v[156:159], v[190:193], v[116:119]
	v_mfma_f32_16x16x32_bf16 v[112:115], v[166:169], v[190:193], v[112:115]
	v_mfma_f32_16x16x32_bf16 v[100:103], v[156:159], v[198:201], v[100:103]
	v_mfma_f32_16x16x32_bf16 v[96:99], v[166:169], v[198:201], v[96:99]
	v_mfma_f32_16x16x32_bf16 v[84:87], v[156:159], v[214:217], v[84:87]
	v_mfma_f32_16x16x32_bf16 v[80:83], v[166:169], v[214:217], v[80:83]
	v_mfma_f32_16x16x32_bf16 v[68:71], v[156:159], v[222:225], v[68:71]
	v_mfma_f32_16x16x32_bf16 v[64:67], v[166:169], v[222:225], v[64:67]
	v_mfma_f32_16x16x32_bf16 v[116:119], v[160:163], v[194:197], v[116:119]
	v_mfma_f32_16x16x32_bf16 v[112:115], v[186:189], v[194:197], v[112:115]
	v_mfma_f32_16x16x32_bf16 v[100:103], v[160:163], v[202:205], v[100:103]
	v_mfma_f32_16x16x32_bf16 v[96:99], v[186:189], v[202:205], v[96:99]
	v_mfma_f32_16x16x32_bf16 v[84:87], v[160:163], v[218:221], v[84:87]
	v_mfma_f32_16x16x32_bf16 v[80:83], v[186:189], v[218:221], v[80:83]
	v_mfma_f32_16x16x32_bf16 v[68:71], v[160:163], v[226:229], v[68:71]
	v_mfma_f32_16x16x32_bf16 v[64:67], v[186:189], v[226:229], v[64:67]
	s_setprio 0
	s_barrier
	s_add_i32 s4, s4, s54
	v_lshl_add_u64 v[230:231], s[50:51], 0, v[164:165]
	s_mov_b32 m0, s4
	ds_read_b128 v[190:193], v147 offset:16384
	ds_read_b128 v[194:197], v147 offset:17408
	ds_read_b128 v[198:201], v147 offset:18432
	ds_read_b128 v[202:205], v147 offset:19456
	ds_read_b128 v[214:217], v147 offset:20480
	ds_read_b128 v[218:221], v147 offset:21504
	ds_read_b128 v[222:225], v147 offset:22528
	ds_read_b128 v[226:229], v147 offset:23552
	global_load_lds_dwordx4 v[230:231], off
	s_add_i32 m0, s4, 0x2000
	s_add_u32 s24, s50, 0x40000
	v_lshl_add_u64 v[232:233], s[50:51], 0, v[128:129]
	s_addc_u32 s25, s51, 0
	s_add_i32 s4, s5, s54
	global_load_lds_dwordx4 v[232:233], off
	v_lshl_add_u64 v[234:235], s[24:25], 0, v[164:165]
	s_mov_b32 m0, s4
	v_lshl_add_u64 v[236:237], s[0:1], 0, v[130:131]
	global_load_lds_dwordx4 v[234:235], off
	v_lshl_add_u64 v[234:235], s[24:25], 0, v[128:129]
	s_add_i32 m0, s4, 0x2000
	s_nop 0
	global_load_lds_dwordx4 v[234:235], off
	v_lshl_add_u64 v[234:235], s[0:1], 0, v[132:133]
	s_mov_b32 m0, s56
	s_nop 0
	global_load_lds_dwordx4 v[234:235], off
	s_mov_b32 m0, s57
	s_nop 0
	global_load_lds_dwordx4 v[236:237], off
	s_waitcnt vmcnt(8)
	s_waitcnt lgkmcnt(0)
	s_barrier
; #define PG8_STAGE(bufoff, gbase, voff) do { _Pragma("unroll") for (int _i = 0; _i < 2; ++_i) \
;         __builtin_amdgcn_global_load_lds((const unsigned*)((const char*)(gbase) + (voff)[_i]), (PG8_LAS unsigned*)(lds + (bufoff) + ldsw + _i * 8192), 16, 0, 0); } while (0)
; #define PG8_LDA(dst, b, h) do { _Pragma("unroll") for (int m = 0; m < 4; ++m) _Pragma("unroll") for (int k = 0; k < 2; ++k) dst[m][k] = *(const PG8_LAS bf16x8*)(lds + PG8_SA(b, h) + aoff + m * 2048 + k * 1024); } while (0)
; #define PG8_LDB(dst, b, h) do { _Pragma("unroll") for (int n = 0; n < 2; ++n) _Pragma("unroll") for (int k = 0; k < 2; ++k) dst[n][k] = *(const PG8_LAS bf16x8*)(lds + PG8_SB(b, h) + boff + n * 2048 + k * 1024); } while (0)
; #define PG8_MMA(ai, bj, At, Bt) do { __builtin_amdgcn_s_setprio(1); _Pragma("unroll") for (int m = 0; m < 4; ++m) _Pragma("unroll") for (int n = 0; n < 2; ++n) _Pragma("unroll") for (int k = 0; k < 2; ++k) \
;         acc[ai][bj][m][n] = __builtin_amdgcn_mfma_f32_16x16x32_bf16(Bt[n][k], At[m][k], acc[ai][bj][m][n], 0, 0, 0); __builtin_amdgcn_s_setprio(0); } while (0)
; #define PG8_WAIT_V(n) asm volatile("s_waitcnt vmcnt(" #n ")" ::: "memory")
; #define PG8_WAIT_L(n) asm volatile("s_waitcnt lgkmcnt(" #n ")" ::: "memory")
; #define PG8_BAR __builtin_amdgcn_s_barrier()
; #define PG8_SCHED __builtin_amdgcn_sched_barrier(0)
; template <class Epi, class Sched, bool ALIGN_EPI = false, bool SP2 = false>
; __device__ __forceinline__ void gemm_phase(PG8_LAS unsigned char* lds, const Gemm g, const Sched& S, const Epi& E) {
;     ...
;             PG8_WAIT_V(8); PG8_WAIT_L(0); PG8_BAR; PG8_MMA(1, 0, At, B0); PG8_MMA(1, 1, At, B1); PG8_BAR; PG8_SCHED;
;             PG8_LDB(B0, 1, 0); PG8_LDB(B1, 1, 1); PG8_SCHED; PG8_LDA(At, 1, 0); PG8_STAGE(PG8_SA(0, 1), a2 + hstepA, voffA);
;             PG8_WAIT_V(8); PG8_WAIT_L(0); PG8_BAR; PG8_MMA(0, 0, At, B0); PG8_MMA(0, 1, At, B1); PG8_BAR; PG8_SCHED;
	s_setprio 1
	v_mfma_f32_16x16x32_bf16 v[60:63], v[138:141], v[190:193], v[60:63]
	v_mfma_f32_16x16x32_bf16 v[56:59], v[148:151], v[190:193], v[56:59]
	v_mfma_f32_16x16x32_bf16 v[44:47], v[138:141], v[198:201], v[44:47]
	v_mfma_f32_16x16x32_bf16 v[40:43], v[148:151], v[198:201], v[40:43]
	v_mfma_f32_16x16x32_bf16 v[28:31], v[138:141], v[214:217], v[28:31]
	v_mfma_f32_16x16x32_bf16 v[24:27], v[148:151], v[214:217], v[24:27]
	v_mfma_f32_16x16x32_bf16 v[12:15], v[138:141], v[222:225], v[12:15]
	v_mfma_f32_16x16x32_bf16 v[8:11], v[148:151], v[222:225], v[8:11]
	v_mfma_f32_16x16x32_bf16 v[60:63], v[142:145], v[194:197], v[60:63]
	v_mfma_f32_16x16x32_bf16 v[56:59], v[152:155], v[194:197], v[56:59]
	v_mfma_f32_16x16x32_bf16 v[44:47], v[142:145], v[202:205], v[44:47]
	v_mfma_f32_16x16x32_bf16 v[40:43], v[152:155], v[202:205], v[40:43]
	v_mfma_f32_16x16x32_bf16 v[28:31], v[142:145], v[218:221], v[28:31]
	v_mfma_f32_16x16x32_bf16 v[24:27], v[152:155], v[218:221], v[24:27]
	v_mfma_f32_16x16x32_bf16 v[12:15], v[142:145], v[226:229], v[12:15]
	v_mfma_f32_16x16x32_bf16 v[8:11], v[152:155], v[226:229], v[8:11]
	v_mfma_f32_16x16x32_bf16 v[52:55], v[156:159], v[190:193], v[52:55]
	v_mfma_f32_16x16x32_bf16 v[48:51], v[166:169], v[190:193], v[48:51]
	v_mfma_f32_16x16x32_bf16 v[36:39], v[156:159], v[198:201], v[36:39]
	v_mfma_f32_16x16x32_bf16 v[32:35], v[166:169], v[198:201], v[32:35]
	v_mfma_f32_16x16x32_bf16 v[20:23], v[156:159], v[214:217], v[20:23]
	v_mfma_f32_16x16x32_bf16 v[16:19], v[166:169], v[214:217], v[16:19]
	v_mfma_f32_16x16x32_bf16 v[4:7], v[156:159], v[222:225], v[4:7]
	v_mfma_f32_16x16x32_bf16 v[0:3], v[166:169], v[222:225], v[0:3]
	v_mfma_f32_16x16x32_bf16 v[52:55], v[160:163], v[194:197], v[52:55]
	v_mfma_f32_16x16x32_bf16 v[48:51], v[186:189], v[194:197], v[48:51]
	v_mfma_f32_16x16x32_bf16 v[36:39], v[160:163], v[202:205], v[36:39]
	v_mfma_f32_16x16x32_bf16 v[32:35], v[186:189], v[202:205], v[32:35]
	v_mfma_f32_16x16x32_bf16 v[20:23], v[160:163], v[218:221], v[20:23]
	v_mfma_f32_16x16x32_bf16 v[16:19], v[186:189], v[218:221], v[16:19]
	v_mfma_f32_16x16x32_bf16 v[4:7], v[160:163], v[226:229], v[4:7]
	v_mfma_f32_16x16x32_bf16 v[0:3], v[186:189], v[226:229], v[0:3]
	s_setprio 0
	s_barrier
	s_add_i32 s4, 0, 0x18000
	s_add_i32 s5, 0, 0x1c000
	v_add_u32_e32 v152, s4, v146
	v_add_u32_e32 v186, s5, v146
	ds_read_b128 v[138:141], v152
	ds_read_b128 v[142:145], v152 offset:1024
	ds_read_b128 v[148:151], v152 offset:2048
	ds_read_b128 v[152:155], v152 offset:3072
	ds_read_b128 v[156:159], v186
	ds_read_b128 v[160:163], v186 offset:1024
	ds_read_b128 v[166:169], v186 offset:2048
	ds_read_b128 v[186:189], v186 offset:3072
	s_add_u32 s0, s0, 0x40000
	s_addc_u32 s1, s1, 0
	s_mov_b32 m0, s58
	v_lshl_add_u64 v[238:239], s[0:1], 0, v[132:133]
	ds_read_b128 v[190:193], v147 offset:32768
	ds_read_b128 v[194:197], v147 offset:33792
	ds_read_b128 v[198:201], v147 offset:34816
	ds_read_b128 v[202:205], v147 offset:35840
	ds_read_b128 v[214:217], v147 offset:36864
	ds_read_b128 v[218:221], v147 offset:37888
	ds_read_b128 v[222:225], v147 offset:38912
	ds_read_b128 v[226:229], v147 offset:39936
	global_load_lds_dwordx4 v[238:239], off
	v_lshl_add_u64 v[238:239], s[0:1], 0, v[130:131]
	s_mov_b32 m0, s59
	s_nop 0
	global_load_lds_dwordx4 v[238:239], off
	s_waitcnt vmcnt(8)
	s_waitcnt lgkmcnt(0)
	s_barrier
	s_setprio 1
	v_mfma_f32_16x16x32_bf16 v[124:127], v[138:141], v[190:193], v[124:127]
	v_mfma_f32_16x16x32_bf16 v[120:123], v[148:151], v[190:193], v[120:123]
	v_mfma_f32_16x16x32_bf16 v[108:111], v[138:141], v[198:201], v[108:111]
	v_mfma_f32_16x16x32_bf16 v[104:107], v[148:151], v[198:201], v[104:107]
	v_mfma_f32_16x16x32_bf16 v[92:95], v[138:141], v[214:217], v[92:95]
	v_mfma_f32_16x16x32_bf16 v[88:91], v[148:151], v[214:217], v[88:91]
	v_mfma_f32_16x16x32_bf16 v[76:79], v[138:141], v[222:225], v[76:79]
	v_mfma_f32_16x16x32_bf16 v[72:75], v[148:151], v[222:225], v[72:75]
	v_mfma_f32_16x16x32_bf16 v[124:127], v[142:145], v[194:197], v[124:127]
	v_mfma_f32_16x16x32_bf16 v[120:123], v[152:155], v[194:197], v[120:123]
	v_mfma_f32_16x16x32_bf16 v[108:111], v[142:145], v[202:205], v[108:111]
	v_mfma_f32_16x16x32_bf16 v[104:107], v[152:155], v[202:205], v[104:107]
	v_mfma_f32_16x16x32_bf16 v[92:95], v[142:145], v[218:221], v[92:95]
	v_mfma_f32_16x16x32_bf16 v[88:91], v[152:155], v[218:221], v[88:91]
	v_mfma_f32_16x16x32_bf16 v[76:79], v[142:145], v[226:229], v[76:79]
	v_mfma_f32_16x16x32_bf16 v[72:75], v[152:155], v[226:229], v[72:75]
	v_mfma_f32_16x16x32_bf16 v[116:119], v[156:159], v[190:193], v[116:119]
	v_mfma_f32_16x16x32_bf16 v[112:115], v[166:169], v[190:193], v[112:115]
	v_mfma_f32_16x16x32_bf16 v[100:103], v[156:159], v[198:201], v[100:103]
	v_mfma_f32_16x16x32_bf16 v[96:99], v[166:169], v[198:201], v[96:99]
	v_mfma_f32_16x16x32_bf16 v[84:87], v[156:159], v[214:217], v[84:87]
	v_mfma_f32_16x16x32_bf16 v[80:83], v[166:169], v[214:217], v[80:83]
	v_mfma_f32_16x16x32_bf16 v[68:71], v[156:159], v[222:225], v[68:71]
	v_mfma_f32_16x16x32_bf16 v[64:67], v[166:169], v[222:225], v[64:67]
	v_mfma_f32_16x16x32_bf16 v[116:119], v[160:163], v[194:197], v[116:119]
	v_mfma_f32_16x16x32_bf16 v[112:115], v[186:189], v[194:197], v[112:115]
	v_mfma_f32_16x16x32_bf16 v[100:103], v[160:163], v[202:205], v[100:103]
	v_mfma_f32_16x16x32_bf16 v[96:99], v[186:189], v[202:205], v[96:99]
	v_mfma_f32_16x16x32_bf16 v[84:87], v[160:163], v[218:221], v[84:87]
	v_mfma_f32_16x16x32_bf16 v[80:83], v[186:189], v[218:221], v[80:83]
	v_mfma_f32_16x16x32_bf16 v[68:71], v[160:163], v[226:229], v[68:71]
	v_mfma_f32_16x16x32_bf16 v[64:67], v[186:189], v[226:229], v[64:67]
	s_setprio 0
	s_barrier
; #define PG8_STAGE(bufoff, gbase, voff) do { _Pragma("unroll") for (int _i = 0; _i < 2; ++_i) \
;         __builtin_amdgcn_global_load_lds((const unsigned*)((const char*)(gbase) + (voff)[_i]), (PG8_LAS unsigned*)(lds + (bufoff) + ldsw + _i * 8192), 16, 0, 0); } while (0)
; #define PG8_LDA(dst, b, h) do { _Pragma("unroll") for (int m = 0; m < 4; ++m) _Pragma("unroll") for (int k = 0; k < 2; ++k) dst[m][k] = *(const PG8_LAS bf16x8*)(lds + PG8_SA(b, h) + aoff + m * 2048 + k * 1024); } while (0)
; #define PG8_WAIT_V(n) asm volatile("s_waitcnt vmcnt(" #n ")" ::: "memory")
; template <class Epi, class Sched, bool ALIGN_EPI = false, bool SP2 = false>
; __device__ __forceinline__ void gemm_phase(PG8_LAS unsigned char* lds, const Gemm g, const Sched& S, const Epi& E) {
;     ...
;             PG8_LDA(At, 1, 1); PG8_STAGE(PG8_SB(1, 0), b3, voffB); PG8_STAGE(PG8_SB(1, 1), b3 + hstepB, voffB); PG8_STAGE(PG8_SA(1, 0), a3, voffA);
;             PG8_WAIT_V(8); PG8_WAIT_L(0); PG8_BAR; PG8_MMA(1, 0, At, B0); PG8_MMA(1, 1, At, B1); PG8_BAR; PG8_SCHED;
;             } else {
;             PG8_LDB(B0, 0, 0); PG8_SCHED; PG8_LDA(At, 0, 0); PG8_STAGE(PG8_SA(1, 1), a1 + hstepA, voffA);
;             PG8_WAIT_L(8); PG8_BAR; PG8_WAIT_L(0); PG8_MMA(0, 0, At, B0); PG8_BAR; PG8_SCHED;
;             PG8_LDB(B1, 0, 1); PG8_STAGE(PG8_SB(0, 0), b2, voffB);
;             PG8_BAR; PG8_WAIT_L(0); PG8_MMA(0, 1, At, B1); PG8_BAR;
;             PG8_LDA(At, 0, 1); PG8_STAGE(PG8_SA(0, 0), a2, voffA);
;             PG8_BAR; PG8_WAIT_L(0); PG8_MMA(1, 0, At, B0); PG8_BAR; PG8_SCHED;
;             PG8_STAGE(PG8_SB(0, 1), b2 + hstepB, voffB);
;             PG8_WAIT_V(6); PG8_BAR; PG8_MMA(1, 1, At, B1); PG8_BAR;
;             PG8_LDB(B0, 1, 0); PG8_SCHED; PG8_LDA(At, 1, 0); PG8_STAGE(PG8_SA(0, 1), a2 + hstepA, voffA);
;             PG8_WAIT_L(8); PG8_BAR; PG8_WAIT_L(0); PG8_MMA(0, 0, At, B0); PG8_BAR; PG8_SCHED;
;             PG8_LDB(B1, 1, 1); PG8_STAGE(PG8_SB(1, 0), b3, voffB);
;             PG8_BAR; PG8_WAIT_L(0); PG8_MMA(0, 1, At, B1); PG8_BAR;
;             PG8_LDA(At, 1, 1); PG8_STAGE(PG8_SA(1, 0), a3, voffA);
;             PG8_BAR; PG8_WAIT_L(0); PG8_MMA(1, 0, At, B0); PG8_BAR; PG8_SCHED;
;             PG8_STAGE(PG8_SB(1, 1), b3 + hstepB, voffB);
;             PG8_WAIT_V(6); PG8_BAR; PG8_MMA(1, 1, At, B1); PG8_BAR;
;             }
;         }
;         if constexpr (ALIGN_EPI) { if (wr == 0) PG8_BAR; }
	s_add_i32 s0, s4, s54
	v_lshl_add_u64 v[230:231], v[230:231], 0, s[14:15]
	s_mov_b32 m0, s0
	ds_read_b128 v[190:193], v147 offset:49152
	ds_read_b128 v[194:197], v147 offset:50176
	ds_read_b128 v[198:201], v147 offset:51200
	ds_read_b128 v[202:205], v147 offset:52224
	ds_read_b128 v[214:217], v147 offset:53248
	ds_read_b128 v[218:221], v147 offset:54272
	ds_read_b128 v[222:225], v147 offset:55296
	ds_read_b128 v[226:229], v147 offset:56320
	global_load_lds_dwordx4 v[230:231], off
	s_add_i32 m0, s0, 0x2000
	s_add_u32 s0, s50, 0x40080
	v_lshl_add_u64 v[230:231], v[232:233], 0, s[14:15]
	s_addc_u32 s1, s51, 0
	s_add_i32 s4, s5, s54
	global_load_lds_dwordx4 v[230:231], off
	v_lshl_add_u64 v[230:231], s[0:1], 0, v[164:165]
	s_mov_b32 m0, s4
	s_nop 0
	global_load_lds_dwordx4 v[230:231], off
	v_lshl_add_u64 v[230:231], s[0:1], 0, v[128:129]
	s_add_i32 m0, s4, 0x2000
	s_nop 0
	global_load_lds_dwordx4 v[230:231], off
	v_lshl_add_u64 v[230:231], v[234:235], 0, s[14:15]
	s_mov_b32 m0, s62
	s_nop 0
	global_load_lds_dwordx4 v[230:231], off
	v_lshl_add_u64 v[230:231], v[236:237], 0, s[14:15]
	s_mov_b32 m0, s63
	s_nop 0
	global_load_lds_dwordx4 v[230:231], off
	s_waitcnt vmcnt(8)
	s_waitcnt lgkmcnt(0)
	s_barrier
	s_setprio 1
	v_mfma_f32_16x16x32_bf16 v[60:63], v[138:141], v[190:193], v[60:63]
	v_mfma_f32_16x16x32_bf16 v[56:59], v[148:151], v[190:193], v[56:59]
	v_mfma_f32_16x16x32_bf16 v[44:47], v[138:141], v[198:201], v[44:47]
	v_mfma_f32_16x16x32_bf16 v[40:43], v[148:151], v[198:201], v[40:43]
	v_mfma_f32_16x16x32_bf16 v[28:31], v[138:141], v[214:217], v[28:31]
	v_mfma_f32_16x16x32_bf16 v[24:27], v[148:151], v[214:217], v[24:27]
	v_mfma_f32_16x16x32_bf16 v[12:15], v[138:141], v[222:225], v[12:15]
	v_mfma_f32_16x16x32_bf16 v[8:11], v[148:151], v[222:225], v[8:11]
	v_mfma_f32_16x16x32_bf16 v[60:63], v[142:145], v[194:197], v[60:63]
	v_mfma_f32_16x16x32_bf16 v[56:59], v[152:155], v[194:197], v[56:59]
	v_mfma_f32_16x16x32_bf16 v[44:47], v[142:145], v[202:205], v[44:47]
	v_mfma_f32_16x16x32_bf16 v[40:43], v[152:155], v[202:205], v[40:43]
	v_mfma_f32_16x16x32_bf16 v[28:31], v[142:145], v[218:221], v[28:31]
	v_mfma_f32_16x16x32_bf16 v[24:27], v[152:155], v[218:221], v[24:27]
	v_mfma_f32_16x16x32_bf16 v[12:15], v[142:145], v[226:229], v[12:15]
	v_mfma_f32_16x16x32_bf16 v[8:11], v[152:155], v[226:229], v[8:11]
	v_mfma_f32_16x16x32_bf16 v[52:55], v[156:159], v[190:193], v[52:55]
	v_mfma_f32_16x16x32_bf16 v[48:51], v[166:169], v[190:193], v[48:51]
	v_mfma_f32_16x16x32_bf16 v[36:39], v[156:159], v[198:201], v[36:39]
	v_mfma_f32_16x16x32_bf16 v[32:35], v[166:169], v[198:201], v[32:35]
	v_mfma_f32_16x16x32_bf16 v[20:23], v[156:159], v[214:217], v[20:23]
	v_mfma_f32_16x16x32_bf16 v[16:19], v[166:169], v[214:217], v[16:19]
	v_mfma_f32_16x16x32_bf16 v[4:7], v[156:159], v[222:225], v[4:7]
	v_mfma_f32_16x16x32_bf16 v[0:3], v[166:169], v[222:225], v[0:3]
	v_mfma_f32_16x16x32_bf16 v[52:55], v[160:163], v[194:197], v[52:55]
	v_mfma_f32_16x16x32_bf16 v[48:51], v[186:189], v[194:197], v[48:51]
	v_mfma_f32_16x16x32_bf16 v[36:39], v[160:163], v[202:205], v[36:39]
	v_mfma_f32_16x16x32_bf16 v[32:35], v[186:189], v[202:205], v[32:35]
	v_mfma_f32_16x16x32_bf16 v[20:23], v[160:163], v[218:221], v[20:23]
	v_mfma_f32_16x16x32_bf16 v[16:19], v[186:189], v[218:221], v[16:19]
	v_mfma_f32_16x16x32_bf16 v[4:7], v[160:163], v[226:229], v[4:7]
	v_mfma_f32_16x16x32_bf16 v[0:3], v[186:189], v[226:229], v[0:3]
	s_setprio 0
	s_barrier
	s_add_i32 s18, s18, 2
	s_add_u32 s16, s16, 0x100
	s_addc_u32 s17, s17, 0
	s_add_u32 s48, s48, 0x100
	s_addc_u32 s49, s49, 0
	s_cmp_gt_u32 s18, 13
	s_cbranch_scc0 .LBB0_1218
	s_and_b64 vcc, exec, s[42:43]
	s_cbranch_vccz .LBB0_1221
	s_barrier

; #define PG8_STAGE(bufoff, gbase, voff) do { _Pragma("unroll") for (int _i = 0; _i < 2; ++_i) \
;         __builtin_amdgcn_global_load_lds((const unsigned*)((const char*)(gbase) + (voff)[_i]), (PG8_LAS unsigned*)(lds + (bufoff) + ldsw + _i * 8192), 16, 0, 0); } while (0)
; #define PG8_LDA(dst, b, h) do { _Pragma("unroll") for (int m = 0; m < 4; ++m) _Pragma("unroll") for (int k = 0; k < 2; ++k) dst[m][k] = *(const PG8_LAS bf16x8*)(lds + PG8_SA(b, h) + aoff + m * 2048 + k * 1024); } while (0)
; #define PG8_LDB(dst, b, h) do { _Pragma("unroll") for (int n = 0; n < 2; ++n) _Pragma("unroll") for (int k = 0; k < 2; ++k) dst[n][k] = *(const PG8_LAS bf16x8*)(lds + PG8_SB(b, h) + boff + n * 2048 + k * 1024); } while (0)
; #define PG8_MMA(ai, bj, At, Bt) do { __builtin_amdgcn_s_setprio(1); _Pragma("unroll") for (int m = 0; m < 4; ++m) _Pragma("unroll") for (int n = 0; n < 2; ++n) _Pragma("unroll") for (int k = 0; k < 2; ++k) \
;         acc[ai][bj][m][n] = __builtin_amdgcn_mfma_f32_16x16x32_bf16(Bt[n][k], At[m][k], acc[ai][bj][m][n], 0, 0, 0); __builtin_amdgcn_s_setprio(0); } while (0)
; #define PG8_WAIT_V(n) asm volatile("s_waitcnt vmcnt(" #n ")" ::: "memory")
; #define PG8_WAIT_L(n) asm volatile("s_waitcnt lgkmcnt(" #n ")" ::: "memory")
; template <class Epi, class Sched, bool ALIGN_EPI = false, bool SP2 = false>
; __device__ __forceinline__ void gemm_phase(PG8_LAS unsigned char* lds, const Gemm g, const Sched& S, const Epi& E) {
;     ...
;             const bool last = (t == nt - 2);
;             const char* a1 = cA + (size_t)(t + 1) * kstep;
;             const char* a2 = last ? nA : cA + (size_t)(t + 2) * kstep; const char* b2 = last ? nB : cB + (size_t)(t + 2) * kstep;
;             const char* a3 = a2 + kstep; const char* b3 = b2 + kstep;
;             if (last && has_next) S.a_ready(nxt);
;             if constexpr (SP2) {
;             PG8_LDB(B0, 0, 0); PG8_LDB(B1, 0, 1); PG8_SCHED; PG8_LDA(At, 0, 0); PG8_STAGE(PG8_SA(1, 1), a1 + hstepA, voffA);
;             PG8_WAIT_V(8); PG8_WAIT_L(0); PG8_BAR; PG8_MMA(0, 0, At, B0); PG8_MMA(0, 1, At, B1); PG8_BAR; PG8_SCHED;
;             PG8_LDA(At, 0, 1); PG8_STAGE(PG8_SB(0, 0), b2, voffB); PG8_STAGE(PG8_SB(0, 1), b2 + hstepB, voffB); PG8_STAGE(PG8_SA(0, 0), a2, voffA);
;             PG8_WAIT_V(8); PG8_WAIT_L(0); PG8_BAR; PG8_MMA(1, 0, At, B0); PG8_MMA(1, 1, At, B1); PG8_BAR; PG8_SCHED;
.LBB0_1297:
	s_add_u32 s0, s56, 0xfff00080
	s_addc_u32 s1, s57, -1
	s_add_i32 s4, 0, 0x10000
	s_cmp_eq_u32 s63, 60
	s_cselect_b32 s1, s16, s1
	s_cselect_b32 s0, s17, s0
	s_cselect_b32 s59, s49, s62
	s_cselect_b32 s58, s51, s61
	s_add_i32 s5, 0, 0x14000
	v_add_u32_e32 v152, s4, v138
	v_add_u32_e32 v186, s5, v138
	ds_read_b128 v[140:143], v152
	ds_read_b128 v[144:147], v152 offset:1024
	ds_read_b128 v[148:151], v152 offset:2048
	ds_read_b128 v[152:155], v152 offset:3072
	ds_read_b128 v[156:159], v186
	ds_read_b128 v[160:163], v186 offset:1024
	ds_read_b128 v[166:169], v186 offset:2048
	ds_read_b128 v[186:189], v186 offset:3072
	v_lshl_add_u64 v[230:231], s[56:57], 0, v[136:137]
	s_add_i32 m0, s43, 0xc000
	ds_read_b128 v[190:193], v139
	ds_read_b128 v[194:197], v139 offset:1024
	ds_read_b128 v[198:201], v139 offset:2048
	ds_read_b128 v[202:205], v139 offset:3072
	ds_read_b128 v[214:217], v139 offset:4096
	ds_read_b128 v[218:221], v139 offset:5120
	ds_read_b128 v[222:225], v139 offset:6144
	ds_read_b128 v[226:229], v139 offset:7168
	global_load_lds_dwordx4 v[230:231], off
	v_lshl_add_u64 v[230:231], s[56:57], 0, v[134:135]
	s_add_i32 m0, s43, 0xe000
	s_nop 0
	global_load_lds_dwordx4 v[230:231], off
	s_waitcnt vmcnt(8)
	s_waitcnt lgkmcnt(0)
	s_barrier
	s_setprio 1
	v_mfma_f32_16x16x32_bf16 v[124:127], v[140:143], v[190:193], v[124:127]
	v_mfma_f32_16x16x32_bf16 v[120:123], v[148:151], v[190:193], v[120:123]
	v_mfma_f32_16x16x32_bf16 v[116:119], v[140:143], v[198:201], v[116:119]
	v_mfma_f32_16x16x32_bf16 v[112:115], v[148:151], v[198:201], v[112:115]
	v_mfma_f32_16x16x32_bf16 v[100:103], v[140:143], v[214:217], v[100:103]
	v_mfma_f32_16x16x32_bf16 v[96:99], v[148:151], v[214:217], v[96:99]
	v_mfma_f32_16x16x32_bf16 v[84:87], v[140:143], v[222:225], v[84:87]
	v_mfma_f32_16x16x32_bf16 v[80:83], v[148:151], v[222:225], v[80:83]
	v_mfma_f32_16x16x32_bf16 v[124:127], v[144:147], v[194:197], v[124:127]
	v_mfma_f32_16x16x32_bf16 v[120:123], v[152:155], v[194:197], v[120:123]
	v_mfma_f32_16x16x32_bf16 v[116:119], v[144:147], v[202:205], v[116:119]
	v_mfma_f32_16x16x32_bf16 v[112:115], v[152:155], v[202:205], v[112:115]
	v_mfma_f32_16x16x32_bf16 v[100:103], v[144:147], v[218:221], v[100:103]
	v_mfma_f32_16x16x32_bf16 v[96:99], v[152:155], v[218:221], v[96:99]
	v_mfma_f32_16x16x32_bf16 v[84:87], v[144:147], v[226:229], v[84:87]
	v_mfma_f32_16x16x32_bf16 v[80:83], v[152:155], v[226:229], v[80:83]
	v_mfma_f32_16x16x32_bf16 v[108:111], v[156:159], v[190:193], v[108:111]
	v_mfma_f32_16x16x32_bf16 v[104:107], v[166:169], v[190:193], v[104:107]
	v_mfma_f32_16x16x32_bf16 v[92:95], v[156:159], v[198:201], v[92:95]
	v_mfma_f32_16x16x32_bf16 v[88:91], v[166:169], v[198:201], v[88:91]
	v_mfma_f32_16x16x32_bf16 v[76:79], v[156:159], v[214:217], v[76:79]
	v_mfma_f32_16x16x32_bf16 v[72:75], v[166:169], v[214:217], v[72:75]
	v_mfma_f32_16x16x32_bf16 v[68:71], v[156:159], v[222:225], v[68:71]
	v_mfma_f32_16x16x32_bf16 v[64:67], v[166:169], v[222:225], v[64:67]
	v_mfma_f32_16x16x32_bf16 v[108:111], v[160:163], v[194:197], v[108:111]
	v_mfma_f32_16x16x32_bf16 v[104:107], v[186:189], v[194:197], v[104:107]
	v_mfma_f32_16x16x32_bf16 v[92:95], v[160:163], v[202:205], v[92:95]
	v_mfma_f32_16x16x32_bf16 v[88:91], v[186:189], v[202:205], v[88:91]
	v_mfma_f32_16x16x32_bf16 v[76:79], v[160:163], v[218:221], v[76:79]
	v_mfma_f32_16x16x32_bf16 v[72:75], v[186:189], v[218:221], v[72:75]
	v_mfma_f32_16x16x32_bf16 v[68:71], v[160:163], v[226:229], v[68:71]
	v_mfma_f32_16x16x32_bf16 v[64:67], v[186:189], v[226:229], v[64:67]
	s_setprio 0
	s_barrier
	s_add_i32 s4, s4, s29
	v_lshl_add_u64 v[230:231], s[58:59], 0, v[164:165]
	s_mov_b32 m0, s4
	ds_read_b128 v[190:193], v139 offset:16384
	ds_read_b128 v[194:197], v139 offset:17408
	ds_read_b128 v[198:201], v139 offset:18432
	ds_read_b128 v[202:205], v139 offset:19456
	ds_read_b128 v[214:217], v139 offset:20480
	ds_read_b128 v[218:221], v139 offset:21504
	ds_read_b128 v[222:225], v139 offset:22528
	ds_read_b128 v[226:229], v139 offset:23552
	global_load_lds_dwordx4 v[230:231], off
	s_add_i32 m0, s4, 0x2000
	s_add_u32 s36, s58, 0x100000
	v_lshl_add_u64 v[232:233], s[58:59], 0, v[132:133]
	s_addc_u32 s37, s59, 0
	s_add_i32 s4, s5, s29
	global_load_lds_dwordx4 v[232:233], off
	v_lshl_add_u64 v[234:235], s[36:37], 0, v[164:165]
	s_mov_b32 m0, s4
	v_lshl_add_u64 v[236:237], s[0:1], 0, v[130:131]
	global_load_lds_dwordx4 v[234:235], off
	v_lshl_add_u64 v[234:235], s[36:37], 0, v[132:133]
	s_add_i32 m0, s4, 0x2000
	s_nop 0
	global_load_lds_dwordx4 v[234:235], off
	v_lshl_add_u64 v[234:235], s[0:1], 0, v[128:129]
	s_mov_b32 m0, s43
	s_nop 0
	global_load_lds_dwordx4 v[234:235], off
	s_mov_b32 m0, s46
	s_nop 0
	global_load_lds_dwordx4 v[236:237], off
	s_waitcnt vmcnt(8)
	s_waitcnt lgkmcnt(0)
	s_barrier
; #define PG8_STAGE(bufoff, gbase, voff) do { _Pragma("unroll") for (int _i = 0; _i < 2; ++_i) \
;         __builtin_amdgcn_global_load_lds((const unsigned*)((const char*)(gbase) + (voff)[_i]), (PG8_LAS unsigned*)(lds + (bufoff) + ldsw + _i * 8192), 16, 0, 0); } while (0)
; #define PG8_LDA(dst, b, h) do { _Pragma("unroll") for (int m = 0; m < 4; ++m) _Pragma("unroll") for (int k = 0; k < 2; ++k) dst[m][k] = *(const PG8_LAS bf16x8*)(lds + PG8_SA(b, h) + aoff + m * 2048 + k * 1024); } while (0)
; #define PG8_LDB(dst, b, h) do { _Pragma("unroll") for (int n = 0; n < 2; ++n) _Pragma("unroll") for (int k = 0; k < 2; ++k) dst[n][k] = *(const PG8_LAS bf16x8*)(lds + PG8_SB(b, h) + boff + n * 2048 + k * 1024); } while (0)
; #define PG8_MMA(ai, bj, At, Bt) do { __builtin_amdgcn_s_setprio(1); _Pragma("unroll") for (int m = 0; m < 4; ++m) _Pragma("unroll") for (int n = 0; n < 2; ++n) _Pragma("unroll") for (int k = 0; k < 2; ++k) \
;         acc[ai][bj][m][n] = __builtin_amdgcn_mfma_f32_16x16x32_bf16(Bt[n][k], At[m][k], acc[ai][bj][m][n], 0, 0, 0); __builtin_amdgcn_s_setprio(0); } while (0)
; #define PG8_WAIT_V(n) asm volatile("s_waitcnt vmcnt(" #n ")" ::: "memory")
; #define PG8_WAIT_L(n) asm volatile("s_waitcnt lgkmcnt(" #n ")" ::: "memory")
; #define PG8_BAR __builtin_amdgcn_s_barrier()
; #define PG8_SCHED __builtin_amdgcn_sched_barrier(0)
; template <class Epi, class Sched, bool ALIGN_EPI = false, bool SP2 = false>
; __device__ __forceinline__ void gemm_phase(PG8_LAS unsigned char* lds, const Gemm g, const Sched& S, const Epi& E) {
;     ...
;             PG8_WAIT_V(8); PG8_WAIT_L(0); PG8_BAR; PG8_MMA(1, 0, At, B0); PG8_MMA(1, 1, At, B1); PG8_BAR; PG8_SCHED;
;             PG8_LDB(B0, 1, 0); PG8_LDB(B1, 1, 1); PG8_SCHED; PG8_LDA(At, 1, 0); PG8_STAGE(PG8_SA(0, 1), a2 + hstepA, voffA);
;             PG8_WAIT_V(8); PG8_WAIT_L(0); PG8_BAR; PG8_MMA(0, 0, At, B0); PG8_MMA(0, 1, At, B1); PG8_BAR; PG8_SCHED;
	s_setprio 1
	v_mfma_f32_16x16x32_bf16 v[60:63], v[140:143], v[190:193], v[60:63]
	v_mfma_f32_16x16x32_bf16 v[56:59], v[148:151], v[190:193], v[56:59]
	v_mfma_f32_16x16x32_bf16 v[52:55], v[140:143], v[198:201], v[52:55]
	v_mfma_f32_16x16x32_bf16 v[48:51], v[148:151], v[198:201], v[48:51]
	v_mfma_f32_16x16x32_bf16 v[36:39], v[140:143], v[214:217], v[36:39]
	v_mfma_f32_16x16x32_bf16 v[32:35], v[148:151], v[214:217], v[32:35]
	v_mfma_f32_16x16x32_bf16 v[20:23], v[140:143], v[222:225], v[20:23]
	v_mfma_f32_16x16x32_bf16 v[16:19], v[148:151], v[222:225], v[16:19]
	v_mfma_f32_16x16x32_bf16 v[60:63], v[144:147], v[194:197], v[60:63]
	v_mfma_f32_16x16x32_bf16 v[56:59], v[152:155], v[194:197], v[56:59]
	v_mfma_f32_16x16x32_bf16 v[52:55], v[144:147], v[202:205], v[52:55]
	v_mfma_f32_16x16x32_bf16 v[48:51], v[152:155], v[202:205], v[48:51]
	v_mfma_f32_16x16x32_bf16 v[36:39], v[144:147], v[218:221], v[36:39]
	v_mfma_f32_16x16x32_bf16 v[32:35], v[152:155], v[218:221], v[32:35]
	v_mfma_f32_16x16x32_bf16 v[20:23], v[144:147], v[226:229], v[20:23]
	v_mfma_f32_16x16x32_bf16 v[16:19], v[152:155], v[226:229], v[16:19]
	v_mfma_f32_16x16x32_bf16 v[44:47], v[156:159], v[190:193], v[44:47]
	v_mfma_f32_16x16x32_bf16 v[40:43], v[166:169], v[190:193], v[40:43]
	v_mfma_f32_16x16x32_bf16 v[28:31], v[156:159], v[198:201], v[28:31]
	v_mfma_f32_16x16x32_bf16 v[24:27], v[166:169], v[198:201], v[24:27]
	v_mfma_f32_16x16x32_bf16 v[12:15], v[156:159], v[214:217], v[12:15]
	v_mfma_f32_16x16x32_bf16 v[8:11], v[166:169], v[214:217], v[8:11]
	v_mfma_f32_16x16x32_bf16 v[4:7], v[156:159], v[222:225], v[4:7]
	v_mfma_f32_16x16x32_bf16 v[0:3], v[166:169], v[222:225], v[0:3]
	v_mfma_f32_16x16x32_bf16 v[44:47], v[160:163], v[194:197], v[44:47]
	v_mfma_f32_16x16x32_bf16 v[40:43], v[186:189], v[194:197], v[40:43]
	v_mfma_f32_16x16x32_bf16 v[28:31], v[160:163], v[202:205], v[28:31]
	v_mfma_f32_16x16x32_bf16 v[24:27], v[186:189], v[202:205], v[24:27]
	v_mfma_f32_16x16x32_bf16 v[12:15], v[160:163], v[218:221], v[12:15]
	v_mfma_f32_16x16x32_bf16 v[8:11], v[186:189], v[218:221], v[8:11]
	v_mfma_f32_16x16x32_bf16 v[4:7], v[160:163], v[226:229], v[4:7]
	v_mfma_f32_16x16x32_bf16 v[0:3], v[186:189], v[226:229], v[0:3]
	s_setprio 0
	s_barrier
	s_add_i32 s4, 0, 0x18000
	s_add_i32 s5, 0, 0x1c000
	v_add_u32_e32 v152, s4, v138
	v_add_u32_e32 v186, s5, v138
	ds_read_b128 v[140:143], v152
	ds_read_b128 v[144:147], v152 offset:1024
	ds_read_b128 v[148:151], v152 offset:2048
	ds_read_b128 v[152:155], v152 offset:3072
	ds_read_b128 v[156:159], v186
	ds_read_b128 v[160:163], v186 offset:1024
	ds_read_b128 v[166:169], v186 offset:2048
	ds_read_b128 v[186:189], v186 offset:3072
	s_add_u32 s0, s0, 0x100000
	s_addc_u32 s1, s1, 0
	s_mov_b32 m0, s47
	v_lshl_add_u64 v[238:239], s[0:1], 0, v[128:129]
	ds_read_b128 v[190:193], v139 offset:32768
	ds_read_b128 v[194:197], v139 offset:33792
	ds_read_b128 v[198:201], v139 offset:34816
	ds_read_b128 v[202:205], v139 offset:35840
	ds_read_b128 v[214:217], v139 offset:36864
	ds_read_b128 v[218:221], v139 offset:37888
	ds_read_b128 v[222:225], v139 offset:38912
	ds_read_b128 v[226:229], v139 offset:39936
	global_load_lds_dwordx4 v[238:239], off
	v_lshl_add_u64 v[238:239], s[0:1], 0, v[130:131]
	s_mov_b32 m0, s60
	s_nop 0
	global_load_lds_dwordx4 v[238:239], off
	s_waitcnt vmcnt(8)
	s_waitcnt lgkmcnt(0)
	s_barrier
	s_setprio 1
	v_mfma_f32_16x16x32_bf16 v[124:127], v[140:143], v[190:193], v[124:127]
	v_mfma_f32_16x16x32_bf16 v[120:123], v[148:151], v[190:193], v[120:123]
	v_mfma_f32_16x16x32_bf16 v[116:119], v[140:143], v[198:201], v[116:119]
	v_mfma_f32_16x16x32_bf16 v[112:115], v[148:151], v[198:201], v[112:115]
	v_mfma_f32_16x16x32_bf16 v[100:103], v[140:143], v[214:217], v[100:103]
	v_mfma_f32_16x16x32_bf16 v[96:99], v[148:151], v[214:217], v[96:99]
	v_mfma_f32_16x16x32_bf16 v[84:87], v[140:143], v[222:225], v[84:87]
	v_mfma_f32_16x16x32_bf16 v[80:83], v[148:151], v[222:225], v[80:83]
	v_mfma_f32_16x16x32_bf16 v[124:127], v[144:147], v[194:197], v[124:127]
	v_mfma_f32_16x16x32_bf16 v[120:123], v[152:155], v[194:197], v[120:123]
	v_mfma_f32_16x16x32_bf16 v[116:119], v[144:147], v[202:205], v[116:119]
	v_mfma_f32_16x16x32_bf16 v[112:115], v[152:155], v[202:205], v[112:115]
	v_mfma_f32_16x16x32_bf16 v[100:103], v[144:147], v[218:221], v[100:103]
	v_mfma_f32_16x16x32_bf16 v[96:99], v[152:155], v[218:221], v[96:99]
	v_mfma_f32_16x16x32_bf16 v[84:87], v[144:147], v[226:229], v[84:87]
	v_mfma_f32_16x16x32_bf16 v[80:83], v[152:155], v[226:229], v[80:83]
	v_mfma_f32_16x16x32_bf16 v[108:111], v[156:159], v[190:193], v[108:111]
	v_mfma_f32_16x16x32_bf16 v[104:107], v[166:169], v[190:193], v[104:107]
	v_mfma_f32_16x16x32_bf16 v[92:95], v[156:159], v[198:201], v[92:95]
	v_mfma_f32_16x16x32_bf16 v[88:91], v[166:169], v[198:201], v[88:91]
	v_mfma_f32_16x16x32_bf16 v[76:79], v[156:159], v[214:217], v[76:79]
	v_mfma_f32_16x16x32_bf16 v[72:75], v[166:169], v[214:217], v[72:75]
	v_mfma_f32_16x16x32_bf16 v[68:71], v[156:159], v[222:225], v[68:71]
	v_mfma_f32_16x16x32_bf16 v[64:67], v[166:169], v[222:225], v[64:67]
	v_mfma_f32_16x16x32_bf16 v[108:111], v[160:163], v[194:197], v[108:111]
	v_mfma_f32_16x16x32_bf16 v[104:107], v[186:189], v[194:197], v[104:107]
	v_mfma_f32_16x16x32_bf16 v[92:95], v[160:163], v[202:205], v[92:95]
	v_mfma_f32_16x16x32_bf16 v[88:91], v[186:189], v[202:205], v[88:91]
	v_mfma_f32_16x16x32_bf16 v[76:79], v[160:163], v[218:221], v[76:79]
	v_mfma_f32_16x16x32_bf16 v[72:75], v[186:189], v[218:221], v[72:75]
	v_mfma_f32_16x16x32_bf16 v[68:71], v[160:163], v[226:229], v[68:71]
	v_mfma_f32_16x16x32_bf16 v[64:67], v[186:189], v[226:229], v[64:67]
	s_setprio 0
	s_barrier
; #define PG8_STAGE(bufoff, gbase, voff) do { _Pragma("unroll") for (int _i = 0; _i < 2; ++_i) \
;         __builtin_amdgcn_global_load_lds((const unsigned*)((const char*)(gbase) + (voff)[_i]), (PG8_LAS unsigned*)(lds + (bufoff) + ldsw + _i * 8192), 16, 0, 0); } while (0)
; #define PG8_LDA(dst, b, h) do { _Pragma("unroll") for (int m = 0; m < 4; ++m) _Pragma("unroll") for (int k = 0; k < 2; ++k) dst[m][k] = *(const PG8_LAS bf16x8*)(lds + PG8_SA(b, h) + aoff + m * 2048 + k * 1024); } while (0)
; #define PG8_WAIT_V(n) asm volatile("s_waitcnt vmcnt(" #n ")" ::: "memory")
; template <class Epi, class Sched, bool ALIGN_EPI = false, bool SP2 = false>
; __device__ __forceinline__ void gemm_phase(PG8_LAS unsigned char* lds, const Gemm g, const Sched& S, const Epi& E) {
;     ...
;             PG8_LDA(At, 1, 1); PG8_STAGE(PG8_SB(1, 0), b3, voffB); PG8_STAGE(PG8_SB(1, 1), b3 + hstepB, voffB); PG8_STAGE(PG8_SA(1, 0), a3, voffA);
;             PG8_WAIT_V(8); PG8_WAIT_L(0); PG8_BAR; PG8_MMA(1, 0, At, B0); PG8_MMA(1, 1, At, B1); PG8_BAR; PG8_SCHED;
;             } else {
;             PG8_LDB(B0, 0, 0); PG8_SCHED; PG8_LDA(At, 0, 0); PG8_STAGE(PG8_SA(1, 1), a1 + hstepA, voffA);
;             PG8_WAIT_L(8); PG8_BAR; PG8_WAIT_L(0); PG8_MMA(0, 0, At, B0); PG8_BAR; PG8_SCHED;
;             PG8_LDB(B1, 0, 1); PG8_STAGE(PG8_SB(0, 0), b2, voffB);
;             PG8_BAR; PG8_WAIT_L(0); PG8_MMA(0, 1, At, B1); PG8_BAR;
;             PG8_LDA(At, 0, 1); PG8_STAGE(PG8_SA(0, 0), a2, voffA);
;             PG8_BAR; PG8_WAIT_L(0); PG8_MMA(1, 0, At, B0); PG8_BAR; PG8_SCHED;
;             PG8_STAGE(PG8_SB(0, 1), b2 + hstepB, voffB);
;             PG8_WAIT_V(6); PG8_BAR; PG8_MMA(1, 1, At, B1); PG8_BAR;
;             PG8_LDB(B0, 1, 0); PG8_SCHED; PG8_LDA(At, 1, 0); PG8_STAGE(PG8_SA(0, 1), a2 + hstepA, voffA);
;             PG8_WAIT_L(8); PG8_BAR; PG8_WAIT_L(0); PG8_MMA(0, 0, At, B0); PG8_BAR; PG8_SCHED;
;             PG8_LDB(B1, 1, 1); PG8_STAGE(PG8_SB(1, 0), b3, voffB);
;             PG8_BAR; PG8_WAIT_L(0); PG8_MMA(0, 1, At, B1); PG8_BAR;
;             PG8_LDA(At, 1, 1); PG8_STAGE(PG8_SA(1, 0), a3, voffA);
;             PG8_BAR; PG8_WAIT_L(0); PG8_MMA(1, 0, At, B0); PG8_BAR; PG8_SCHED;
;             PG8_STAGE(PG8_SB(1, 1), b3 + hstepB, voffB);
;             PG8_WAIT_V(6); PG8_BAR; PG8_MMA(1, 1, At, B1); PG8_BAR;
;             }
;         }
;         if constexpr (ALIGN_EPI) { if (wr == 0) PG8_BAR; }
	s_add_i32 s0, s4, s29
	v_lshl_add_u64 v[230:231], v[230:231], 0, s[14:15]
	s_mov_b32 m0, s0
	ds_read_b128 v[190:193], v139 offset:49152
	ds_read_b128 v[194:197], v139 offset:50176
	ds_read_b128 v[198:201], v139 offset:51200
	ds_read_b128 v[202:205], v139 offset:52224
	ds_read_b128 v[214:217], v139 offset:53248
	ds_read_b128 v[218:221], v139 offset:54272
	ds_read_b128 v[222:225], v139 offset:55296
	ds_read_b128 v[226:229], v139 offset:56320
	global_load_lds_dwordx4 v[230:231], off
	s_add_i32 m0, s0, 0x2000
	s_add_u32 s0, s58, 0x100080
	v_lshl_add_u64 v[230:231], v[232:233], 0, s[14:15]
	s_addc_u32 s1, s59, 0
	s_add_i32 s4, s5, s29
	global_load_lds_dwordx4 v[230:231], off
	v_lshl_add_u64 v[230:231], s[0:1], 0, v[164:165]
	s_mov_b32 m0, s4
	s_nop 0
	global_load_lds_dwordx4 v[230:231], off
	v_lshl_add_u64 v[230:231], s[0:1], 0, v[132:133]
	s_add_i32 m0, s4, 0x2000
	s_nop 0
	global_load_lds_dwordx4 v[230:231], off
	v_lshl_add_u64 v[230:231], v[234:235], 0, s[14:15]
	s_mov_b32 m0, s9
	s_nop 0
	global_load_lds_dwordx4 v[230:231], off
	v_lshl_add_u64 v[230:231], v[236:237], 0, s[14:15]
	s_mov_b32 m0, s25
	s_nop 0
	global_load_lds_dwordx4 v[230:231], off
	s_waitcnt vmcnt(8)
	s_waitcnt lgkmcnt(0)
	s_barrier
	s_setprio 1
	v_mfma_f32_16x16x32_bf16 v[60:63], v[140:143], v[190:193], v[60:63]
	v_mfma_f32_16x16x32_bf16 v[56:59], v[148:151], v[190:193], v[56:59]
	v_mfma_f32_16x16x32_bf16 v[52:55], v[140:143], v[198:201], v[52:55]
	v_mfma_f32_16x16x32_bf16 v[48:51], v[148:151], v[198:201], v[48:51]
	v_mfma_f32_16x16x32_bf16 v[36:39], v[140:143], v[214:217], v[36:39]
	v_mfma_f32_16x16x32_bf16 v[32:35], v[148:151], v[214:217], v[32:35]
	v_mfma_f32_16x16x32_bf16 v[20:23], v[140:143], v[222:225], v[20:23]
	v_mfma_f32_16x16x32_bf16 v[16:19], v[148:151], v[222:225], v[16:19]
	v_mfma_f32_16x16x32_bf16 v[60:63], v[144:147], v[194:197], v[60:63]
	v_mfma_f32_16x16x32_bf16 v[56:59], v[152:155], v[194:197], v[56:59]
	v_mfma_f32_16x16x32_bf16 v[52:55], v[144:147], v[202:205], v[52:55]
	v_mfma_f32_16x16x32_bf16 v[48:51], v[152:155], v[202:205], v[48:51]
	v_mfma_f32_16x16x32_bf16 v[36:39], v[144:147], v[218:221], v[36:39]
	v_mfma_f32_16x16x32_bf16 v[32:35], v[152:155], v[218:221], v[32:35]
	v_mfma_f32_16x16x32_bf16 v[20:23], v[144:147], v[226:229], v[20:23]
	v_mfma_f32_16x16x32_bf16 v[16:19], v[152:155], v[226:229], v[16:19]
	v_mfma_f32_16x16x32_bf16 v[44:47], v[156:159], v[190:193], v[44:47]
	v_mfma_f32_16x16x32_bf16 v[40:43], v[166:169], v[190:193], v[40:43]
	v_mfma_f32_16x16x32_bf16 v[28:31], v[156:159], v[198:201], v[28:31]
	v_mfma_f32_16x16x32_bf16 v[24:27], v[166:169], v[198:201], v[24:27]
	v_mfma_f32_16x16x32_bf16 v[12:15], v[156:159], v[214:217], v[12:15]
	v_mfma_f32_16x16x32_bf16 v[8:11], v[166:169], v[214:217], v[8:11]
	v_mfma_f32_16x16x32_bf16 v[4:7], v[156:159], v[222:225], v[4:7]
	v_mfma_f32_16x16x32_bf16 v[0:3], v[166:169], v[222:225], v[0:3]
	v_mfma_f32_16x16x32_bf16 v[44:47], v[160:163], v[194:197], v[44:47]
	v_mfma_f32_16x16x32_bf16 v[40:43], v[186:189], v[194:197], v[40:43]
	v_mfma_f32_16x16x32_bf16 v[28:31], v[160:163], v[202:205], v[28:31]
	v_mfma_f32_16x16x32_bf16 v[24:27], v[186:189], v[202:205], v[24:27]
	v_mfma_f32_16x16x32_bf16 v[12:15], v[160:163], v[218:221], v[12:15]
	v_mfma_f32_16x16x32_bf16 v[8:11], v[186:189], v[218:221], v[8:11]
	v_mfma_f32_16x16x32_bf16 v[4:7], v[160:163], v[226:229], v[4:7]
	v_mfma_f32_16x16x32_bf16 v[0:3], v[186:189], v[226:229], v[0:3]
	s_setprio 0
	s_barrier
	s_add_i32 s63, s63, 2
	s_add_u32 s61, s61, 0x100
	s_addc_u32 s62, s62, 0
	s_add_u32 s56, s56, 0x100
	s_addc_u32 s57, s57, 0
	s_cmp_gt_u32 s63, 61
	s_cbranch_scc0 .LBB0_1297
	s_and_b64 vcc, exec, s[40:41]
	s_cbranch_vccz .LBB0_1300
	s_barrier

; #define PG8_STAGE(bufoff, gbase, voff) do { _Pragma("unroll") for (int _i = 0; _i < 2; ++_i) \
;         __builtin_amdgcn_global_load_lds((const unsigned*)((const char*)(gbase) + (voff)[_i]), (PG8_LAS unsigned*)(lds + (bufoff) + ldsw + _i * 8192), 16, 0, 0); } while (0)
; #define PG8_LDA(dst, b, h) do { _Pragma("unroll") for (int m = 0; m < 4; ++m) _Pragma("unroll") for (int k = 0; k < 2; ++k) dst[m][k] = *(const PG8_LAS bf16x8*)(lds + PG8_SA(b, h) + aoff + m * 2048 + k * 1024); } while (0)
; #define PG8_LDB(dst, b, h) do { _Pragma("unroll") for (int n = 0; n < 2; ++n) _Pragma("unroll") for (int k = 0; k < 2; ++k) dst[n][k] = *(const PG8_LAS bf16x8*)(lds + PG8_SB(b, h) + boff + n * 2048 + k * 1024); } while (0)
; #define PG8_MMA(ai, bj, At, Bt) do { __builtin_amdgcn_s_setprio(1); _Pragma("unroll") for (int m = 0; m < 4; ++m) _Pragma("unroll") for (int n = 0; n < 2; ++n) _Pragma("unroll") for (int k = 0; k < 2; ++k) \
;         acc[ai][bj][m][n] = __builtin_amdgcn_mfma_f32_16x16x32_bf16(Bt[n][k], At[m][k], acc[ai][bj][m][n], 0, 0, 0); __builtin_amdgcn_s_setprio(0); } while (0)
; #define PG8_WAIT_V(n) asm volatile("s_waitcnt vmcnt(" #n ")" ::: "memory")
; #define PG8_BAR __builtin_amdgcn_s_barrier()
; template <class Epi, class Sched, bool ALIGN_EPI = false, bool SP2 = false>
; __device__ __forceinline__ void gemm_phase(PG8_LAS unsigned char* lds, const Gemm g, const Sched& S, const Epi& E) {
;     ...
;         for (int t = 0; t < nt; t += 2) {
;             const bool last = (t == nt - 2);
;             const char* a1 = cA + (size_t)(t + 1) * kstep;
;             const char* a2 = last ? nA : cA + (size_t)(t + 2) * kstep; const char* b2 = last ? nB : cB + (size_t)(t + 2) * kstep;
;             const char* a3 = a2 + kstep; const char* b3 = b2 + kstep;
;             if (last && has_next) S.a_ready(nxt);
;             if constexpr (SP2) {
;             PG8_LDB(B0, 0, 0); PG8_LDB(B1, 0, 1); PG8_SCHED; PG8_LDA(At, 0, 0); PG8_STAGE(PG8_SA(1, 1), a1 + hstepA, voffA);
;             PG8_WAIT_V(8); PG8_WAIT_L(0); PG8_BAR; PG8_MMA(0, 0, At, B0); PG8_MMA(0, 1, At, B1); PG8_BAR; PG8_SCHED;
;             PG8_LDA(At, 0, 1); PG8_STAGE(PG8_SB(0, 0), b2, voffB); PG8_STAGE(PG8_SB(0, 1), b2 + hstepB, voffB); PG8_STAGE(PG8_SA(0, 0), a2, voffA);
;             PG8_WAIT_V(8); PG8_WAIT_L(0); PG8_BAR; PG8_MMA(1, 0, At, B0); PG8_MMA(1, 1, At, B1); PG8_BAR; PG8_SCHED;
.LBB0_1317:
	s_add_u32 s0, s58, 0xfff00080
	s_addc_u32 s1, s59, -1
	s_add_i32 s4, 0, 0x10000
	s_cmp_eq_u32 s43, 4
	s_cselect_b32 s1, s41, s1
	s_cselect_b32 s0, s40, s0
	s_cselect_b32 s61, s57, s17
	s_cselect_b32 s60, s56, s16
	s_add_i32 s5, 0, 0x14000
	v_add_u32_e32 v150, s4, v136
	v_add_u32_e32 v162, s5, v136
	ds_read_b128 v[138:141], v150
	ds_read_b128 v[142:145], v150 offset:1024
	ds_read_b128 v[146:149], v150 offset:2048
	ds_read_b128 v[150:153], v150 offset:3072
	ds_read_b128 v[154:157], v162
	ds_read_b128 v[158:161], v162 offset:1024
	ds_read_b128 v[166:169], v162 offset:2048
	ds_read_b128 v[186:189], v162 offset:3072
	v_lshl_add_u64 v[162:163], s[58:59], 0, v[134:135]
	s_add_i32 m0, s13, 0xc000
	ds_read_b128 v[190:193], v137
	ds_read_b128 v[194:197], v137 offset:1024
	ds_read_b128 v[198:201], v137 offset:2048
	ds_read_b128 v[202:205], v137 offset:3072
	ds_read_b128 v[214:217], v137 offset:4096
	ds_read_b128 v[218:221], v137 offset:5120
	ds_read_b128 v[222:225], v137 offset:6144
	ds_read_b128 v[226:229], v137 offset:7168
	global_load_lds_dwordx4 v[162:163], off
	v_lshl_add_u64 v[162:163], s[58:59], 0, v[132:133]
	s_add_i32 m0, s13, 0xe000
	s_nop 0
	global_load_lds_dwordx4 v[162:163], off
	s_waitcnt vmcnt(8)
	s_waitcnt lgkmcnt(0)
	s_barrier
	s_setprio 1
	v_mfma_f32_16x16x32_bf16 v[124:127], v[138:141], v[190:193], v[124:127]
	v_mfma_f32_16x16x32_bf16 v[120:123], v[146:149], v[190:193], v[120:123]
	v_mfma_f32_16x16x32_bf16 v[116:119], v[138:141], v[198:201], v[116:119]
	v_mfma_f32_16x16x32_bf16 v[112:115], v[146:149], v[198:201], v[112:115]
	v_mfma_f32_16x16x32_bf16 v[108:111], v[138:141], v[214:217], v[108:111]
	v_mfma_f32_16x16x32_bf16 v[100:103], v[146:149], v[214:217], v[100:103]
	v_mfma_f32_16x16x32_bf16 v[92:95], v[138:141], v[222:225], v[92:95]
	v_mfma_f32_16x16x32_bf16 v[84:87], v[146:149], v[222:225], v[84:87]
	v_mfma_f32_16x16x32_bf16 v[124:127], v[142:145], v[194:197], v[124:127]
	v_mfma_f32_16x16x32_bf16 v[120:123], v[150:153], v[194:197], v[120:123]
	v_mfma_f32_16x16x32_bf16 v[116:119], v[142:145], v[202:205], v[116:119]
	v_mfma_f32_16x16x32_bf16 v[112:115], v[150:153], v[202:205], v[112:115]
	v_mfma_f32_16x16x32_bf16 v[108:111], v[142:145], v[218:221], v[108:111]
	v_mfma_f32_16x16x32_bf16 v[100:103], v[150:153], v[218:221], v[100:103]
	v_mfma_f32_16x16x32_bf16 v[92:95], v[142:145], v[226:229], v[92:95]
	v_mfma_f32_16x16x32_bf16 v[84:87], v[150:153], v[226:229], v[84:87]
	v_mfma_f32_16x16x32_bf16 v[104:107], v[154:157], v[190:193], v[104:107]
	v_mfma_f32_16x16x32_bf16 v[96:99], v[166:169], v[190:193], v[96:99]
	v_mfma_f32_16x16x32_bf16 v[88:91], v[154:157], v[198:201], v[88:91]
	v_mfma_f32_16x16x32_bf16 v[80:83], v[166:169], v[198:201], v[80:83]
	v_mfma_f32_16x16x32_bf16 v[76:79], v[154:157], v[214:217], v[76:79]
	v_mfma_f32_16x16x32_bf16 v[72:75], v[166:169], v[214:217], v[72:75]
	v_mfma_f32_16x16x32_bf16 v[68:71], v[154:157], v[222:225], v[68:71]
	v_mfma_f32_16x16x32_bf16 v[64:67], v[166:169], v[222:225], v[64:67]
	v_mfma_f32_16x16x32_bf16 v[104:107], v[158:161], v[194:197], v[104:107]
	v_mfma_f32_16x16x32_bf16 v[96:99], v[186:189], v[194:197], v[96:99]
	v_mfma_f32_16x16x32_bf16 v[88:91], v[158:161], v[202:205], v[88:91]
	v_mfma_f32_16x16x32_bf16 v[80:83], v[186:189], v[202:205], v[80:83]
	v_mfma_f32_16x16x32_bf16 v[76:79], v[158:161], v[218:221], v[76:79]
	v_mfma_f32_16x16x32_bf16 v[72:75], v[186:189], v[218:221], v[72:75]
	v_mfma_f32_16x16x32_bf16 v[68:71], v[158:161], v[226:229], v[68:71]
	v_mfma_f32_16x16x32_bf16 v[64:67], v[186:189], v[226:229], v[64:67]
	s_setprio 0
	s_barrier
	s_add_i32 s4, s4, s8
	v_lshl_add_u64 v[162:163], s[60:61], 0, v[130:131]
	s_mov_b32 m0, s4
	ds_read_b128 v[190:193], v137 offset:16384
	ds_read_b128 v[194:197], v137 offset:17408
	ds_read_b128 v[198:201], v137 offset:18432
	ds_read_b128 v[202:205], v137 offset:19456
	ds_read_b128 v[214:217], v137 offset:20480
	ds_read_b128 v[218:221], v137 offset:21504
	ds_read_b128 v[222:225], v137 offset:22528
	ds_read_b128 v[226:229], v137 offset:23552
	global_load_lds_dwordx4 v[162:163], off
	s_add_i32 m0, s4, 0x2000
	s_add_u32 s36, s60, 0x100000
	v_lshl_add_u64 v[230:231], s[60:61], 0, v[128:129]
	s_addc_u32 s37, s61, 0
	s_add_i32 s4, s5, s8
	global_load_lds_dwordx4 v[230:231], off
	v_lshl_add_u64 v[232:233], s[36:37], 0, v[130:131]
	s_mov_b32 m0, s4
	v_lshl_add_u64 v[234:235], s[0:1], 0, v[128:129]
	global_load_lds_dwordx4 v[232:233], off
	v_lshl_add_u64 v[232:233], s[36:37], 0, v[128:129]
	s_add_i32 m0, s4, 0x2000
	s_nop 0
	global_load_lds_dwordx4 v[232:233], off
	v_lshl_add_u64 v[232:233], s[0:1], 0, v[130:131]
	s_mov_b32 m0, s13
	s_nop 0
	global_load_lds_dwordx4 v[232:233], off
	s_mov_b32 m0, s18
	s_nop 0
	global_load_lds_dwordx4 v[234:235], off
	s_waitcnt vmcnt(8)
	s_waitcnt lgkmcnt(0)
	s_barrier
; #define PG8_STAGE(bufoff, gbase, voff) do { _Pragma("unroll") for (int _i = 0; _i < 2; ++_i) \
;         __builtin_amdgcn_global_load_lds((const unsigned*)((const char*)(gbase) + (voff)[_i]), (PG8_LAS unsigned*)(lds + (bufoff) + ldsw + _i * 8192), 16, 0, 0); } while (0)
; #define PG8_LDA(dst, b, h) do { _Pragma("unroll") for (int m = 0; m < 4; ++m) _Pragma("unroll") for (int k = 0; k < 2; ++k) dst[m][k] = *(const PG8_LAS bf16x8*)(lds + PG8_SA(b, h) + aoff + m * 2048 + k * 1024); } while (0)
; #define PG8_LDB(dst, b, h) do { _Pragma("unroll") for (int n = 0; n < 2; ++n) _Pragma("unroll") for (int k = 0; k < 2; ++k) dst[n][k] = *(const PG8_LAS bf16x8*)(lds + PG8_SB(b, h) + boff + n * 2048 + k * 1024); } while (0)
; #define PG8_MMA(ai, bj, At, Bt) do { __builtin_amdgcn_s_setprio(1); _Pragma("unroll") for (int m = 0; m < 4; ++m) _Pragma("unroll") for (int n = 0; n < 2; ++n) _Pragma("unroll") for (int k = 0; k < 2; ++k) \
;         acc[ai][bj][m][n] = __builtin_amdgcn_mfma_f32_16x16x32_bf16(Bt[n][k], At[m][k], acc[ai][bj][m][n], 0, 0, 0); __builtin_amdgcn_s_setprio(0); } while (0)
; #define PG8_WAIT_V(n) asm volatile("s_waitcnt vmcnt(" #n ")" ::: "memory")
; #define PG8_WAIT_L(n) asm volatile("s_waitcnt lgkmcnt(" #n ")" ::: "memory")
; #define PG8_BAR __builtin_amdgcn_s_barrier()
; #define PG8_SCHED __builtin_amdgcn_sched_barrier(0)
; template <class Epi, class Sched, bool ALIGN_EPI = false, bool SP2 = false>
; __device__ __forceinline__ void gemm_phase(PG8_LAS unsigned char* lds, const Gemm g, const Sched& S, const Epi& E) {
;     ...
;             PG8_WAIT_V(8); PG8_WAIT_L(0); PG8_BAR; PG8_MMA(1, 0, At, B0); PG8_MMA(1, 1, At, B1); PG8_BAR; PG8_SCHED;
;             PG8_LDB(B0, 1, 0); PG8_LDB(B1, 1, 1); PG8_SCHED; PG8_LDA(At, 1, 0); PG8_STAGE(PG8_SA(0, 1), a2 + hstepA, voffA);
;             PG8_WAIT_V(8); PG8_WAIT_L(0); PG8_BAR; PG8_MMA(0, 0, At, B0); PG8_MMA(0, 1, At, B1); PG8_BAR; PG8_SCHED;
	s_setprio 1
	v_mfma_f32_16x16x32_bf16 v[60:63], v[138:141], v[190:193], v[60:63]
	v_mfma_f32_16x16x32_bf16 v[56:59], v[146:149], v[190:193], v[56:59]
	v_mfma_f32_16x16x32_bf16 v[52:55], v[138:141], v[198:201], v[52:55]
	v_mfma_f32_16x16x32_bf16 v[48:51], v[146:149], v[198:201], v[48:51]
	v_mfma_f32_16x16x32_bf16 v[40:43], v[138:141], v[214:217], v[40:43]
	v_mfma_f32_16x16x32_bf16 v[32:35], v[146:149], v[214:217], v[32:35]
	v_mfma_f32_16x16x32_bf16 v[24:27], v[138:141], v[222:225], v[24:27]
	v_mfma_f32_16x16x32_bf16 v[16:19], v[146:149], v[222:225], v[16:19]
	v_mfma_f32_16x16x32_bf16 v[60:63], v[142:145], v[194:197], v[60:63]
	v_mfma_f32_16x16x32_bf16 v[56:59], v[150:153], v[194:197], v[56:59]
	v_mfma_f32_16x16x32_bf16 v[52:55], v[142:145], v[202:205], v[52:55]
	v_mfma_f32_16x16x32_bf16 v[48:51], v[150:153], v[202:205], v[48:51]
	v_mfma_f32_16x16x32_bf16 v[40:43], v[142:145], v[218:221], v[40:43]
	v_mfma_f32_16x16x32_bf16 v[32:35], v[150:153], v[218:221], v[32:35]
	v_mfma_f32_16x16x32_bf16 v[24:27], v[142:145], v[226:229], v[24:27]
	v_mfma_f32_16x16x32_bf16 v[16:19], v[150:153], v[226:229], v[16:19]
	v_mfma_f32_16x16x32_bf16 v[44:47], v[154:157], v[190:193], v[44:47]
	v_mfma_f32_16x16x32_bf16 v[36:39], v[166:169], v[190:193], v[36:39]
	v_mfma_f32_16x16x32_bf16 v[28:31], v[154:157], v[198:201], v[28:31]
	v_mfma_f32_16x16x32_bf16 v[20:23], v[166:169], v[198:201], v[20:23]
	v_mfma_f32_16x16x32_bf16 v[12:15], v[154:157], v[214:217], v[12:15]
	v_mfma_f32_16x16x32_bf16 v[8:11], v[166:169], v[214:217], v[8:11]
	v_mfma_f32_16x16x32_bf16 v[4:7], v[154:157], v[222:225], v[4:7]
	v_mfma_f32_16x16x32_bf16 v[0:3], v[166:169], v[222:225], v[0:3]
	v_mfma_f32_16x16x32_bf16 v[44:47], v[158:161], v[194:197], v[44:47]
	v_mfma_f32_16x16x32_bf16 v[36:39], v[186:189], v[194:197], v[36:39]
	v_mfma_f32_16x16x32_bf16 v[28:31], v[158:161], v[202:205], v[28:31]
	v_mfma_f32_16x16x32_bf16 v[20:23], v[186:189], v[202:205], v[20:23]
	v_mfma_f32_16x16x32_bf16 v[12:15], v[158:161], v[218:221], v[12:15]
	v_mfma_f32_16x16x32_bf16 v[8:11], v[186:189], v[218:221], v[8:11]
	v_mfma_f32_16x16x32_bf16 v[4:7], v[158:161], v[226:229], v[4:7]
	v_mfma_f32_16x16x32_bf16 v[0:3], v[186:189], v[226:229], v[0:3]
	s_setprio 0
	s_barrier
	s_add_i32 s4, 0, 0x18000
	s_add_i32 s5, 0, 0x1c000
	v_add_u32_e32 v150, s4, v136
	v_add_u32_e32 v164, s5, v136
	ds_read_b128 v[138:141], v150
	ds_read_b128 v[142:145], v150 offset:1024
	ds_read_b128 v[146:149], v150 offset:2048
	ds_read_b128 v[150:153], v150 offset:3072
	ds_read_b128 v[154:157], v164
	ds_read_b128 v[158:161], v164 offset:1024
	ds_read_b128 v[166:169], v164 offset:2048
	ds_read_b128 v[186:189], v164 offset:3072
	s_add_u32 s0, s0, 0x100000
	s_addc_u32 s1, s1, 0
	s_mov_b32 m0, s19
	v_lshl_add_u64 v[236:237], s[0:1], 0, v[130:131]
	ds_read_b128 v[190:193], v137 offset:32768
	ds_read_b128 v[194:197], v137 offset:33792
	ds_read_b128 v[198:201], v137 offset:34816
	ds_read_b128 v[202:205], v137 offset:35840
	ds_read_b128 v[214:217], v137 offset:36864
	ds_read_b128 v[218:221], v137 offset:37888
	ds_read_b128 v[222:225], v137 offset:38912
	ds_read_b128 v[226:229], v137 offset:39936
	global_load_lds_dwordx4 v[236:237], off
	v_lshl_add_u64 v[236:237], s[0:1], 0, v[128:129]
	s_mov_b32 m0, s24
	s_nop 0
	global_load_lds_dwordx4 v[236:237], off
	s_waitcnt vmcnt(8)
	s_waitcnt lgkmcnt(0)
	s_barrier
	s_setprio 1
	v_mfma_f32_16x16x32_bf16 v[124:127], v[138:141], v[190:193], v[124:127]
	v_mfma_f32_16x16x32_bf16 v[120:123], v[146:149], v[190:193], v[120:123]
	v_mfma_f32_16x16x32_bf16 v[116:119], v[138:141], v[198:201], v[116:119]
	v_mfma_f32_16x16x32_bf16 v[112:115], v[146:149], v[198:201], v[112:115]
	v_mfma_f32_16x16x32_bf16 v[108:111], v[138:141], v[214:217], v[108:111]
	v_mfma_f32_16x16x32_bf16 v[100:103], v[146:149], v[214:217], v[100:103]
	v_mfma_f32_16x16x32_bf16 v[92:95], v[138:141], v[222:225], v[92:95]
	v_mfma_f32_16x16x32_bf16 v[84:87], v[146:149], v[222:225], v[84:87]
	v_mfma_f32_16x16x32_bf16 v[124:127], v[142:145], v[194:197], v[124:127]
	v_mfma_f32_16x16x32_bf16 v[120:123], v[150:153], v[194:197], v[120:123]
	v_mfma_f32_16x16x32_bf16 v[116:119], v[142:145], v[202:205], v[116:119]
	v_mfma_f32_16x16x32_bf16 v[112:115], v[150:153], v[202:205], v[112:115]
	v_mfma_f32_16x16x32_bf16 v[108:111], v[142:145], v[218:221], v[108:111]
	v_mfma_f32_16x16x32_bf16 v[100:103], v[150:153], v[218:221], v[100:103]
	v_mfma_f32_16x16x32_bf16 v[92:95], v[142:145], v[226:229], v[92:95]
	v_mfma_f32_16x16x32_bf16 v[84:87], v[150:153], v[226:229], v[84:87]
	v_mfma_f32_16x16x32_bf16 v[104:107], v[154:157], v[190:193], v[104:107]
	v_mfma_f32_16x16x32_bf16 v[96:99], v[166:169], v[190:193], v[96:99]
	v_mfma_f32_16x16x32_bf16 v[88:91], v[154:157], v[198:201], v[88:91]
	v_mfma_f32_16x16x32_bf16 v[80:83], v[166:169], v[198:201], v[80:83]
	v_mfma_f32_16x16x32_bf16 v[76:79], v[154:157], v[214:217], v[76:79]
	v_mfma_f32_16x16x32_bf16 v[72:75], v[166:169], v[214:217], v[72:75]
	v_mfma_f32_16x16x32_bf16 v[68:71], v[154:157], v[222:225], v[68:71]
	v_mfma_f32_16x16x32_bf16 v[64:67], v[166:169], v[222:225], v[64:67]
	v_mfma_f32_16x16x32_bf16 v[104:107], v[158:161], v[194:197], v[104:107]
	v_mfma_f32_16x16x32_bf16 v[96:99], v[186:189], v[194:197], v[96:99]
	v_mfma_f32_16x16x32_bf16 v[88:91], v[158:161], v[202:205], v[88:91]
	v_mfma_f32_16x16x32_bf16 v[80:83], v[186:189], v[202:205], v[80:83]
	v_mfma_f32_16x16x32_bf16 v[76:79], v[158:161], v[218:221], v[76:79]
	v_mfma_f32_16x16x32_bf16 v[72:75], v[186:189], v[218:221], v[72:75]
	v_mfma_f32_16x16x32_bf16 v[68:71], v[158:161], v[226:229], v[68:71]
	v_mfma_f32_16x16x32_bf16 v[64:67], v[186:189], v[226:229], v[64:67]
	s_setprio 0
	s_barrier
; #define PG8_STAGE(bufoff, gbase, voff) do { _Pragma("unroll") for (int _i = 0; _i < 2; ++_i) \
;         __builtin_amdgcn_global_load_lds((const unsigned*)((const char*)(gbase) + (voff)[_i]), (PG8_LAS unsigned*)(lds + (bufoff) + ldsw + _i * 8192), 16, 0, 0); } while (0)
; #define PG8_LDA(dst, b, h) do { _Pragma("unroll") for (int m = 0; m < 4; ++m) _Pragma("unroll") for (int k = 0; k < 2; ++k) dst[m][k] = *(const PG8_LAS bf16x8*)(lds + PG8_SA(b, h) + aoff + m * 2048 + k * 1024); } while (0)
; #define PG8_WAIT_V(n) asm volatile("s_waitcnt vmcnt(" #n ")" ::: "memory")
; template <class Epi, class Sched, bool ALIGN_EPI = false, bool SP2 = false>
; __device__ __forceinline__ void gemm_phase(PG8_LAS unsigned char* lds, const Gemm g, const Sched& S, const Epi& E) {
;     ...
;             PG8_LDA(At, 1, 1); PG8_STAGE(PG8_SB(1, 0), b3, voffB); PG8_STAGE(PG8_SB(1, 1), b3 + hstepB, voffB); PG8_STAGE(PG8_SA(1, 0), a3, voffA);
;             PG8_WAIT_V(8); PG8_WAIT_L(0); PG8_BAR; PG8_MMA(1, 0, At, B0); PG8_MMA(1, 1, At, B1); PG8_BAR; PG8_SCHED;
;             } else {
;             PG8_LDB(B0, 0, 0); PG8_SCHED; PG8_LDA(At, 0, 0); PG8_STAGE(PG8_SA(1, 1), a1 + hstepA, voffA);
;             PG8_WAIT_L(8); PG8_BAR; PG8_WAIT_L(0); PG8_MMA(0, 0, At, B0); PG8_BAR; PG8_SCHED;
;             PG8_LDB(B1, 0, 1); PG8_STAGE(PG8_SB(0, 0), b2, voffB);
;             PG8_BAR; PG8_WAIT_L(0); PG8_MMA(0, 1, At, B1); PG8_BAR;
;             PG8_LDA(At, 0, 1); PG8_STAGE(PG8_SA(0, 0), a2, voffA);
;             PG8_BAR; PG8_WAIT_L(0); PG8_MMA(1, 0, At, B0); PG8_BAR; PG8_SCHED;
;             PG8_STAGE(PG8_SB(0, 1), b2 + hstepB, voffB);
;             PG8_WAIT_V(6); PG8_BAR; PG8_MMA(1, 1, At, B1); PG8_BAR;
;             PG8_LDB(B0, 1, 0); PG8_SCHED; PG8_LDA(At, 1, 0); PG8_STAGE(PG8_SA(0, 1), a2 + hstepA, voffA);
;             PG8_WAIT_L(8); PG8_BAR; PG8_WAIT_L(0); PG8_MMA(0, 0, At, B0); PG8_BAR; PG8_SCHED;
;             PG8_LDB(B1, 1, 1); PG8_STAGE(PG8_SB(1, 0), b3, voffB);
;             PG8_BAR; PG8_WAIT_L(0); PG8_MMA(0, 1, At, B1); PG8_BAR;
;             PG8_LDA(At, 1, 1); PG8_STAGE(PG8_SA(1, 0), a3, voffA);
;             PG8_BAR; PG8_WAIT_L(0); PG8_MMA(1, 0, At, B0); PG8_BAR; PG8_SCHED;
;             PG8_STAGE(PG8_SB(1, 1), b3 + hstepB, voffB);
;             PG8_WAIT_V(6); PG8_BAR; PG8_MMA(1, 1, At, B1); PG8_BAR;
;             }
;         }
;         if constexpr (ALIGN_EPI) { if (wr == 0) PG8_BAR; }
	s_add_i32 s0, s4, s8
	v_lshl_add_u64 v[162:163], v[162:163], 0, s[14:15]
	s_mov_b32 m0, s0
	ds_read_b128 v[190:193], v137 offset:49152
	ds_read_b128 v[194:197], v137 offset:50176
	ds_read_b128 v[198:201], v137 offset:51200
	ds_read_b128 v[202:205], v137 offset:52224
	ds_read_b128 v[214:217], v137 offset:53248
	ds_read_b128 v[218:221], v137 offset:54272
	ds_read_b128 v[222:225], v137 offset:55296
	ds_read_b128 v[226:229], v137 offset:56320
	global_load_lds_dwordx4 v[162:163], off
	s_add_i32 m0, s0, 0x2000
	s_add_u32 s0, s60, 0x100080
	v_lshl_add_u64 v[162:163], v[230:231], 0, s[14:15]
	s_addc_u32 s1, s61, 0
	s_add_i32 s4, s5, s8
	global_load_lds_dwordx4 v[162:163], off
	v_lshl_add_u64 v[162:163], s[0:1], 0, v[130:131]
	s_mov_b32 m0, s4
	s_nop 0
	global_load_lds_dwordx4 v[162:163], off
	v_lshl_add_u64 v[162:163], s[0:1], 0, v[128:129]
	s_add_i32 m0, s4, 0x2000
	s_nop 0
	global_load_lds_dwordx4 v[162:163], off
	v_lshl_add_u64 v[162:163], v[232:233], 0, s[14:15]
	s_mov_b32 m0, s35
	s_nop 0
	global_load_lds_dwordx4 v[162:163], off
	v_lshl_add_u64 v[162:163], v[234:235], 0, s[14:15]
	s_mov_b32 m0, s46
	s_nop 0
	global_load_lds_dwordx4 v[162:163], off
	s_waitcnt vmcnt(8)
	s_waitcnt lgkmcnt(0)
	s_barrier
	s_setprio 1
	v_mfma_f32_16x16x32_bf16 v[60:63], v[138:141], v[190:193], v[60:63]
	v_mfma_f32_16x16x32_bf16 v[56:59], v[146:149], v[190:193], v[56:59]
	v_mfma_f32_16x16x32_bf16 v[52:55], v[138:141], v[198:201], v[52:55]
	v_mfma_f32_16x16x32_bf16 v[48:51], v[146:149], v[198:201], v[48:51]
	v_mfma_f32_16x16x32_bf16 v[40:43], v[138:141], v[214:217], v[40:43]
	v_mfma_f32_16x16x32_bf16 v[32:35], v[146:149], v[214:217], v[32:35]
	v_mfma_f32_16x16x32_bf16 v[24:27], v[138:141], v[222:225], v[24:27]
	v_mfma_f32_16x16x32_bf16 v[16:19], v[146:149], v[222:225], v[16:19]
	v_mfma_f32_16x16x32_bf16 v[60:63], v[142:145], v[194:197], v[60:63]
	v_mfma_f32_16x16x32_bf16 v[56:59], v[150:153], v[194:197], v[56:59]
	v_mfma_f32_16x16x32_bf16 v[52:55], v[142:145], v[202:205], v[52:55]
	v_mfma_f32_16x16x32_bf16 v[48:51], v[150:153], v[202:205], v[48:51]
	v_mfma_f32_16x16x32_bf16 v[40:43], v[142:145], v[218:221], v[40:43]
	v_mfma_f32_16x16x32_bf16 v[32:35], v[150:153], v[218:221], v[32:35]
	v_mfma_f32_16x16x32_bf16 v[24:27], v[142:145], v[226:229], v[24:27]
	v_mfma_f32_16x16x32_bf16 v[16:19], v[150:153], v[226:229], v[16:19]
	v_mfma_f32_16x16x32_bf16 v[44:47], v[154:157], v[190:193], v[44:47]
	v_mfma_f32_16x16x32_bf16 v[36:39], v[166:169], v[190:193], v[36:39]
	v_mfma_f32_16x16x32_bf16 v[28:31], v[154:157], v[198:201], v[28:31]
	v_mfma_f32_16x16x32_bf16 v[20:23], v[166:169], v[198:201], v[20:23]
	v_mfma_f32_16x16x32_bf16 v[12:15], v[154:157], v[214:217], v[12:15]
	v_mfma_f32_16x16x32_bf16 v[8:11], v[166:169], v[214:217], v[8:11]
	v_mfma_f32_16x16x32_bf16 v[4:7], v[154:157], v[222:225], v[4:7]
	v_mfma_f32_16x16x32_bf16 v[0:3], v[166:169], v[222:225], v[0:3]
	v_mfma_f32_16x16x32_bf16 v[44:47], v[158:161], v[194:197], v[44:47]
	v_mfma_f32_16x16x32_bf16 v[36:39], v[186:189], v[194:197], v[36:39]
	v_mfma_f32_16x16x32_bf16 v[28:31], v[158:161], v[202:205], v[28:31]
	v_mfma_f32_16x16x32_bf16 v[20:23], v[186:189], v[202:205], v[20:23]
	v_mfma_f32_16x16x32_bf16 v[12:15], v[158:161], v[218:221], v[12:15]
	v_mfma_f32_16x16x32_bf16 v[8:11], v[186:189], v[218:221], v[8:11]
	v_mfma_f32_16x16x32_bf16 v[4:7], v[158:161], v[226:229], v[4:7]
	v_mfma_f32_16x16x32_bf16 v[0:3], v[186:189], v[226:229], v[0:3]
	s_setprio 0
	s_barrier
	s_add_i32 s43, s43, 2
	s_add_u32 s16, s16, 0x100
	s_addc_u32 s17, s17, 0
	s_add_u32 s58, s58, 0x100
	s_addc_u32 s59, s59, 0
	s_cmp_gt_u32 s43, 5
	s_cbranch_scc0 .LBB0_1317
	s_and_b64 vcc, exec, s[30:31]
	s_cbranch_vccz .LBB0_1320
	s_barrier
